# K-loop phase 1: second LDS-DMA address precomputed before the LDS reads and m0 stepped by s_add (no second readfirstlane chain), on the k16 stack
# baseline (speedup 1.0000x reference)
; #define STAGE(P, BASE, LD, br, kt) do { const bf16* _gb = BASE + ((long)(br) * (LD) + (long)(kt) * BK); \
;     _Pragma("unroll") for (int _i = 0; _i < 2; ++_i) { \
;       __builtin_amdgcn_global_load_lds((const unsigned*)(_gb + ((&LD == &lda) ? offA[_i] : offB[_i])), \
;         (unsigned*)((char*)(P) + tidx_ * 16 + _i * 8192), 16, 0, 0); } } while (0)
; #define LDA(dst, b, h) _Pragma("unroll") for (int m = 0; m < 4; ++m) _Pragma("unroll") for (int k = 0; k < 2; ++k) \
;     dst[m][k] = *reinterpret_cast<const bf16x8*>(smem + (((b) * 2 + (h)) * 16384 + m * 2048 + k * 1024) + aoff)
; #define LDB(dst, b, h) _Pragma("unroll") for (int n = 0; n < 2; ++n) _Pragma("unroll") for (int k = 0; k < 2; ++k) \
;     dst[n][k] = *reinterpret_cast<const bf16x8*>(smem + (((b) * 2 + (h)) * 16384 + n * 2048 + k * 1024) + boff)
; #define MMA(ai, bj, At_, Bt_) do { __builtin_amdgcn_s_setprio(1); \
;     _Pragma("unroll") for (int m = 0; m < 4; ++m) _Pragma("unroll") for (int n = 0; n < 2; ++n) _Pragma("unroll") for (int k = 0; k < 2; ++k) \
;       acc[ai][bj][m][n] = __builtin_amdgcn_mfma_f32_16x16x32_bf16(Bt_[n][k], At_[m][k], acc[ai][bj][m][n], 0, 0, 0); \
;     __builtin_amdgcn_s_setprio(0); } while (0)
; #define WAIT_L(n) asm volatile("s_waitcnt lgkmcnt(" #n ")" ::: "memory")
; #define BAR __builtin_amdgcn_s_barrier()
; #define SCHED __builtin_amdgcn_sched_barrier(0)
; template <class Epi, int NB>
; DEV void gemm_tile_nb(const bf16* __restrict__ A, int lda, long strideA, const bf16* __restrict__ Bt, int ldb, long strideB, int K, int brow, int bcol, Epi& epi) {
;     ...
;     LDB(B0, 0, 0); SCHED; LDA(At, 0, 0); STAGE(SA(1, 1), A, lda, brow + HALF, t + 1);
;     WAIT_L(8); BAR; WAIT_L(0); MMA(0, 0, At, B0); BAR; SCHED;
;     LDB(B1, 0, 1); STAGE(SB(0, 0), Bt, ldb, bcol, t + 2);
;     BAR; WAIT_L(0); MMA(0, 1, At, B1); BAR;
;     LDA(At, 0, 1); STAGE(SA(0, 0), A, lda, brow, t + 2);
;     BAR; WAIT_L(0); MMA(1, 0, At, B0); BAR; SCHED;
.LBB0_138:
	v_add_u32_e32 v159, 0xc000, v146
	v_lshl_add_u64 v[204:205], s[88:89], 0, v[138:139]
	v_readfirstlane_b32 s48, v159
	v_lshl_add_u64 v[160:161], v[204:205], 0, s[38:39]
	v_lshl_add_u64 v[208:209], s[88:89], 0, v[140:141]
	v_lshl_add_u64 v[214:215], v[208:209], 0, s[38:39]
	s_mov_b32 m0, s48
	ds_read_b128 v[184:187], v0
	ds_read_b128 v[188:191], v0 offset:1024
	ds_read_b128 v[192:195], v0 offset:2048
	ds_read_b128 v[196:199], v0 offset:3072
	ds_read_b128 v[200:203], v0 offset:4096
	ds_read_b128 v[218:221], v0 offset:5120
	ds_read_b128 v[222:225], v0 offset:6144
	ds_read_b128 v[226:229], v0 offset:7168
	global_load_lds_dwordx4 v[160:161], off
	s_add_i32 m0, m0, 0x2000
	v_add_u32_e32 v160, 0xe000, v146
	global_load_lds_dwordx4 v[214:215], off
	s_waitcnt lgkmcnt(8)
	s_barrier
	s_waitcnt lgkmcnt(0)
	s_setprio 1
	s_waitcnt lgkmcnt(0)
	v_mfma_f32_16x16x32_bf16 v[126:129], v[162:165], v[184:187], v[126:129]
	v_mfma_f32_16x16x32_bf16 v[122:125], v[170:173], v[184:187], v[122:125]
	v_mfma_f32_16x16x32_bf16 v[118:121], v[162:165], v[192:195], v[118:121]
	v_mfma_f32_16x16x32_bf16 v[114:117], v[170:173], v[192:195], v[114:117]
	v_mfma_f32_16x16x32_bf16 v[110:113], v[162:165], v[200:203], v[110:113]
	v_mfma_f32_16x16x32_bf16 v[106:109], v[170:173], v[200:203], v[106:109]
	v_mfma_f32_16x16x32_bf16 v[102:105], v[162:165], v[222:225], v[102:105]
	v_mfma_f32_16x16x32_bf16 v[98:101], v[170:173], v[222:225], v[98:101]
	v_mfma_f32_16x16x32_bf16 v[126:129], v[166:169], v[188:191], v[126:129]
	v_mfma_f32_16x16x32_bf16 v[122:125], v[174:177], v[188:191], v[122:125]
	v_mfma_f32_16x16x32_bf16 v[118:121], v[166:169], v[196:199], v[118:121]
	v_mfma_f32_16x16x32_bf16 v[114:117], v[174:177], v[196:199], v[114:117]
	v_mfma_f32_16x16x32_bf16 v[110:113], v[166:169], v[218:221], v[110:113]
	v_mfma_f32_16x16x32_bf16 v[106:109], v[174:177], v[218:221], v[106:109]
	v_mfma_f32_16x16x32_bf16 v[102:105], v[166:169], v[226:229], v[102:105]
	v_mfma_f32_16x16x32_bf16 v[98:101], v[174:177], v[226:229], v[98:101]
	s_setprio 0
	s_barrier
	v_lshl_add_u64 v[214:215], s[88:89], 0, v[134:135]
	v_readfirstlane_b32 s48, v145
	v_lshl_add_u64 v[246:247], v[214:215], 0, s[50:51]
	s_mov_b32 m0, s48
	ds_read_b128 v[230:233], v144 offset:16384
	ds_read_b128 v[234:237], v144 offset:17408
	ds_read_b128 v[238:241], v144 offset:18432
	ds_read_b128 v[242:245], v144 offset:19456
	global_load_lds_dwordx4 v[246:247], off
	v_lshl_add_u64 v[246:247], s[88:89], 0, v[136:137]
	v_readfirstlane_b32 s48, v148
	v_lshl_add_u64 v[248:249], v[246:247], 0, s[50:51]
	s_mov_b32 m0, s48
	s_nop 0
	global_load_lds_dwordx4 v[248:249], off
	s_barrier
	s_waitcnt lgkmcnt(0)
	s_setprio 1
	s_waitcnt lgkmcnt(0)
	v_mfma_f32_16x16x32_bf16 v[94:97], v[230:233], v[184:187], v[94:97]
	v_mfma_f32_16x16x32_bf16 v[90:93], v[238:241], v[184:187], v[90:93]
	v_mfma_f32_16x16x32_bf16 v[86:89], v[230:233], v[192:195], v[86:89]
	v_mfma_f32_16x16x32_bf16 v[70:73], v[238:241], v[192:195], v[70:73]
	v_mfma_f32_16x16x32_bf16 v[62:65], v[230:233], v[200:203], v[62:65]
	v_mfma_f32_16x16x32_bf16 v[58:61], v[238:241], v[200:203], v[58:61]
	v_mfma_f32_16x16x32_bf16 v[54:57], v[230:233], v[222:225], v[54:57]
	v_mfma_f32_16x16x32_bf16 v[50:53], v[238:241], v[222:225], v[50:53]
	v_mfma_f32_16x16x32_bf16 v[94:97], v[234:237], v[188:191], v[94:97]
	v_mfma_f32_16x16x32_bf16 v[90:93], v[242:245], v[188:191], v[90:93]
	v_mfma_f32_16x16x32_bf16 v[86:89], v[234:237], v[196:199], v[86:89]
	v_mfma_f32_16x16x32_bf16 v[70:73], v[242:245], v[196:199], v[70:73]
	v_mfma_f32_16x16x32_bf16 v[62:65], v[234:237], v[218:221], v[62:65]
	v_mfma_f32_16x16x32_bf16 v[58:61], v[242:245], v[218:221], v[58:61]
	v_mfma_f32_16x16x32_bf16 v[54:57], v[234:237], v[226:229], v[54:57]
	v_mfma_f32_16x16x32_bf16 v[50:53], v[242:245], v[226:229], v[50:53]
	s_setprio 0
	v_readfirstlane_b32 s48, v146
	v_lshl_add_u64 v[248:249], v[204:205], 0, s[56:57]
	s_mov_b32 m0, s48
	v_readfirstlane_b32 s48, v150
	s_barrier
	ds_read_b128 v[184:187], v0 offset:16384
	ds_read_b128 v[188:191], v0 offset:17408
	ds_read_b128 v[192:195], v0 offset:18432
	ds_read_b128 v[196:199], v0 offset:19456
	ds_read_b128 v[200:203], v0 offset:20480
	ds_read_b128 v[218:221], v0 offset:21504
	ds_read_b128 v[222:225], v0 offset:22528
	ds_read_b128 v[226:229], v0 offset:23552
	global_load_lds_dwordx4 v[248:249], off
	v_lshl_add_u64 v[248:249], v[208:209], 0, s[56:57]
	s_mov_b32 m0, s48
	s_nop 0
	global_load_lds_dwordx4 v[248:249], off
	s_waitcnt vmcnt(10)
	s_barrier
	s_waitcnt lgkmcnt(0)
	s_setprio 1
	s_waitcnt lgkmcnt(0)
	v_mfma_f32_16x16x32_bf16 v[46:49], v[162:165], v[184:187], v[46:49]
	v_mfma_f32_16x16x32_bf16 v[42:45], v[170:173], v[184:187], v[42:45]
	v_mfma_f32_16x16x32_bf16 v[38:41], v[162:165], v[192:195], v[38:41]
	v_mfma_f32_16x16x32_bf16 v[34:37], v[170:173], v[192:195], v[34:37]
	v_mfma_f32_16x16x32_bf16 v[30:33], v[162:165], v[200:203], v[30:33]
	v_mfma_f32_16x16x32_bf16 v[26:29], v[170:173], v[200:203], v[26:29]
	v_mfma_f32_16x16x32_bf16 v[22:25], v[162:165], v[222:225], v[22:25]
	v_mfma_f32_16x16x32_bf16 v[18:21], v[170:173], v[222:225], v[18:21]
	v_mfma_f32_16x16x32_bf16 v[46:49], v[166:169], v[188:191], v[46:49]
	v_mfma_f32_16x16x32_bf16 v[42:45], v[174:177], v[188:191], v[42:45]
	v_mfma_f32_16x16x32_bf16 v[38:41], v[166:169], v[196:199], v[38:41]
	v_mfma_f32_16x16x32_bf16 v[34:37], v[174:177], v[196:199], v[34:37]
	v_mfma_f32_16x16x32_bf16 v[30:33], v[166:169], v[218:221], v[30:33]
	v_mfma_f32_16x16x32_bf16 v[26:29], v[174:177], v[218:221], v[26:29]
	v_mfma_f32_16x16x32_bf16 v[22:25], v[166:169], v[226:229], v[22:25]
	v_mfma_f32_16x16x32_bf16 v[18:21], v[174:177], v[226:229], v[18:21]
	s_setprio 0
	s_barrier
; #define STAGE(P, BASE, LD, br, kt) do { const bf16* _gb = BASE + ((long)(br) * (LD) + (long)(kt) * BK); \
;     _Pragma("unroll") for (int _i = 0; _i < 2; ++_i) { \
;       __builtin_amdgcn_global_load_lds((const unsigned*)(_gb + ((&LD == &lda) ? offA[_i] : offB[_i])), \
;         (unsigned*)((char*)(P) + tidx_ * 16 + _i * 8192), 16, 0, 0); } } while (0)
; #define LDA(dst, b, h) _Pragma("unroll") for (int m = 0; m < 4; ++m) _Pragma("unroll") for (int k = 0; k < 2; ++k) \
;     dst[m][k] = *reinterpret_cast<const bf16x8*>(smem + (((b) * 2 + (h)) * 16384 + m * 2048 + k * 1024) + aoff)
; #define LDB(dst, b, h) _Pragma("unroll") for (int n = 0; n < 2; ++n) _Pragma("unroll") for (int k = 0; k < 2; ++k) \
;     dst[n][k] = *reinterpret_cast<const bf16x8*>(smem + (((b) * 2 + (h)) * 16384 + n * 2048 + k * 1024) + boff)
; #define MMA(ai, bj, At_, Bt_) do { __builtin_amdgcn_s_setprio(1); \
;     _Pragma("unroll") for (int m = 0; m < 4; ++m) _Pragma("unroll") for (int n = 0; n < 2; ++n) _Pragma("unroll") for (int k = 0; k < 2; ++k) \
;       acc[ai][bj][m][n] = __builtin_amdgcn_mfma_f32_16x16x32_bf16(Bt_[n][k], At_[m][k], acc[ai][bj][m][n], 0, 0, 0); \
;     __builtin_amdgcn_s_setprio(0); } while (0)
; #define WAIT_V(n) asm volatile("s_waitcnt vmcnt(" #n ")" ::: "memory")
; #define WAIT_L(n) asm volatile("s_waitcnt lgkmcnt(" #n ")" ::: "memory")
; #define BAR __builtin_amdgcn_s_barrier()
; #define SCHED __builtin_amdgcn_sched_barrier(0)
; template <class Epi, int NB>
; DEV void gemm_tile_nb(const bf16* __restrict__ A, int lda, long strideA, const bf16* __restrict__ Bt, int ldb, long strideB, int K, int brow, int bcol, Epi& epi) {
;     ...
;     STAGE(SB(0, 1), Bt, ldb, bcol + HALF, t + 2);
;     WAIT_V(6); BAR; MMA(1, 1, At, B1); BAR;
;     LDB(B0, 1, 0); SCHED; LDA(At, 1, 0); STAGE(SA(0, 1), A, lda, brow + HALF, t + 2);
;     WAIT_L(8); BAR; WAIT_L(0); MMA(0, 0, At, B0); BAR; SCHED;
;     LDB(B1, 1, 1); STAGE(SB(1, 0), Bt, ldb, bcol, t + 3);
;     BAR; WAIT_L(0); MMA(0, 1, At, B1); BAR;
	v_readfirstlane_b32 s48, v147
	v_lshl_add_u64 v[162:163], v[214:215], 0, s[58:59]
	s_mov_b32 m0, s48
	v_readfirstlane_b32 s48, v151
	global_load_lds_dwordx4 v[162:163], off
	v_lshl_add_u64 v[162:163], v[246:247], 0, s[58:59]
	s_mov_b32 m0, s48
	s_nop 0
	global_load_lds_dwordx4 v[162:163], off
	ds_read_b128 v[162:165], v144 offset:32768
	ds_read_b128 v[166:169], v144 offset:33792
	ds_read_b128 v[170:173], v144 offset:34816
	ds_read_b128 v[174:177], v144 offset:35840
	s_waitcnt vmcnt(6)
	s_barrier
	s_setprio 1
	v_mfma_f32_16x16x32_bf16 v[14:17], v[230:233], v[184:187], v[14:17]
	v_mfma_f32_16x16x32_bf16 v[10:13], v[238:241], v[184:187], v[10:13]
	v_mfma_f32_16x16x32_bf16 v[6:9], v[230:233], v[192:195], v[6:9]
	v_mfma_f32_16x16x32_bf16 v[2:5], v[238:241], v[192:195], v[2:5]
	v_mfma_f32_16x16x32_bf16 v[66:69], v[230:233], v[200:203], v[66:69]
	v_mfma_f32_16x16x32_bf16 v[74:77], v[238:241], v[200:203], v[74:77]
	v_mfma_f32_16x16x32_bf16 v[78:81], v[230:233], v[222:225], v[78:81]
	v_mfma_f32_16x16x32_bf16 v[82:85], v[238:241], v[222:225], v[82:85]
	v_mfma_f32_16x16x32_bf16 v[14:17], v[234:237], v[188:191], v[14:17]
	v_mfma_f32_16x16x32_bf16 v[10:13], v[242:245], v[188:191], v[10:13]
	v_mfma_f32_16x16x32_bf16 v[6:9], v[234:237], v[196:199], v[6:9]
	v_mfma_f32_16x16x32_bf16 v[2:5], v[242:245], v[196:199], v[2:5]
	v_mfma_f32_16x16x32_bf16 v[66:69], v[234:237], v[218:221], v[66:69]
	v_mfma_f32_16x16x32_bf16 v[74:77], v[242:245], v[218:221], v[74:77]
	v_mfma_f32_16x16x32_bf16 v[78:81], v[234:237], v[226:229], v[78:81]
	v_mfma_f32_16x16x32_bf16 v[82:85], v[242:245], v[226:229], v[82:85]
	s_setprio 0
	s_barrier
	v_readfirstlane_b32 s48, v149
	v_lshl_add_u64 v[230:231], v[204:205], 0, s[16:17]
	s_mov_b32 m0, s48
	v_readfirstlane_b32 s48, v152
	ds_read_b128 v[184:187], v0 offset:32768
	ds_read_b128 v[188:191], v0 offset:33792
	ds_read_b128 v[192:195], v0 offset:34816
	ds_read_b128 v[196:199], v0 offset:35840
	ds_read_b128 v[200:203], v0 offset:36864
	ds_read_b128 v[218:221], v0 offset:37888
	ds_read_b128 v[222:225], v0 offset:38912
	ds_read_b128 v[226:229], v0 offset:39936
	global_load_lds_dwordx4 v[230:231], off
	v_lshl_add_u64 v[230:231], v[208:209], 0, s[16:17]
	s_mov_b32 m0, s48
	s_nop 0
	global_load_lds_dwordx4 v[230:231], off
	s_waitcnt lgkmcnt(8)
	s_barrier
	s_waitcnt lgkmcnt(0)
	s_setprio 1
	s_waitcnt lgkmcnt(0)
	v_mfma_f32_16x16x32_bf16 v[126:129], v[162:165], v[184:187], v[126:129]
	v_mfma_f32_16x16x32_bf16 v[122:125], v[170:173], v[184:187], v[122:125]
	v_mfma_f32_16x16x32_bf16 v[118:121], v[162:165], v[192:195], v[118:121]
	v_mfma_f32_16x16x32_bf16 v[114:117], v[170:173], v[192:195], v[114:117]
	v_mfma_f32_16x16x32_bf16 v[110:113], v[162:165], v[200:203], v[110:113]
	v_mfma_f32_16x16x32_bf16 v[106:109], v[170:173], v[200:203], v[106:109]
	v_mfma_f32_16x16x32_bf16 v[102:105], v[162:165], v[222:225], v[102:105]
	v_mfma_f32_16x16x32_bf16 v[98:101], v[170:173], v[222:225], v[98:101]
	v_mfma_f32_16x16x32_bf16 v[126:129], v[166:169], v[188:191], v[126:129]
	v_mfma_f32_16x16x32_bf16 v[122:125], v[174:177], v[188:191], v[122:125]
	v_mfma_f32_16x16x32_bf16 v[118:121], v[166:169], v[196:199], v[118:121]
	v_mfma_f32_16x16x32_bf16 v[114:117], v[174:177], v[196:199], v[114:117]
	v_mfma_f32_16x16x32_bf16 v[110:113], v[166:169], v[218:221], v[110:113]
	v_mfma_f32_16x16x32_bf16 v[106:109], v[174:177], v[218:221], v[106:109]
	v_mfma_f32_16x16x32_bf16 v[102:105], v[166:169], v[226:229], v[102:105]
	v_mfma_f32_16x16x32_bf16 v[98:101], v[174:177], v[226:229], v[98:101]
	s_setprio 0
	s_barrier
	v_readfirstlane_b32 s48, v153
	v_lshl_add_u64 v[248:249], v[214:215], 0, s[36:37]
	s_mov_b32 m0, s48
	v_readfirstlane_b32 s48, v154
	ds_read_b128 v[230:233], v144 offset:49152
	ds_read_b128 v[234:237], v144 offset:50176
	ds_read_b128 v[238:241], v144 offset:51200
	ds_read_b128 v[242:245], v144 offset:52224
	global_load_lds_dwordx4 v[248:249], off
	v_lshl_add_u64 v[248:249], v[246:247], 0, s[36:37]
	s_mov_b32 m0, s48
	s_nop 0
	global_load_lds_dwordx4 v[248:249], off
	s_barrier
	s_waitcnt lgkmcnt(0)
	s_setprio 1
	s_waitcnt lgkmcnt(0)
	v_mfma_f32_16x16x32_bf16 v[94:97], v[230:233], v[184:187], v[94:97]
	v_mfma_f32_16x16x32_bf16 v[90:93], v[238:241], v[184:187], v[90:93]
	v_mfma_f32_16x16x32_bf16 v[86:89], v[230:233], v[192:195], v[86:89]
	v_mfma_f32_16x16x32_bf16 v[70:73], v[238:241], v[192:195], v[70:73]
	v_mfma_f32_16x16x32_bf16 v[62:65], v[230:233], v[200:203], v[62:65]
	v_mfma_f32_16x16x32_bf16 v[58:61], v[238:241], v[200:203], v[58:61]
	v_mfma_f32_16x16x32_bf16 v[54:57], v[230:233], v[222:225], v[54:57]
	v_mfma_f32_16x16x32_bf16 v[50:53], v[238:241], v[222:225], v[50:53]
	v_mfma_f32_16x16x32_bf16 v[94:97], v[234:237], v[188:191], v[94:97]
	v_mfma_f32_16x16x32_bf16 v[90:93], v[242:245], v[188:191], v[90:93]
	v_mfma_f32_16x16x32_bf16 v[86:89], v[234:237], v[196:199], v[86:89]
	v_mfma_f32_16x16x32_bf16 v[70:73], v[242:245], v[196:199], v[70:73]
	v_mfma_f32_16x16x32_bf16 v[62:65], v[234:237], v[218:221], v[62:65]
	v_mfma_f32_16x16x32_bf16 v[58:61], v[242:245], v[218:221], v[58:61]
	v_mfma_f32_16x16x32_bf16 v[54:57], v[234:237], v[226:229], v[54:57]
	v_mfma_f32_16x16x32_bf16 v[50:53], v[242:245], v[226:229], v[50:53]
	s_setprio 0
	v_readfirstlane_b32 s48, v155
	v_lshl_add_u64 v[204:205], v[204:205], 0, s[18:19]
	s_mov_b32 m0, s48
	v_readfirstlane_b32 s48, v156
	s_barrier
	ds_read_b128 v[184:187], v0 offset:49152
	ds_read_b128 v[188:191], v0 offset:50176
	ds_read_b128 v[192:195], v0 offset:51200
	ds_read_b128 v[196:199], v0 offset:52224
	ds_read_b128 v[200:203], v0 offset:53248
	ds_read_b128 v[218:221], v0 offset:54272
	ds_read_b128 v[222:225], v0 offset:55296
	ds_read_b128 v[226:229], v0 offset:56320
	global_load_lds_dwordx4 v[204:205], off
	v_lshl_add_u64 v[204:205], v[208:209], 0, s[18:19]
	s_mov_b32 m0, s48
	s_nop 0
	global_load_lds_dwordx4 v[204:205], off
	s_waitcnt vmcnt(10)
	s_barrier
; #define STAGE(P, BASE, LD, br, kt) do { const bf16* _gb = BASE + ((long)(br) * (LD) + (long)(kt) * BK); \
;     _Pragma("unroll") for (int _i = 0; _i < 2; ++_i) { \
;       __builtin_amdgcn_global_load_lds((const unsigned*)(_gb + ((&LD == &lda) ? offA[_i] : offB[_i])), \
;         (unsigned*)((char*)(P) + tidx_ * 16 + _i * 8192), 16, 0, 0); } } while (0)
; #define LDA(dst, b, h) _Pragma("unroll") for (int m = 0; m < 4; ++m) _Pragma("unroll") for (int k = 0; k < 2; ++k) \
;     dst[m][k] = *reinterpret_cast<const bf16x8*>(smem + (((b) * 2 + (h)) * 16384 + m * 2048 + k * 1024) + aoff)
; #define LDB(dst, b, h) _Pragma("unroll") for (int n = 0; n < 2; ++n) _Pragma("unroll") for (int k = 0; k < 2; ++k) \
;     dst[n][k] = *reinterpret_cast<const bf16x8*>(smem + (((b) * 2 + (h)) * 16384 + n * 2048 + k * 1024) + boff)
; #define MMA(ai, bj, At_, Bt_) do { __builtin_amdgcn_s_setprio(1); \
;     _Pragma("unroll") for (int m = 0; m < 4; ++m) _Pragma("unroll") for (int n = 0; n < 2; ++n) _Pragma("unroll") for (int k = 0; k < 2; ++k) \
;       acc[ai][bj][m][n] = __builtin_amdgcn_mfma_f32_16x16x32_bf16(Bt_[n][k], At_[m][k], acc[ai][bj][m][n], 0, 0, 0); \
;     __builtin_amdgcn_s_setprio(0); } while (0)
; #define WAIT_V(n) asm volatile("s_waitcnt vmcnt(" #n ")" ::: "memory")
; #define WAIT_L(n) asm volatile("s_waitcnt lgkmcnt(" #n ")" ::: "memory")
; #define BAR __builtin_amdgcn_s_barrier()
; #define SCHED __builtin_amdgcn_sched_barrier(0)
; template <class Epi, int NB>
; DEV void gemm_tile_nb(const bf16* __restrict__ A, int lda, long strideA, const bf16* __restrict__ Bt, int ldb, long strideB, int K, int brow, int bcol, Epi& epi) {
;     ...
;     LDA(At, 1, 1); STAGE(SA(1, 0), A, lda, brow, t + 3);
;     BAR; WAIT_L(0); MMA(1, 0, At, B0); BAR; SCHED;
;     STAGE(SB(1, 1), Bt, ldb, bcol + HALF, t + 3);
;     WAIT_V(6); BAR; MMA(1, 1, At, B1); BAR;
;   }
;   { LDB(B0, 0, 0); LDA(At, 0, 0); STAGE(SA(1, 1), A, lda, brow + HALF, nt - 1);
;     BAR; WAIT_L(0); MMA(0, 0, At, B0); BAR;
	s_waitcnt lgkmcnt(0)
	s_setprio 1
	s_waitcnt lgkmcnt(0)
	v_mfma_f32_16x16x32_bf16 v[46:49], v[162:165], v[184:187], v[46:49]
	v_mfma_f32_16x16x32_bf16 v[42:45], v[170:173], v[184:187], v[42:45]
	v_mfma_f32_16x16x32_bf16 v[38:41], v[162:165], v[192:195], v[38:41]
	v_mfma_f32_16x16x32_bf16 v[34:37], v[170:173], v[192:195], v[34:37]
	v_mfma_f32_16x16x32_bf16 v[30:33], v[162:165], v[200:203], v[30:33]
	v_mfma_f32_16x16x32_bf16 v[26:29], v[170:173], v[200:203], v[26:29]
	v_mfma_f32_16x16x32_bf16 v[22:25], v[162:165], v[222:225], v[22:25]
	v_mfma_f32_16x16x32_bf16 v[18:21], v[170:173], v[222:225], v[18:21]
	v_mfma_f32_16x16x32_bf16 v[46:49], v[166:169], v[188:191], v[46:49]
	v_mfma_f32_16x16x32_bf16 v[42:45], v[174:177], v[188:191], v[42:45]
	v_mfma_f32_16x16x32_bf16 v[38:41], v[166:169], v[196:199], v[38:41]
	v_mfma_f32_16x16x32_bf16 v[34:37], v[174:177], v[196:199], v[34:37]
	v_mfma_f32_16x16x32_bf16 v[30:33], v[166:169], v[218:221], v[30:33]
	v_mfma_f32_16x16x32_bf16 v[26:29], v[174:177], v[218:221], v[26:29]
	v_mfma_f32_16x16x32_bf16 v[22:25], v[166:169], v[226:229], v[22:25]
	v_mfma_f32_16x16x32_bf16 v[18:21], v[174:177], v[226:229], v[18:21]
	s_setprio 0
	s_barrier
	v_readfirstlane_b32 s48, v157
	v_lshl_add_u64 v[162:163], v[214:215], 0, s[22:23]
	s_mov_b32 m0, s48
	v_readfirstlane_b32 s48, v158
	global_load_lds_dwordx4 v[162:163], off
	v_lshl_add_u64 v[162:163], v[246:247], 0, s[22:23]
	s_mov_b32 m0, s48
	s_nop 0
	global_load_lds_dwordx4 v[162:163], off
	ds_read_b128 v[162:165], v144
	ds_read_b128 v[166:169], v144 offset:1024
	ds_read_b128 v[170:173], v144 offset:2048
	ds_read_b128 v[174:177], v144 offset:3072
	s_waitcnt vmcnt(6)
	s_barrier
	s_setprio 1
	v_mfma_f32_16x16x32_bf16 v[14:17], v[230:233], v[184:187], v[14:17]
	v_mfma_f32_16x16x32_bf16 v[10:13], v[238:241], v[184:187], v[10:13]
	v_mfma_f32_16x16x32_bf16 v[6:9], v[230:233], v[192:195], v[6:9]
	v_mfma_f32_16x16x32_bf16 v[2:5], v[238:241], v[192:195], v[2:5]
	v_mfma_f32_16x16x32_bf16 v[66:69], v[230:233], v[200:203], v[66:69]
	v_mfma_f32_16x16x32_bf16 v[74:77], v[238:241], v[200:203], v[74:77]
	v_mfma_f32_16x16x32_bf16 v[78:81], v[230:233], v[222:225], v[78:81]
	v_mfma_f32_16x16x32_bf16 v[82:85], v[238:241], v[222:225], v[82:85]
	v_mfma_f32_16x16x32_bf16 v[14:17], v[234:237], v[188:191], v[14:17]
	v_mfma_f32_16x16x32_bf16 v[10:13], v[242:245], v[188:191], v[10:13]
	v_mfma_f32_16x16x32_bf16 v[6:9], v[234:237], v[196:199], v[6:9]
	v_mfma_f32_16x16x32_bf16 v[2:5], v[242:245], v[196:199], v[2:5]
	v_mfma_f32_16x16x32_bf16 v[66:69], v[234:237], v[218:221], v[66:69]
	v_mfma_f32_16x16x32_bf16 v[74:77], v[242:245], v[218:221], v[74:77]
	v_mfma_f32_16x16x32_bf16 v[78:81], v[234:237], v[226:229], v[78:81]
	v_mfma_f32_16x16x32_bf16 v[82:85], v[242:245], v[226:229], v[82:85]
	s_setprio 0
	s_add_i32 s45, s45, 2
	v_lshl_add_u64 v[134:135], v[134:135], 0, s[72:73]
	v_lshl_add_u64 v[136:137], v[136:137], 0, s[72:73]
	v_lshl_add_u64 v[138:139], v[138:139], 0, s[72:73]
	s_cmp_gt_u32 s45, 11
	v_lshl_add_u64 v[140:141], v[140:141], 0, s[72:73]
	s_barrier
	s_cbranch_scc0 .LBB0_138
	s_mov_b64 s[38:39], 0x780
	v_readfirstlane_b32 s45, v159
	v_lshl_add_u64 v[132:133], v[132:133], 0, s[38:39]
	s_mov_b32 m0, s45
	v_readfirstlane_b32 s45, v160
	ds_read_b128 v[134:137], v144
	ds_read_b128 v[138:141], v144 offset:1024
	ds_read_b128 v[146:149], v144 offset:2048
	ds_read_b128 v[150:153], v144 offset:3072
	ds_read_b128 v[154:157], v0
	ds_read_b128 v[162:165], v0 offset:1024
	ds_read_b128 v[166:169], v0 offset:2048
	ds_read_b128 v[170:173], v0 offset:3072
	ds_read_b128 v[174:177], v0 offset:4096
	ds_read_b128 v[184:187], v0 offset:5120
	ds_read_b128 v[188:191], v0 offset:6144
	ds_read_b128 v[192:195], v0 offset:7168
	global_load_lds_dwordx4 v[132:133], off
	v_lshl_add_u64 v[130:131], v[130:131], 0, s[38:39]
	s_mov_b32 m0, s45
	s_cmpk_lt_u32 s55, 0x100
	global_load_lds_dwordx4 v[130:131], off
	s_barrier
	s_waitcnt lgkmcnt(0)
	s_setprio 1
	s_waitcnt lgkmcnt(0)
	v_mfma_f32_16x16x32_bf16 v[126:129], v[134:137], v[154:157], v[126:129]
	v_mfma_f32_16x16x32_bf16 v[118:121], v[134:137], v[166:169], v[118:121]
	v_mfma_f32_16x16x32_bf16 v[110:113], v[134:137], v[174:177], v[110:113]
	v_mfma_f32_16x16x32_bf16 v[102:105], v[134:137], v[188:191], v[102:105]
	v_mfma_f32_16x16x32_bf16 v[98:101], v[146:149], v[188:191], v[98:101]
	v_mfma_f32_16x16x32_bf16 v[126:129], v[138:141], v[162:165], v[126:129]
	v_mfma_f32_16x16x32_bf16 v[122:125], v[146:149], v[154:157], v[122:125]
	v_mfma_f32_16x16x32_bf16 v[118:121], v[138:141], v[170:173], v[118:121]
	v_mfma_f32_16x16x32_bf16 v[114:117], v[146:149], v[166:169], v[114:117]
	v_mfma_f32_16x16x32_bf16 v[110:113], v[138:141], v[184:187], v[110:113]
	v_mfma_f32_16x16x32_bf16 v[106:109], v[146:149], v[174:177], v[106:109]
	v_mfma_f32_16x16x32_bf16 v[102:105], v[138:141], v[192:195], v[102:105]
	v_mfma_f32_16x16x32_bf16 v[98:101], v[150:153], v[192:195], v[98:101]
	v_mfma_f32_16x16x32_bf16 v[130:133], v[150:153], v[162:165], v[122:125]
	v_mfma_f32_16x16x32_bf16 v[158:161], v[150:153], v[170:173], v[114:117]
	v_mfma_f32_16x16x32_bf16 v[196:199], v[150:153], v[184:187], v[106:109]
	s_setprio 0
	s_barrier
	s_nop 0
	ds_read_b128 v[106:109], v144 offset:16384
	ds_read_b128 v[114:117], v144 offset:17408
	ds_read_b128 v[122:125], v144 offset:18432
	ds_read_b128 v[200:203], v144 offset:19456
	s_barrier
; #define LDA(dst, b, h) _Pragma("unroll") for (int m = 0; m < 4; ++m) _Pragma("unroll") for (int k = 0; k < 2; ++k) \
;     dst[m][k] = *reinterpret_cast<const bf16x8*>(smem + (((b) * 2 + (h)) * 16384 + m * 2048 + k * 1024) + aoff)
; #define LDB(dst, b, h) _Pragma("unroll") for (int n = 0; n < 2; ++n) _Pragma("unroll") for (int k = 0; k < 2; ++k) \
;     dst[n][k] = *reinterpret_cast<const bf16x8*>(smem + (((b) * 2 + (h)) * 16384 + n * 2048 + k * 1024) + boff)
; #define MMA(ai, bj, At_, Bt_) do { __builtin_amdgcn_s_setprio(1); \
;     _Pragma("unroll") for (int m = 0; m < 4; ++m) _Pragma("unroll") for (int n = 0; n < 2; ++n) _Pragma("unroll") for (int k = 0; k < 2; ++k) \
;       acc[ai][bj][m][n] = __builtin_amdgcn_mfma_f32_16x16x32_bf16(Bt_[n][k], At_[m][k], acc[ai][bj][m][n], 0, 0, 0); \
;     __builtin_amdgcn_s_setprio(0); } while (0)
; #define WAIT_V(n) asm volatile("s_waitcnt vmcnt(" #n ")" ::: "memory")
; #define WAIT_L(n) asm volatile("s_waitcnt lgkmcnt(" #n ")" ::: "memory")
; #define BAR __builtin_amdgcn_s_barrier()
; template <class Epi, int NB>
; DEV void gemm_tile_nb(const bf16* __restrict__ A, int lda, long strideA, const bf16* __restrict__ Bt, int ldb, long strideB, int K, int brow, int bcol, Epi& epi) {
;     ...
;     BAR; WAIT_L(0); MMA(0, 0, At, B0); BAR;
;     LDB(B1, 0, 1); BAR; WAIT_L(0); MMA(0, 1, At, B1); BAR;
;     LDA(At, 0, 1); WAIT_V(4); BAR; WAIT_L(0); MMA(1, 0, At, B0); MMA(1, 1, At, B1); BAR; }
;   { LDB(B0, 1, 0); LDA(At, 1, 0); WAIT_V(2); BAR; WAIT_L(0); MMA(0, 0, At, B0); BAR;
	s_waitcnt lgkmcnt(0)
	s_setprio 1
	s_waitcnt lgkmcnt(0)
	v_mfma_f32_16x16x32_bf16 v[86:89], v[106:109], v[166:169], v[86:89]
	v_mfma_f32_16x16x32_bf16 v[70:73], v[122:125], v[166:169], v[70:73]
	v_mfma_f32_16x16x32_bf16 v[62:65], v[106:109], v[174:177], v[62:65]
	v_mfma_f32_16x16x32_bf16 v[58:61], v[122:125], v[174:177], v[58:61]
	v_mfma_f32_16x16x32_bf16 v[54:57], v[106:109], v[188:191], v[54:57]
	v_mfma_f32_16x16x32_bf16 v[50:53], v[122:125], v[188:191], v[50:53]
	v_mfma_f32_16x16x32_bf16 v[94:97], v[106:109], v[154:157], v[94:97]
	v_mfma_f32_16x16x32_bf16 v[90:93], v[122:125], v[154:157], v[90:93]
	v_mfma_f32_16x16x32_bf16 v[86:89], v[114:117], v[170:173], v[86:89]
	v_mfma_f32_16x16x32_bf16 v[70:73], v[200:203], v[170:173], v[70:73]
	v_mfma_f32_16x16x32_bf16 v[62:65], v[114:117], v[184:187], v[62:65]
	v_mfma_f32_16x16x32_bf16 v[58:61], v[200:203], v[184:187], v[58:61]
	v_mfma_f32_16x16x32_bf16 v[54:57], v[114:117], v[192:195], v[54:57]
	v_mfma_f32_16x16x32_bf16 v[50:53], v[200:203], v[192:195], v[50:53]
	v_mfma_f32_16x16x32_bf16 v[218:221], v[114:117], v[162:165], v[94:97]
	v_mfma_f32_16x16x32_bf16 v[154:157], v[200:203], v[162:165], v[90:93]
	s_setprio 0
	s_barrier
	s_nop 0
	ds_read_b128 v[90:93], v0 offset:16384
	ds_read_b128 v[94:97], v0 offset:17408
	ds_read_b128 v[162:165], v0 offset:18432
	ds_read_b128 v[166:169], v0 offset:19456
	ds_read_b128 v[170:173], v0 offset:20480
	ds_read_b128 v[174:177], v0 offset:21504
	ds_read_b128 v[184:187], v0 offset:22528
	ds_read_b128 v[188:191], v0 offset:23552
	s_waitcnt vmcnt(4)
	s_barrier
	s_waitcnt lgkmcnt(0)
	s_setprio 1
	s_waitcnt lgkmcnt(0)
	v_mfma_f32_16x16x32_bf16 v[46:49], v[134:137], v[90:93], v[46:49]
	v_mfma_f32_16x16x32_bf16 v[42:45], v[146:149], v[90:93], v[42:45]
	v_mfma_f32_16x16x32_bf16 v[38:41], v[134:137], v[162:165], v[38:41]
	v_mfma_f32_16x16x32_bf16 v[34:37], v[146:149], v[162:165], v[34:37]
	v_mfma_f32_16x16x32_bf16 v[30:33], v[134:137], v[170:173], v[30:33]
	v_mfma_f32_16x16x32_bf16 v[26:29], v[146:149], v[170:173], v[26:29]
	v_mfma_f32_16x16x32_bf16 v[22:25], v[134:137], v[184:187], v[22:25]
	v_mfma_f32_16x16x32_bf16 v[18:21], v[146:149], v[184:187], v[18:21]
	v_mfma_f32_16x16x32_bf16 v[46:49], v[138:141], v[94:97], v[46:49]
	v_mfma_f32_16x16x32_bf16 v[42:45], v[150:153], v[94:97], v[42:45]
	v_mfma_f32_16x16x32_bf16 v[38:41], v[138:141], v[166:169], v[38:41]
	v_mfma_f32_16x16x32_bf16 v[34:37], v[150:153], v[166:169], v[34:37]
	v_mfma_f32_16x16x32_bf16 v[30:33], v[138:141], v[174:177], v[30:33]
	v_mfma_f32_16x16x32_bf16 v[26:29], v[150:153], v[174:177], v[26:29]
	v_mfma_f32_16x16x32_bf16 v[22:25], v[138:141], v[188:191], v[22:25]
	v_mfma_f32_16x16x32_bf16 v[18:21], v[150:153], v[188:191], v[18:21]
	s_setprio 0
	s_setprio 1
	v_mfma_f32_16x16x32_bf16 v[66:69], v[106:109], v[170:173], v[66:69]
	v_mfma_f32_16x16x32_bf16 v[134:137], v[114:117], v[174:177], v[66:69]
	v_mfma_f32_16x16x32_bf16 v[66:69], v[122:125], v[170:173], v[74:77]
	v_mfma_f32_16x16x32_bf16 v[14:17], v[106:109], v[90:93], v[14:17]
	v_mfma_f32_16x16x32_bf16 v[10:13], v[122:125], v[90:93], v[10:13]
	v_mfma_f32_16x16x32_bf16 v[6:9], v[106:109], v[162:165], v[6:9]
	v_mfma_f32_16x16x32_bf16 v[2:5], v[122:125], v[162:165], v[2:5]
	v_mfma_f32_16x16x32_bf16 v[138:141], v[200:203], v[174:177], v[66:69]
	v_mfma_f32_16x16x32_bf16 v[66:69], v[106:109], v[184:187], v[78:81]
	v_mfma_f32_16x16x32_bf16 v[14:17], v[114:117], v[94:97], v[14:17]
	v_mfma_f32_16x16x32_bf16 v[10:13], v[200:203], v[94:97], v[10:13]
	v_mfma_f32_16x16x32_bf16 v[6:9], v[114:117], v[166:169], v[6:9]
	v_mfma_f32_16x16x32_bf16 v[2:5], v[200:203], v[166:169], v[2:5]
	v_mfma_f32_16x16x32_bf16 v[146:149], v[114:117], v[188:191], v[66:69]
	v_mfma_f32_16x16x32_bf16 v[66:69], v[122:125], v[184:187], v[82:85]
	v_mfma_f32_16x16x32_bf16 v[150:153], v[200:203], v[188:191], v[66:69]
	s_setprio 0
	s_barrier
	ds_read_b128 v[162:165], v144 offset:32768
	ds_read_b128 v[166:169], v144 offset:33792
	ds_read_b128 v[170:173], v144 offset:34816
	ds_read_b128 v[174:177], v144 offset:35840
	s_nop 0
	ds_read_b128 v[66:69], v0 offset:32768
	ds_read_b128 v[74:77], v0 offset:33792
	ds_read_b128 v[78:81], v0 offset:34816
	ds_read_b128 v[184:187], v0 offset:35840
	ds_read_b128 v[188:191], v0 offset:36864
	ds_read_b128 v[192:195], v0 offset:37888
	ds_read_b128 v[200:203], v0 offset:38912
	ds_read_b128 v[222:225], v0 offset:39936
	s_waitcnt vmcnt(2)
	s_barrier
; #define LDA(dst, b, h) _Pragma("unroll") for (int m = 0; m < 4; ++m) _Pragma("unroll") for (int k = 0; k < 2; ++k) \
;     dst[m][k] = *reinterpret_cast<const bf16x8*>(smem + (((b) * 2 + (h)) * 16384 + m * 2048 + k * 1024) + aoff)
; #define LDB(dst, b, h) _Pragma("unroll") for (int n = 0; n < 2; ++n) _Pragma("unroll") for (int k = 0; k < 2; ++k) \
;     dst[n][k] = *reinterpret_cast<const bf16x8*>(smem + (((b) * 2 + (h)) * 16384 + n * 2048 + k * 1024) + boff)
; #define MMA(ai, bj, At_, Bt_) do { __builtin_amdgcn_s_setprio(1); \
;     _Pragma("unroll") for (int m = 0; m < 4; ++m) _Pragma("unroll") for (int n = 0; n < 2; ++n) _Pragma("unroll") for (int k = 0; k < 2; ++k) \
;       acc[ai][bj][m][n] = __builtin_amdgcn_mfma_f32_16x16x32_bf16(Bt_[n][k], At_[m][k], acc[ai][bj][m][n], 0, 0, 0); \
;     __builtin_amdgcn_s_setprio(0); } while (0)
; #define WAIT_V(n) asm volatile("s_waitcnt vmcnt(" #n ")" ::: "memory")
; #define WAIT_L(n) asm volatile("s_waitcnt lgkmcnt(" #n ")" ::: "memory")
; #define BAR __builtin_amdgcn_s_barrier()
; template <class Epi, int NB>
; DEV void gemm_tile_nb(const bf16* __restrict__ A, int lda, long strideA, const bf16* __restrict__ Bt, int ldb, long strideB, int K, int brow, int bcol, Epi& epi) {
;     ...
;   { LDB(B0, 1, 0); LDA(At, 1, 0); WAIT_V(2); BAR; WAIT_L(0); MMA(0, 0, At, B0); BAR;
;     LDB(B1, 1, 1); WAIT_V(0); BAR; WAIT_L(0); MMA(0, 1, At, B1); BAR;
;     LDA(At, 1, 1); BAR; WAIT_L(0); MMA(1, 0, At, B0); MMA(1, 1, At, B1); BAR; }
;   if (wr == 0) BAR;
	s_waitcnt lgkmcnt(0)
	s_setprio 1
	s_waitcnt lgkmcnt(0)
	v_mfma_f32_16x16x32_bf16 v[82:85], v[162:165], v[66:69], v[126:129]
	v_mfma_f32_16x16x32_bf16 v[122:125], v[166:169], v[74:77], v[82:85]
	v_mfma_f32_16x16x32_bf16 v[82:85], v[170:173], v[66:69], v[130:133]
	v_mfma_f32_16x16x32_bf16 v[126:129], v[174:177], v[74:77], v[82:85]
	v_mfma_f32_16x16x32_bf16 v[82:85], v[162:165], v[78:81], v[118:121]
	v_mfma_f32_16x16x32_bf16 v[114:117], v[166:169], v[184:187], v[82:85]
	v_mfma_f32_16x16x32_bf16 v[82:85], v[170:173], v[78:81], v[158:161]
	v_mfma_f32_16x16x32_bf16 v[118:121], v[174:177], v[184:187], v[82:85]
	v_mfma_f32_16x16x32_bf16 v[82:85], v[162:165], v[188:191], v[110:113]
	v_mfma_f32_16x16x32_bf16 v[106:109], v[166:169], v[192:195], v[82:85]
	v_mfma_f32_16x16x32_bf16 v[82:85], v[170:173], v[188:191], v[196:199]
	v_mfma_f32_16x16x32_bf16 v[110:113], v[174:177], v[192:195], v[82:85]
	v_mfma_f32_16x16x32_bf16 v[82:85], v[162:165], v[200:203], v[102:105]
	v_mfma_f32_16x16x32_bf16 v[90:93], v[166:169], v[222:225], v[82:85]
	v_mfma_f32_16x16x32_bf16 v[82:85], v[170:173], v[200:203], v[98:101]
	v_mfma_f32_16x16x32_bf16 v[94:97], v[174:177], v[222:225], v[82:85]
	s_setprio 0
	s_barrier
	ds_read_b128 v[130:133], v144 offset:49152
	ds_read_b128 v[158:161], v144 offset:50176
	ds_read_b128 v[196:199], v144 offset:51200
	ds_read_b128 v[226:229], v144 offset:52224
	s_waitcnt vmcnt(0)
	s_barrier
	s_waitcnt lgkmcnt(0)
	s_setprio 1
	s_waitcnt lgkmcnt(0)
	v_mfma_f32_16x16x32_bf16 v[82:85], v[130:133], v[66:69], v[218:221]
	v_mfma_f32_16x16x32_bf16 v[66:69], v[196:199], v[66:69], v[154:157]
	v_mfma_f32_16x16x32_bf16 v[102:105], v[226:229], v[74:77], v[66:69]
	v_mfma_f32_16x16x32_bf16 v[66:69], v[130:133], v[78:81], v[86:89]
	v_mfma_f32_16x16x32_bf16 v[98:101], v[158:161], v[74:77], v[82:85]
	v_mfma_f32_16x16x32_bf16 v[82:85], v[158:161], v[184:187], v[66:69]
	v_mfma_f32_16x16x32_bf16 v[66:69], v[196:199], v[78:81], v[70:73]
	v_mfma_f32_16x16x32_bf16 v[62:65], v[130:133], v[188:191], v[62:65]
	v_mfma_f32_16x16x32_bf16 v[58:61], v[196:199], v[188:191], v[58:61]
	v_mfma_f32_16x16x32_bf16 v[54:57], v[130:133], v[200:203], v[54:57]
	v_mfma_f32_16x16x32_bf16 v[50:53], v[196:199], v[200:203], v[50:53]
	v_mfma_f32_16x16x32_bf16 v[86:89], v[226:229], v[184:187], v[66:69]
	v_mfma_f32_16x16x32_bf16 v[74:77], v[158:161], v[192:195], v[62:65]
	v_mfma_f32_16x16x32_bf16 v[78:81], v[226:229], v[192:195], v[58:61]
	v_mfma_f32_16x16x32_bf16 v[66:69], v[158:161], v[222:225], v[54:57]
	v_mfma_f32_16x16x32_bf16 v[70:73], v[226:229], v[222:225], v[50:53]
	s_setprio 0
	s_barrier
	ds_read_b128 v[154:157], v0 offset:49152
	ds_read_b128 v[184:187], v0 offset:50176
	ds_read_b128 v[188:191], v0 offset:51200
	ds_read_b128 v[192:195], v0 offset:52224
	ds_read_b128 v[200:203], v0 offset:53248
	ds_read_b128 v[218:221], v0 offset:54272
	ds_read_b128 v[222:225], v0 offset:55296
	ds_read_b128 v[230:233], v0 offset:56320
	s_barrier
	s_waitcnt lgkmcnt(0)
	s_setprio 1
	s_waitcnt lgkmcnt(0)
	v_mfma_f32_16x16x32_bf16 v[46:49], v[162:165], v[154:157], v[46:49]
	v_mfma_f32_16x16x32_bf16 v[42:45], v[170:173], v[154:157], v[42:45]
	v_mfma_f32_16x16x32_bf16 v[38:41], v[162:165], v[188:191], v[38:41]
	v_mfma_f32_16x16x32_bf16 v[34:37], v[170:173], v[188:191], v[34:37]
	v_mfma_f32_16x16x32_bf16 v[30:33], v[162:165], v[200:203], v[30:33]
	v_mfma_f32_16x16x32_bf16 v[26:29], v[170:173], v[200:203], v[26:29]
	v_mfma_f32_16x16x32_bf16 v[22:25], v[162:165], v[222:225], v[22:25]
	v_mfma_f32_16x16x32_bf16 v[18:21], v[170:173], v[222:225], v[18:21]
	v_mfma_f32_16x16x32_bf16 v[58:61], v[166:169], v[184:187], v[46:49]
	v_mfma_f32_16x16x32_bf16 v[62:65], v[174:177], v[184:187], v[42:45]
	v_mfma_f32_16x16x32_bf16 v[50:53], v[166:169], v[192:195], v[38:41]
	v_mfma_f32_16x16x32_bf16 v[54:57], v[174:177], v[192:195], v[34:37]
	v_mfma_f32_16x16x32_bf16 v[42:45], v[166:169], v[218:221], v[30:33]
	v_mfma_f32_16x16x32_bf16 v[46:49], v[174:177], v[218:221], v[26:29]
	v_mfma_f32_16x16x32_bf16 v[34:37], v[166:169], v[230:233], v[22:25]
	v_mfma_f32_16x16x32_bf16 v[38:41], v[174:177], v[230:233], v[18:21]
	s_setprio 0
	s_setprio 1
	v_mfma_f32_16x16x32_bf16 v[2:5], v[196:199], v[188:191], v[2:5]
	v_mfma_f32_16x16x32_bf16 v[10:13], v[196:199], v[154:157], v[10:13]
	v_mfma_f32_16x16x32_bf16 v[22:25], v[226:229], v[192:195], v[2:5]
	v_mfma_f32_16x16x32_bf16 v[2:5], v[130:133], v[200:203], v[134:137]
	v_mfma_f32_16x16x32_bf16 v[14:17], v[130:133], v[154:157], v[14:17]
	v_mfma_f32_16x16x32_bf16 v[30:33], v[226:229], v[184:187], v[10:13]
	v_mfma_f32_16x16x32_bf16 v[6:9], v[130:133], v[188:191], v[6:9]
	v_mfma_f32_16x16x32_bf16 v[10:13], v[158:161], v[218:221], v[2:5]
	v_mfma_f32_16x16x32_bf16 v[2:5], v[196:199], v[200:203], v[138:141]
	v_mfma_f32_16x16x32_bf16 v[26:29], v[158:161], v[184:187], v[14:17]
	v_mfma_f32_16x16x32_bf16 v[18:21], v[158:161], v[192:195], v[6:9]
	v_mfma_f32_16x16x32_bf16 v[14:17], v[226:229], v[218:221], v[2:5]
	v_mfma_f32_16x16x32_bf16 v[2:5], v[130:133], v[222:225], v[146:149]
	v_mfma_f32_16x16x32_bf16 v[6:9], v[196:199], v[222:225], v[150:153]
	v_mfma_f32_16x16x32_bf16 v[2:5], v[158:161], v[230:233], v[2:5]
	v_mfma_f32_16x16x32_bf16 v[6:9], v[226:229], v[230:233], v[6:9]
	s_setprio 0
	v_readlane_b32 s48, v250, 5
	v_readlane_b32 s49, v250, 6
	s_barrier
	s_cbranch_scc0 .LBB0_133
	s_barrier
	s_branch .LBB0_133

; #define STAGE(P, BASE, LD, br, kt) do { const bf16* _gb = BASE + ((long)(br) * (LD) + (long)(kt) * BK); \
;     _Pragma("unroll") for (int _i = 0; _i < 2; ++_i) { \
;       __builtin_amdgcn_global_load_lds((const unsigned*)(_gb + ((&LD == &lda) ? offA[_i] : offB[_i])), \
;         (unsigned*)((char*)(P) + tidx_ * 16 + _i * 8192), 16, 0, 0); } } while (0)
; #define LDA(dst, b, h) _Pragma("unroll") for (int m = 0; m < 4; ++m) _Pragma("unroll") for (int k = 0; k < 2; ++k) \
;     dst[m][k] = *reinterpret_cast<const bf16x8*>(smem + (((b) * 2 + (h)) * 16384 + m * 2048 + k * 1024) + aoff)
; #define LDB(dst, b, h) _Pragma("unroll") for (int n = 0; n < 2; ++n) _Pragma("unroll") for (int k = 0; k < 2; ++k) \
;     dst[n][k] = *reinterpret_cast<const bf16x8*>(smem + (((b) * 2 + (h)) * 16384 + n * 2048 + k * 1024) + boff)
; #define MMA(ai, bj, At_, Bt_) do { __builtin_amdgcn_s_setprio(1); \
;     _Pragma("unroll") for (int m = 0; m < 4; ++m) _Pragma("unroll") for (int n = 0; n < 2; ++n) _Pragma("unroll") for (int k = 0; k < 2; ++k) \
;       acc[ai][bj][m][n] = __builtin_amdgcn_mfma_f32_16x16x32_bf16(Bt_[n][k], At_[m][k], acc[ai][bj][m][n], 0, 0, 0); \
;     __builtin_amdgcn_s_setprio(0); } while (0)
; #define WAIT_L(n) asm volatile("s_waitcnt lgkmcnt(" #n ")" ::: "memory")
; #define BAR __builtin_amdgcn_s_barrier()
; #define SCHED __builtin_amdgcn_sched_barrier(0)
; template <class Epi, int NB>
; DEV void gemm_tile_nb(const bf16* __restrict__ A, int lda, long strideA, const bf16* __restrict__ Bt, int ldb, long strideB, int K, int brow, int bcol, Epi& epi) {
;     ...
;     LDB(B0, 0, 0); SCHED; LDA(At, 0, 0); STAGE(SA(1, 1), A, lda, brow + HALF, t + 1);
;     WAIT_L(8); BAR; WAIT_L(0); MMA(0, 0, At, B0); BAR; SCHED;
;     LDB(B1, 0, 1); STAGE(SB(0, 0), Bt, ldb, bcol, t + 2);
;     BAR; WAIT_L(0); MMA(0, 1, At, B1); BAR;
;     LDA(At, 0, 1); STAGE(SA(0, 0), A, lda, brow, t + 2);
;     BAR; WAIT_L(0); MMA(1, 0, At, B0); BAR; SCHED;
.LBB0_768:
	v_add_u32_e32 v159, 0xc000, v146
	v_lshl_add_u64 v[204:205], s[88:89], 0, v[138:139]
	v_readfirstlane_b32 s42, v159
	v_lshl_add_u64 v[160:161], v[204:205], 0, s[44:45]
	v_lshl_add_u64 v[208:209], s[88:89], 0, v[140:141]
	v_lshl_add_u64 v[214:215], v[208:209], 0, s[44:45]
	s_mov_b32 m0, s42
	ds_read_b128 v[184:187], v0
	ds_read_b128 v[188:191], v0 offset:1024
	ds_read_b128 v[192:195], v0 offset:2048
	ds_read_b128 v[196:199], v0 offset:3072
	ds_read_b128 v[200:203], v0 offset:4096
	ds_read_b128 v[218:221], v0 offset:5120
	ds_read_b128 v[222:225], v0 offset:6144
	ds_read_b128 v[226:229], v0 offset:7168
	global_load_lds_dwordx4 v[160:161], off
	s_add_i32 m0, m0, 0x2000
	v_add_u32_e32 v160, 0xe000, v146
	global_load_lds_dwordx4 v[214:215], off
	s_waitcnt lgkmcnt(8)
	s_barrier
	s_waitcnt lgkmcnt(0)
	s_setprio 1
	s_waitcnt lgkmcnt(0)
	v_mfma_f32_16x16x32_bf16 v[126:129], v[162:165], v[184:187], v[126:129]
	v_mfma_f32_16x16x32_bf16 v[122:125], v[170:173], v[184:187], v[122:125]
	v_mfma_f32_16x16x32_bf16 v[118:121], v[162:165], v[192:195], v[118:121]
	v_mfma_f32_16x16x32_bf16 v[114:117], v[170:173], v[192:195], v[114:117]
	v_mfma_f32_16x16x32_bf16 v[110:113], v[162:165], v[200:203], v[110:113]
	v_mfma_f32_16x16x32_bf16 v[106:109], v[170:173], v[200:203], v[106:109]
	v_mfma_f32_16x16x32_bf16 v[102:105], v[162:165], v[222:225], v[102:105]
	v_mfma_f32_16x16x32_bf16 v[98:101], v[170:173], v[222:225], v[98:101]
	v_mfma_f32_16x16x32_bf16 v[126:129], v[166:169], v[188:191], v[126:129]
	v_mfma_f32_16x16x32_bf16 v[122:125], v[174:177], v[188:191], v[122:125]
	v_mfma_f32_16x16x32_bf16 v[118:121], v[166:169], v[196:199], v[118:121]
	v_mfma_f32_16x16x32_bf16 v[114:117], v[174:177], v[196:199], v[114:117]
	v_mfma_f32_16x16x32_bf16 v[110:113], v[166:169], v[218:221], v[110:113]
	v_mfma_f32_16x16x32_bf16 v[106:109], v[174:177], v[218:221], v[106:109]
	v_mfma_f32_16x16x32_bf16 v[102:105], v[166:169], v[226:229], v[102:105]
	v_mfma_f32_16x16x32_bf16 v[98:101], v[174:177], v[226:229], v[98:101]
	s_setprio 0
	s_barrier
	v_lshl_add_u64 v[214:215], s[88:89], 0, v[134:135]
	v_readfirstlane_b32 s42, v145
	v_lshl_add_u64 v[246:247], v[214:215], 0, s[54:55]
	s_mov_b32 m0, s42
	ds_read_b128 v[230:233], v144 offset:16384
	ds_read_b128 v[234:237], v144 offset:17408
	ds_read_b128 v[238:241], v144 offset:18432
	ds_read_b128 v[242:245], v144 offset:19456
	global_load_lds_dwordx4 v[246:247], off
	v_lshl_add_u64 v[246:247], s[88:89], 0, v[136:137]
	v_readfirstlane_b32 s42, v148
	v_lshl_add_u64 v[248:249], v[246:247], 0, s[54:55]
	s_mov_b32 m0, s42
	s_nop 0
	global_load_lds_dwordx4 v[248:249], off
	s_barrier
	s_waitcnt lgkmcnt(0)
	s_setprio 1
	s_waitcnt lgkmcnt(0)
	v_mfma_f32_16x16x32_bf16 v[94:97], v[230:233], v[184:187], v[94:97]
	v_mfma_f32_16x16x32_bf16 v[90:93], v[238:241], v[184:187], v[90:93]
	v_mfma_f32_16x16x32_bf16 v[86:89], v[230:233], v[192:195], v[86:89]
	v_mfma_f32_16x16x32_bf16 v[70:73], v[238:241], v[192:195], v[70:73]
	v_mfma_f32_16x16x32_bf16 v[62:65], v[230:233], v[200:203], v[62:65]
	v_mfma_f32_16x16x32_bf16 v[58:61], v[238:241], v[200:203], v[58:61]
	v_mfma_f32_16x16x32_bf16 v[54:57], v[230:233], v[222:225], v[54:57]
	v_mfma_f32_16x16x32_bf16 v[50:53], v[238:241], v[222:225], v[50:53]
	v_mfma_f32_16x16x32_bf16 v[94:97], v[234:237], v[188:191], v[94:97]
	v_mfma_f32_16x16x32_bf16 v[90:93], v[242:245], v[188:191], v[90:93]
	v_mfma_f32_16x16x32_bf16 v[86:89], v[234:237], v[196:199], v[86:89]
	v_mfma_f32_16x16x32_bf16 v[70:73], v[242:245], v[196:199], v[70:73]
	v_mfma_f32_16x16x32_bf16 v[62:65], v[234:237], v[218:221], v[62:65]
	v_mfma_f32_16x16x32_bf16 v[58:61], v[242:245], v[218:221], v[58:61]
	v_mfma_f32_16x16x32_bf16 v[54:57], v[234:237], v[226:229], v[54:57]
	v_mfma_f32_16x16x32_bf16 v[50:53], v[242:245], v[226:229], v[50:53]
	s_setprio 0
	v_readfirstlane_b32 s42, v146
	v_lshl_add_u64 v[248:249], v[204:205], 0, s[28:29]
	s_mov_b32 m0, s42
	v_readfirstlane_b32 s42, v150
	s_barrier
	ds_read_b128 v[184:187], v0 offset:16384
	ds_read_b128 v[188:191], v0 offset:17408
	ds_read_b128 v[192:195], v0 offset:18432
	ds_read_b128 v[196:199], v0 offset:19456
	ds_read_b128 v[200:203], v0 offset:20480
	ds_read_b128 v[218:221], v0 offset:21504
	ds_read_b128 v[222:225], v0 offset:22528
	ds_read_b128 v[226:229], v0 offset:23552
	global_load_lds_dwordx4 v[248:249], off
	v_lshl_add_u64 v[248:249], v[208:209], 0, s[28:29]
	s_mov_b32 m0, s42
	s_nop 0
	global_load_lds_dwordx4 v[248:249], off
	s_waitcnt vmcnt(10)
	s_barrier
	s_waitcnt lgkmcnt(0)
	s_setprio 1
	s_waitcnt lgkmcnt(0)
	v_mfma_f32_16x16x32_bf16 v[46:49], v[162:165], v[184:187], v[46:49]
	v_mfma_f32_16x16x32_bf16 v[42:45], v[170:173], v[184:187], v[42:45]
	v_mfma_f32_16x16x32_bf16 v[38:41], v[162:165], v[192:195], v[38:41]
	v_mfma_f32_16x16x32_bf16 v[34:37], v[170:173], v[192:195], v[34:37]
	v_mfma_f32_16x16x32_bf16 v[30:33], v[162:165], v[200:203], v[30:33]
	v_mfma_f32_16x16x32_bf16 v[26:29], v[170:173], v[200:203], v[26:29]
	v_mfma_f32_16x16x32_bf16 v[22:25], v[162:165], v[222:225], v[22:25]
	v_mfma_f32_16x16x32_bf16 v[18:21], v[170:173], v[222:225], v[18:21]
	v_mfma_f32_16x16x32_bf16 v[46:49], v[166:169], v[188:191], v[46:49]
	v_mfma_f32_16x16x32_bf16 v[42:45], v[174:177], v[188:191], v[42:45]
	v_mfma_f32_16x16x32_bf16 v[38:41], v[166:169], v[196:199], v[38:41]
	v_mfma_f32_16x16x32_bf16 v[34:37], v[174:177], v[196:199], v[34:37]
	v_mfma_f32_16x16x32_bf16 v[30:33], v[166:169], v[218:221], v[30:33]
	v_mfma_f32_16x16x32_bf16 v[26:29], v[174:177], v[218:221], v[26:29]
	v_mfma_f32_16x16x32_bf16 v[22:25], v[166:169], v[226:229], v[22:25]
	v_mfma_f32_16x16x32_bf16 v[18:21], v[174:177], v[226:229], v[18:21]
	s_setprio 0
	s_barrier
; #define STAGE(P, BASE, LD, br, kt) do { const bf16* _gb = BASE + ((long)(br) * (LD) + (long)(kt) * BK); \
;     _Pragma("unroll") for (int _i = 0; _i < 2; ++_i) { \
;       __builtin_amdgcn_global_load_lds((const unsigned*)(_gb + ((&LD == &lda) ? offA[_i] : offB[_i])), \
;         (unsigned*)((char*)(P) + tidx_ * 16 + _i * 8192), 16, 0, 0); } } while (0)
; #define LDA(dst, b, h) _Pragma("unroll") for (int m = 0; m < 4; ++m) _Pragma("unroll") for (int k = 0; k < 2; ++k) \
;     dst[m][k] = *reinterpret_cast<const bf16x8*>(smem + (((b) * 2 + (h)) * 16384 + m * 2048 + k * 1024) + aoff)
; #define LDB(dst, b, h) _Pragma("unroll") for (int n = 0; n < 2; ++n) _Pragma("unroll") for (int k = 0; k < 2; ++k) \
;     dst[n][k] = *reinterpret_cast<const bf16x8*>(smem + (((b) * 2 + (h)) * 16384 + n * 2048 + k * 1024) + boff)
; #define MMA(ai, bj, At_, Bt_) do { __builtin_amdgcn_s_setprio(1); \
;     _Pragma("unroll") for (int m = 0; m < 4; ++m) _Pragma("unroll") for (int n = 0; n < 2; ++n) _Pragma("unroll") for (int k = 0; k < 2; ++k) \
;       acc[ai][bj][m][n] = __builtin_amdgcn_mfma_f32_16x16x32_bf16(Bt_[n][k], At_[m][k], acc[ai][bj][m][n], 0, 0, 0); \
;     __builtin_amdgcn_s_setprio(0); } while (0)
; #define WAIT_V(n) asm volatile("s_waitcnt vmcnt(" #n ")" ::: "memory")
; #define WAIT_L(n) asm volatile("s_waitcnt lgkmcnt(" #n ")" ::: "memory")
; #define BAR __builtin_amdgcn_s_barrier()
; #define SCHED __builtin_amdgcn_sched_barrier(0)
; template <class Epi, int NB>
; DEV void gemm_tile_nb(const bf16* __restrict__ A, int lda, long strideA, const bf16* __restrict__ Bt, int ldb, long strideB, int K, int brow, int bcol, Epi& epi) {
;     ...
;     STAGE(SB(0, 1), Bt, ldb, bcol + HALF, t + 2);
;     WAIT_V(6); BAR; MMA(1, 1, At, B1); BAR;
;     LDB(B0, 1, 0); SCHED; LDA(At, 1, 0); STAGE(SA(0, 1), A, lda, brow + HALF, t + 2);
;     WAIT_L(8); BAR; WAIT_L(0); MMA(0, 0, At, B0); BAR; SCHED;
;     LDB(B1, 1, 1); STAGE(SB(1, 0), Bt, ldb, bcol, t + 3);
;     BAR; WAIT_L(0); MMA(0, 1, At, B1); BAR;
	v_readfirstlane_b32 s42, v147
	v_lshl_add_u64 v[162:163], v[214:215], 0, s[56:57]
	s_mov_b32 m0, s42
	v_readfirstlane_b32 s42, v151
	global_load_lds_dwordx4 v[162:163], off
	v_lshl_add_u64 v[162:163], v[246:247], 0, s[56:57]
	s_mov_b32 m0, s42
	s_nop 0
	global_load_lds_dwordx4 v[162:163], off
	ds_read_b128 v[162:165], v144 offset:32768
	ds_read_b128 v[166:169], v144 offset:33792
	ds_read_b128 v[170:173], v144 offset:34816
	ds_read_b128 v[174:177], v144 offset:35840
	s_waitcnt vmcnt(6)
	s_barrier
	s_setprio 1
	v_mfma_f32_16x16x32_bf16 v[14:17], v[230:233], v[184:187], v[14:17]
	v_mfma_f32_16x16x32_bf16 v[10:13], v[238:241], v[184:187], v[10:13]
	v_mfma_f32_16x16x32_bf16 v[6:9], v[230:233], v[192:195], v[6:9]
	v_mfma_f32_16x16x32_bf16 v[2:5], v[238:241], v[192:195], v[2:5]
	v_mfma_f32_16x16x32_bf16 v[66:69], v[230:233], v[200:203], v[66:69]
	v_mfma_f32_16x16x32_bf16 v[74:77], v[238:241], v[200:203], v[74:77]
	v_mfma_f32_16x16x32_bf16 v[78:81], v[230:233], v[222:225], v[78:81]
	v_mfma_f32_16x16x32_bf16 v[82:85], v[238:241], v[222:225], v[82:85]
	v_mfma_f32_16x16x32_bf16 v[14:17], v[234:237], v[188:191], v[14:17]
	v_mfma_f32_16x16x32_bf16 v[10:13], v[242:245], v[188:191], v[10:13]
	v_mfma_f32_16x16x32_bf16 v[6:9], v[234:237], v[196:199], v[6:9]
	v_mfma_f32_16x16x32_bf16 v[2:5], v[242:245], v[196:199], v[2:5]
	v_mfma_f32_16x16x32_bf16 v[66:69], v[234:237], v[218:221], v[66:69]
	v_mfma_f32_16x16x32_bf16 v[74:77], v[242:245], v[218:221], v[74:77]
	v_mfma_f32_16x16x32_bf16 v[78:81], v[234:237], v[226:229], v[78:81]
	v_mfma_f32_16x16x32_bf16 v[82:85], v[242:245], v[226:229], v[82:85]
	s_setprio 0
	s_barrier
	v_readfirstlane_b32 s42, v149
	v_lshl_add_u64 v[230:231], v[204:205], 0, s[58:59]
	s_mov_b32 m0, s42
	v_readfirstlane_b32 s42, v152
	ds_read_b128 v[184:187], v0 offset:32768
	ds_read_b128 v[188:191], v0 offset:33792
	ds_read_b128 v[192:195], v0 offset:34816
	ds_read_b128 v[196:199], v0 offset:35840
	ds_read_b128 v[200:203], v0 offset:36864
	ds_read_b128 v[218:221], v0 offset:37888
	ds_read_b128 v[222:225], v0 offset:38912
	ds_read_b128 v[226:229], v0 offset:39936
	global_load_lds_dwordx4 v[230:231], off
	v_lshl_add_u64 v[230:231], v[208:209], 0, s[58:59]
	s_mov_b32 m0, s42
	s_nop 0
	global_load_lds_dwordx4 v[230:231], off
	s_waitcnt lgkmcnt(8)
	s_barrier
	s_waitcnt lgkmcnt(0)
	s_setprio 1
	s_waitcnt lgkmcnt(0)
	v_mfma_f32_16x16x32_bf16 v[126:129], v[162:165], v[184:187], v[126:129]
	v_mfma_f32_16x16x32_bf16 v[122:125], v[170:173], v[184:187], v[122:125]
	v_mfma_f32_16x16x32_bf16 v[118:121], v[162:165], v[192:195], v[118:121]
	v_mfma_f32_16x16x32_bf16 v[114:117], v[170:173], v[192:195], v[114:117]
	v_mfma_f32_16x16x32_bf16 v[110:113], v[162:165], v[200:203], v[110:113]
	v_mfma_f32_16x16x32_bf16 v[106:109], v[170:173], v[200:203], v[106:109]
	v_mfma_f32_16x16x32_bf16 v[102:105], v[162:165], v[222:225], v[102:105]
	v_mfma_f32_16x16x32_bf16 v[98:101], v[170:173], v[222:225], v[98:101]
	v_mfma_f32_16x16x32_bf16 v[126:129], v[166:169], v[188:191], v[126:129]
	v_mfma_f32_16x16x32_bf16 v[122:125], v[174:177], v[188:191], v[122:125]
	v_mfma_f32_16x16x32_bf16 v[118:121], v[166:169], v[196:199], v[118:121]
	v_mfma_f32_16x16x32_bf16 v[114:117], v[174:177], v[196:199], v[114:117]
	v_mfma_f32_16x16x32_bf16 v[110:113], v[166:169], v[218:221], v[110:113]
	v_mfma_f32_16x16x32_bf16 v[106:109], v[174:177], v[218:221], v[106:109]
	v_mfma_f32_16x16x32_bf16 v[102:105], v[166:169], v[226:229], v[102:105]
	v_mfma_f32_16x16x32_bf16 v[98:101], v[174:177], v[226:229], v[98:101]
	s_setprio 0
	s_barrier
	v_readfirstlane_b32 s42, v153
	v_lshl_add_u64 v[248:249], v[214:215], 0, s[60:61]
	s_mov_b32 m0, s42
	v_readfirstlane_b32 s42, v154
	ds_read_b128 v[230:233], v144 offset:49152
	ds_read_b128 v[234:237], v144 offset:50176
	ds_read_b128 v[238:241], v144 offset:51200
	ds_read_b128 v[242:245], v144 offset:52224
	global_load_lds_dwordx4 v[248:249], off
	v_lshl_add_u64 v[248:249], v[246:247], 0, s[60:61]
	s_mov_b32 m0, s42
	s_nop 0
	global_load_lds_dwordx4 v[248:249], off
	s_barrier
	s_waitcnt lgkmcnt(0)
	s_setprio 1
	s_waitcnt lgkmcnt(0)
	v_mfma_f32_16x16x32_bf16 v[94:97], v[230:233], v[184:187], v[94:97]
	v_mfma_f32_16x16x32_bf16 v[90:93], v[238:241], v[184:187], v[90:93]
	v_mfma_f32_16x16x32_bf16 v[86:89], v[230:233], v[192:195], v[86:89]
	v_mfma_f32_16x16x32_bf16 v[70:73], v[238:241], v[192:195], v[70:73]
	v_mfma_f32_16x16x32_bf16 v[62:65], v[230:233], v[200:203], v[62:65]
	v_mfma_f32_16x16x32_bf16 v[58:61], v[238:241], v[200:203], v[58:61]
	v_mfma_f32_16x16x32_bf16 v[54:57], v[230:233], v[222:225], v[54:57]
	v_mfma_f32_16x16x32_bf16 v[50:53], v[238:241], v[222:225], v[50:53]
	v_mfma_f32_16x16x32_bf16 v[94:97], v[234:237], v[188:191], v[94:97]
	v_mfma_f32_16x16x32_bf16 v[90:93], v[242:245], v[188:191], v[90:93]
	v_mfma_f32_16x16x32_bf16 v[86:89], v[234:237], v[196:199], v[86:89]
	v_mfma_f32_16x16x32_bf16 v[70:73], v[242:245], v[196:199], v[70:73]
	v_mfma_f32_16x16x32_bf16 v[62:65], v[234:237], v[218:221], v[62:65]
	v_mfma_f32_16x16x32_bf16 v[58:61], v[242:245], v[218:221], v[58:61]
	v_mfma_f32_16x16x32_bf16 v[54:57], v[234:237], v[226:229], v[54:57]
	v_mfma_f32_16x16x32_bf16 v[50:53], v[242:245], v[226:229], v[50:53]
	s_setprio 0
	v_readfirstlane_b32 s42, v155
	v_lshl_add_u64 v[204:205], v[204:205], 0, s[20:21]
	s_mov_b32 m0, s42
	v_readfirstlane_b32 s42, v156
	s_barrier
	ds_read_b128 v[184:187], v0 offset:49152
	ds_read_b128 v[188:191], v0 offset:50176
	ds_read_b128 v[192:195], v0 offset:51200
	ds_read_b128 v[196:199], v0 offset:52224
	ds_read_b128 v[200:203], v0 offset:53248
	ds_read_b128 v[218:221], v0 offset:54272
	ds_read_b128 v[222:225], v0 offset:55296
	ds_read_b128 v[226:229], v0 offset:56320
	global_load_lds_dwordx4 v[204:205], off
	v_lshl_add_u64 v[204:205], v[208:209], 0, s[20:21]
	s_mov_b32 m0, s42
	s_nop 0
	global_load_lds_dwordx4 v[204:205], off
	s_waitcnt vmcnt(10)
	s_barrier
; #define STAGE(P, BASE, LD, br, kt) do { const bf16* _gb = BASE + ((long)(br) * (LD) + (long)(kt) * BK); \
;     _Pragma("unroll") for (int _i = 0; _i < 2; ++_i) { \
;       __builtin_amdgcn_global_load_lds((const unsigned*)(_gb + ((&LD == &lda) ? offA[_i] : offB[_i])), \
;         (unsigned*)((char*)(P) + tidx_ * 16 + _i * 8192), 16, 0, 0); } } while (0)
; #define LDA(dst, b, h) _Pragma("unroll") for (int m = 0; m < 4; ++m) _Pragma("unroll") for (int k = 0; k < 2; ++k) \
;     dst[m][k] = *reinterpret_cast<const bf16x8*>(smem + (((b) * 2 + (h)) * 16384 + m * 2048 + k * 1024) + aoff)
; #define LDB(dst, b, h) _Pragma("unroll") for (int n = 0; n < 2; ++n) _Pragma("unroll") for (int k = 0; k < 2; ++k) \
;     dst[n][k] = *reinterpret_cast<const bf16x8*>(smem + (((b) * 2 + (h)) * 16384 + n * 2048 + k * 1024) + boff)
; #define MMA(ai, bj, At_, Bt_) do { __builtin_amdgcn_s_setprio(1); \
;     _Pragma("unroll") for (int m = 0; m < 4; ++m) _Pragma("unroll") for (int n = 0; n < 2; ++n) _Pragma("unroll") for (int k = 0; k < 2; ++k) \
;       acc[ai][bj][m][n] = __builtin_amdgcn_mfma_f32_16x16x32_bf16(Bt_[n][k], At_[m][k], acc[ai][bj][m][n], 0, 0, 0); \
;     __builtin_amdgcn_s_setprio(0); } while (0)
; #define WAIT_V(n) asm volatile("s_waitcnt vmcnt(" #n ")" ::: "memory")
; #define WAIT_L(n) asm volatile("s_waitcnt lgkmcnt(" #n ")" ::: "memory")
; #define BAR __builtin_amdgcn_s_barrier()
; #define SCHED __builtin_amdgcn_sched_barrier(0)
; template <class Epi, int NB>
; DEV void gemm_tile_nb(const bf16* __restrict__ A, int lda, long strideA, const bf16* __restrict__ Bt, int ldb, long strideB, int K, int brow, int bcol, Epi& epi) {
;     ...
;     LDA(At, 1, 1); STAGE(SA(1, 0), A, lda, brow, t + 3);
;     BAR; WAIT_L(0); MMA(1, 0, At, B0); BAR; SCHED;
;     STAGE(SB(1, 1), Bt, ldb, bcol + HALF, t + 3);
;     WAIT_V(6); BAR; MMA(1, 1, At, B1); BAR;
;   }
;   { LDB(B0, 0, 0); LDA(At, 0, 0); STAGE(SA(1, 1), A, lda, brow + HALF, nt - 1);
;     BAR; WAIT_L(0); MMA(0, 0, At, B0); BAR;
	s_waitcnt lgkmcnt(0)
	s_setprio 1
	s_waitcnt lgkmcnt(0)
	v_mfma_f32_16x16x32_bf16 v[46:49], v[162:165], v[184:187], v[46:49]
	v_mfma_f32_16x16x32_bf16 v[42:45], v[170:173], v[184:187], v[42:45]
	v_mfma_f32_16x16x32_bf16 v[38:41], v[162:165], v[192:195], v[38:41]
	v_mfma_f32_16x16x32_bf16 v[34:37], v[170:173], v[192:195], v[34:37]
	v_mfma_f32_16x16x32_bf16 v[30:33], v[162:165], v[200:203], v[30:33]
	v_mfma_f32_16x16x32_bf16 v[26:29], v[170:173], v[200:203], v[26:29]
	v_mfma_f32_16x16x32_bf16 v[22:25], v[162:165], v[222:225], v[22:25]
	v_mfma_f32_16x16x32_bf16 v[18:21], v[170:173], v[222:225], v[18:21]
	v_mfma_f32_16x16x32_bf16 v[46:49], v[166:169], v[188:191], v[46:49]
	v_mfma_f32_16x16x32_bf16 v[42:45], v[174:177], v[188:191], v[42:45]
	v_mfma_f32_16x16x32_bf16 v[38:41], v[166:169], v[196:199], v[38:41]
	v_mfma_f32_16x16x32_bf16 v[34:37], v[174:177], v[196:199], v[34:37]
	v_mfma_f32_16x16x32_bf16 v[30:33], v[166:169], v[218:221], v[30:33]
	v_mfma_f32_16x16x32_bf16 v[26:29], v[174:177], v[218:221], v[26:29]
	v_mfma_f32_16x16x32_bf16 v[22:25], v[166:169], v[226:229], v[22:25]
	v_mfma_f32_16x16x32_bf16 v[18:21], v[174:177], v[226:229], v[18:21]
	s_setprio 0
	s_barrier
	v_readfirstlane_b32 s42, v157
	v_lshl_add_u64 v[162:163], v[214:215], 0, s[62:63]
	s_mov_b32 m0, s42
	v_readfirstlane_b32 s42, v158
	global_load_lds_dwordx4 v[162:163], off
	v_lshl_add_u64 v[162:163], v[246:247], 0, s[62:63]
	s_mov_b32 m0, s42
	s_nop 0
	global_load_lds_dwordx4 v[162:163], off
	ds_read_b128 v[162:165], v144
	ds_read_b128 v[166:169], v144 offset:1024
	ds_read_b128 v[170:173], v144 offset:2048
	ds_read_b128 v[174:177], v144 offset:3072
	s_waitcnt vmcnt(6)
	s_barrier
	s_setprio 1
	v_mfma_f32_16x16x32_bf16 v[14:17], v[230:233], v[184:187], v[14:17]
	v_mfma_f32_16x16x32_bf16 v[10:13], v[238:241], v[184:187], v[10:13]
	v_mfma_f32_16x16x32_bf16 v[6:9], v[230:233], v[192:195], v[6:9]
	v_mfma_f32_16x16x32_bf16 v[2:5], v[238:241], v[192:195], v[2:5]
	v_mfma_f32_16x16x32_bf16 v[66:69], v[230:233], v[200:203], v[66:69]
	v_mfma_f32_16x16x32_bf16 v[74:77], v[238:241], v[200:203], v[74:77]
	v_mfma_f32_16x16x32_bf16 v[78:81], v[230:233], v[222:225], v[78:81]
	v_mfma_f32_16x16x32_bf16 v[82:85], v[238:241], v[222:225], v[82:85]
	v_mfma_f32_16x16x32_bf16 v[14:17], v[234:237], v[188:191], v[14:17]
	v_mfma_f32_16x16x32_bf16 v[10:13], v[242:245], v[188:191], v[10:13]
	v_mfma_f32_16x16x32_bf16 v[6:9], v[234:237], v[196:199], v[6:9]
	v_mfma_f32_16x16x32_bf16 v[2:5], v[242:245], v[196:199], v[2:5]
	v_mfma_f32_16x16x32_bf16 v[66:69], v[234:237], v[218:221], v[66:69]
	v_mfma_f32_16x16x32_bf16 v[74:77], v[242:245], v[218:221], v[74:77]
	v_mfma_f32_16x16x32_bf16 v[78:81], v[234:237], v[226:229], v[78:81]
	v_mfma_f32_16x16x32_bf16 v[82:85], v[242:245], v[226:229], v[82:85]
	s_setprio 0
	s_add_i32 s41, s41, 2
	v_lshl_add_u64 v[134:135], v[134:135], 0, s[72:73]
	v_lshl_add_u64 v[136:137], v[136:137], 0, s[72:73]
	v_lshl_add_u64 v[138:139], v[138:139], 0, s[72:73]
	s_cmp_lt_u32 s41, 12
	v_lshl_add_u64 v[140:141], v[140:141], 0, s[72:73]
	s_barrier
	s_cbranch_scc1 .LBB0_768
	s_mov_b64 s[42:43], 0x780
	v_readfirstlane_b32 s41, v159
	v_lshl_add_u64 v[132:133], v[132:133], 0, s[42:43]
	s_mov_b32 m0, s41
	v_readfirstlane_b32 s41, v160
	ds_read_b128 v[134:137], v144
	ds_read_b128 v[138:141], v144 offset:1024
	ds_read_b128 v[146:149], v144 offset:2048
	ds_read_b128 v[150:153], v144 offset:3072
	ds_read_b128 v[154:157], v0
	ds_read_b128 v[162:165], v0 offset:1024
	ds_read_b128 v[166:169], v0 offset:2048
	ds_read_b128 v[170:173], v0 offset:3072
	ds_read_b128 v[174:177], v0 offset:4096
	ds_read_b128 v[184:187], v0 offset:5120
	ds_read_b128 v[188:191], v0 offset:6144
	ds_read_b128 v[192:195], v0 offset:7168
	global_load_lds_dwordx4 v[132:133], off
	v_lshl_add_u64 v[130:131], v[130:131], 0, s[42:43]
	s_mov_b32 m0, s41
	s_cmpk_gt_u32 s52, 0xff
	global_load_lds_dwordx4 v[130:131], off
	s_barrier
	s_waitcnt lgkmcnt(0)
	s_setprio 1
	s_waitcnt lgkmcnt(0)
	v_mfma_f32_16x16x32_bf16 v[126:129], v[134:137], v[154:157], v[126:129]
	v_mfma_f32_16x16x32_bf16 v[118:121], v[134:137], v[166:169], v[118:121]
	v_mfma_f32_16x16x32_bf16 v[110:113], v[134:137], v[174:177], v[110:113]
	v_mfma_f32_16x16x32_bf16 v[102:105], v[134:137], v[188:191], v[102:105]
	v_mfma_f32_16x16x32_bf16 v[98:101], v[146:149], v[188:191], v[98:101]
	v_mfma_f32_16x16x32_bf16 v[126:129], v[138:141], v[162:165], v[126:129]
	v_mfma_f32_16x16x32_bf16 v[122:125], v[146:149], v[154:157], v[122:125]
	v_mfma_f32_16x16x32_bf16 v[118:121], v[138:141], v[170:173], v[118:121]
	v_mfma_f32_16x16x32_bf16 v[114:117], v[146:149], v[166:169], v[114:117]
	v_mfma_f32_16x16x32_bf16 v[110:113], v[138:141], v[184:187], v[110:113]
	v_mfma_f32_16x16x32_bf16 v[106:109], v[146:149], v[174:177], v[106:109]
	v_mfma_f32_16x16x32_bf16 v[102:105], v[138:141], v[192:195], v[102:105]
	v_mfma_f32_16x16x32_bf16 v[98:101], v[150:153], v[192:195], v[98:101]
	v_mfma_f32_16x16x32_bf16 v[130:133], v[150:153], v[162:165], v[122:125]
	v_mfma_f32_16x16x32_bf16 v[158:161], v[150:153], v[170:173], v[114:117]
	v_mfma_f32_16x16x32_bf16 v[196:199], v[150:153], v[184:187], v[106:109]
	s_setprio 0
	s_barrier
	s_nop 0
	ds_read_b128 v[106:109], v144 offset:16384
	ds_read_b128 v[114:117], v144 offset:17408
	ds_read_b128 v[122:125], v144 offset:18432
	ds_read_b128 v[200:203], v144 offset:19456
	s_barrier
; #define LDA(dst, b, h) _Pragma("unroll") for (int m = 0; m < 4; ++m) _Pragma("unroll") for (int k = 0; k < 2; ++k) \
;     dst[m][k] = *reinterpret_cast<const bf16x8*>(smem + (((b) * 2 + (h)) * 16384 + m * 2048 + k * 1024) + aoff)
; #define LDB(dst, b, h) _Pragma("unroll") for (int n = 0; n < 2; ++n) _Pragma("unroll") for (int k = 0; k < 2; ++k) \
;     dst[n][k] = *reinterpret_cast<const bf16x8*>(smem + (((b) * 2 + (h)) * 16384 + n * 2048 + k * 1024) + boff)
; #define MMA(ai, bj, At_, Bt_) do { __builtin_amdgcn_s_setprio(1); \
;     _Pragma("unroll") for (int m = 0; m < 4; ++m) _Pragma("unroll") for (int n = 0; n < 2; ++n) _Pragma("unroll") for (int k = 0; k < 2; ++k) \
;       acc[ai][bj][m][n] = __builtin_amdgcn_mfma_f32_16x16x32_bf16(Bt_[n][k], At_[m][k], acc[ai][bj][m][n], 0, 0, 0); \
;     __builtin_amdgcn_s_setprio(0); } while (0)
; #define WAIT_V(n) asm volatile("s_waitcnt vmcnt(" #n ")" ::: "memory")
; #define WAIT_L(n) asm volatile("s_waitcnt lgkmcnt(" #n ")" ::: "memory")
; #define BAR __builtin_amdgcn_s_barrier()
; template <class Epi, int NB>
; DEV void gemm_tile_nb(const bf16* __restrict__ A, int lda, long strideA, const bf16* __restrict__ Bt, int ldb, long strideB, int K, int brow, int bcol, Epi& epi) {
;     ...
;     BAR; WAIT_L(0); MMA(0, 0, At, B0); BAR;
;     LDB(B1, 0, 1); BAR; WAIT_L(0); MMA(0, 1, At, B1); BAR;
;     LDA(At, 0, 1); WAIT_V(4); BAR; WAIT_L(0); MMA(1, 0, At, B0); MMA(1, 1, At, B1); BAR; }
;   { LDB(B0, 1, 0); LDA(At, 1, 0); WAIT_V(2); BAR; WAIT_L(0); MMA(0, 0, At, B0); BAR;
	s_waitcnt lgkmcnt(0)
	s_setprio 1
	s_waitcnt lgkmcnt(0)
	v_mfma_f32_16x16x32_bf16 v[86:89], v[106:109], v[166:169], v[86:89]
	v_mfma_f32_16x16x32_bf16 v[70:73], v[122:125], v[166:169], v[70:73]
	v_mfma_f32_16x16x32_bf16 v[62:65], v[106:109], v[174:177], v[62:65]
	v_mfma_f32_16x16x32_bf16 v[58:61], v[122:125], v[174:177], v[58:61]
	v_mfma_f32_16x16x32_bf16 v[54:57], v[106:109], v[188:191], v[54:57]
	v_mfma_f32_16x16x32_bf16 v[50:53], v[122:125], v[188:191], v[50:53]
	v_mfma_f32_16x16x32_bf16 v[94:97], v[106:109], v[154:157], v[94:97]
	v_mfma_f32_16x16x32_bf16 v[90:93], v[122:125], v[154:157], v[90:93]
	v_mfma_f32_16x16x32_bf16 v[86:89], v[114:117], v[170:173], v[86:89]
	v_mfma_f32_16x16x32_bf16 v[70:73], v[200:203], v[170:173], v[70:73]
	v_mfma_f32_16x16x32_bf16 v[62:65], v[114:117], v[184:187], v[62:65]
	v_mfma_f32_16x16x32_bf16 v[58:61], v[200:203], v[184:187], v[58:61]
	v_mfma_f32_16x16x32_bf16 v[54:57], v[114:117], v[192:195], v[54:57]
	v_mfma_f32_16x16x32_bf16 v[50:53], v[200:203], v[192:195], v[50:53]
	v_mfma_f32_16x16x32_bf16 v[218:221], v[114:117], v[162:165], v[94:97]
	v_mfma_f32_16x16x32_bf16 v[154:157], v[200:203], v[162:165], v[90:93]
	s_setprio 0
	s_barrier
	s_nop 0
	ds_read_b128 v[90:93], v0 offset:16384
	ds_read_b128 v[94:97], v0 offset:17408
	ds_read_b128 v[162:165], v0 offset:18432
	ds_read_b128 v[166:169], v0 offset:19456
	ds_read_b128 v[170:173], v0 offset:20480
	ds_read_b128 v[174:177], v0 offset:21504
	ds_read_b128 v[184:187], v0 offset:22528
	ds_read_b128 v[188:191], v0 offset:23552
	s_waitcnt vmcnt(4)
	s_barrier
	s_waitcnt lgkmcnt(0)
	s_setprio 1
	s_waitcnt lgkmcnt(0)
	v_mfma_f32_16x16x32_bf16 v[46:49], v[134:137], v[90:93], v[46:49]
	v_mfma_f32_16x16x32_bf16 v[42:45], v[146:149], v[90:93], v[42:45]
	v_mfma_f32_16x16x32_bf16 v[38:41], v[134:137], v[162:165], v[38:41]
	v_mfma_f32_16x16x32_bf16 v[34:37], v[146:149], v[162:165], v[34:37]
	v_mfma_f32_16x16x32_bf16 v[30:33], v[134:137], v[170:173], v[30:33]
	v_mfma_f32_16x16x32_bf16 v[26:29], v[146:149], v[170:173], v[26:29]
	v_mfma_f32_16x16x32_bf16 v[22:25], v[134:137], v[184:187], v[22:25]
	v_mfma_f32_16x16x32_bf16 v[18:21], v[146:149], v[184:187], v[18:21]
	v_mfma_f32_16x16x32_bf16 v[46:49], v[138:141], v[94:97], v[46:49]
	v_mfma_f32_16x16x32_bf16 v[42:45], v[150:153], v[94:97], v[42:45]
	v_mfma_f32_16x16x32_bf16 v[38:41], v[138:141], v[166:169], v[38:41]
	v_mfma_f32_16x16x32_bf16 v[34:37], v[150:153], v[166:169], v[34:37]
	v_mfma_f32_16x16x32_bf16 v[30:33], v[138:141], v[174:177], v[30:33]
	v_mfma_f32_16x16x32_bf16 v[26:29], v[150:153], v[174:177], v[26:29]
	v_mfma_f32_16x16x32_bf16 v[22:25], v[138:141], v[188:191], v[22:25]
	v_mfma_f32_16x16x32_bf16 v[18:21], v[150:153], v[188:191], v[18:21]
	s_setprio 0
	s_setprio 1
	v_mfma_f32_16x16x32_bf16 v[66:69], v[106:109], v[170:173], v[66:69]
	v_mfma_f32_16x16x32_bf16 v[134:137], v[114:117], v[174:177], v[66:69]
	v_mfma_f32_16x16x32_bf16 v[66:69], v[122:125], v[170:173], v[74:77]
	v_mfma_f32_16x16x32_bf16 v[14:17], v[106:109], v[90:93], v[14:17]
	v_mfma_f32_16x16x32_bf16 v[10:13], v[122:125], v[90:93], v[10:13]
	v_mfma_f32_16x16x32_bf16 v[6:9], v[106:109], v[162:165], v[6:9]
	v_mfma_f32_16x16x32_bf16 v[2:5], v[122:125], v[162:165], v[2:5]
	v_mfma_f32_16x16x32_bf16 v[138:141], v[200:203], v[174:177], v[66:69]
	v_mfma_f32_16x16x32_bf16 v[66:69], v[106:109], v[184:187], v[78:81]
	v_mfma_f32_16x16x32_bf16 v[14:17], v[114:117], v[94:97], v[14:17]
	v_mfma_f32_16x16x32_bf16 v[10:13], v[200:203], v[94:97], v[10:13]
	v_mfma_f32_16x16x32_bf16 v[6:9], v[114:117], v[166:169], v[6:9]
	v_mfma_f32_16x16x32_bf16 v[2:5], v[200:203], v[166:169], v[2:5]
	v_mfma_f32_16x16x32_bf16 v[146:149], v[114:117], v[188:191], v[66:69]
	v_mfma_f32_16x16x32_bf16 v[66:69], v[122:125], v[184:187], v[82:85]
	v_mfma_f32_16x16x32_bf16 v[150:153], v[200:203], v[188:191], v[66:69]
	s_setprio 0
	s_barrier
	ds_read_b128 v[162:165], v144 offset:32768
	ds_read_b128 v[166:169], v144 offset:33792
	ds_read_b128 v[170:173], v144 offset:34816
	ds_read_b128 v[174:177], v144 offset:35840
	s_nop 0
	ds_read_b128 v[66:69], v0 offset:32768
	ds_read_b128 v[74:77], v0 offset:33792
	ds_read_b128 v[78:81], v0 offset:34816
	ds_read_b128 v[184:187], v0 offset:35840
	ds_read_b128 v[188:191], v0 offset:36864
	ds_read_b128 v[192:195], v0 offset:37888
	ds_read_b128 v[200:203], v0 offset:38912
	ds_read_b128 v[222:225], v0 offset:39936
	s_waitcnt vmcnt(2)
	s_barrier
; #define LDA(dst, b, h) _Pragma("unroll") for (int m = 0; m < 4; ++m) _Pragma("unroll") for (int k = 0; k < 2; ++k) \
;     dst[m][k] = *reinterpret_cast<const bf16x8*>(smem + (((b) * 2 + (h)) * 16384 + m * 2048 + k * 1024) + aoff)
; #define LDB(dst, b, h) _Pragma("unroll") for (int n = 0; n < 2; ++n) _Pragma("unroll") for (int k = 0; k < 2; ++k) \
;     dst[n][k] = *reinterpret_cast<const bf16x8*>(smem + (((b) * 2 + (h)) * 16384 + n * 2048 + k * 1024) + boff)
; #define MMA(ai, bj, At_, Bt_) do { __builtin_amdgcn_s_setprio(1); \
;     _Pragma("unroll") for (int m = 0; m < 4; ++m) _Pragma("unroll") for (int n = 0; n < 2; ++n) _Pragma("unroll") for (int k = 0; k < 2; ++k) \
;       acc[ai][bj][m][n] = __builtin_amdgcn_mfma_f32_16x16x32_bf16(Bt_[n][k], At_[m][k], acc[ai][bj][m][n], 0, 0, 0); \
;     __builtin_amdgcn_s_setprio(0); } while (0)
; #define WAIT_V(n) asm volatile("s_waitcnt vmcnt(" #n ")" ::: "memory")
; #define WAIT_L(n) asm volatile("s_waitcnt lgkmcnt(" #n ")" ::: "memory")
; #define BAR __builtin_amdgcn_s_barrier()
; template <class Epi, int NB>
; DEV void gemm_tile_nb(const bf16* __restrict__ A, int lda, long strideA, const bf16* __restrict__ Bt, int ldb, long strideB, int K, int brow, int bcol, Epi& epi) {
;     ...
;   { LDB(B0, 1, 0); LDA(At, 1, 0); WAIT_V(2); BAR; WAIT_L(0); MMA(0, 0, At, B0); BAR;
;     LDB(B1, 1, 1); WAIT_V(0); BAR; WAIT_L(0); MMA(0, 1, At, B1); BAR;
;     LDA(At, 1, 1); BAR; WAIT_L(0); MMA(1, 0, At, B0); MMA(1, 1, At, B1); BAR; }
;   if (wr == 0) BAR;
	s_waitcnt lgkmcnt(0)
	s_setprio 1
	s_waitcnt lgkmcnt(0)
	v_mfma_f32_16x16x32_bf16 v[82:85], v[162:165], v[66:69], v[126:129]
	v_mfma_f32_16x16x32_bf16 v[122:125], v[166:169], v[74:77], v[82:85]
	v_mfma_f32_16x16x32_bf16 v[82:85], v[170:173], v[66:69], v[130:133]
	v_mfma_f32_16x16x32_bf16 v[126:129], v[174:177], v[74:77], v[82:85]
	v_mfma_f32_16x16x32_bf16 v[82:85], v[162:165], v[78:81], v[118:121]
	v_mfma_f32_16x16x32_bf16 v[114:117], v[166:169], v[184:187], v[82:85]
	v_mfma_f32_16x16x32_bf16 v[82:85], v[170:173], v[78:81], v[158:161]
	v_mfma_f32_16x16x32_bf16 v[118:121], v[174:177], v[184:187], v[82:85]
	v_mfma_f32_16x16x32_bf16 v[82:85], v[162:165], v[188:191], v[110:113]
	v_mfma_f32_16x16x32_bf16 v[106:109], v[166:169], v[192:195], v[82:85]
	v_mfma_f32_16x16x32_bf16 v[82:85], v[170:173], v[188:191], v[196:199]
	v_mfma_f32_16x16x32_bf16 v[110:113], v[174:177], v[192:195], v[82:85]
	v_mfma_f32_16x16x32_bf16 v[82:85], v[162:165], v[200:203], v[102:105]
	v_mfma_f32_16x16x32_bf16 v[90:93], v[166:169], v[222:225], v[82:85]
	v_mfma_f32_16x16x32_bf16 v[82:85], v[170:173], v[200:203], v[98:101]
	v_mfma_f32_16x16x32_bf16 v[94:97], v[174:177], v[222:225], v[82:85]
	s_setprio 0
	s_barrier
	ds_read_b128 v[130:133], v144 offset:49152
	ds_read_b128 v[158:161], v144 offset:50176
	ds_read_b128 v[196:199], v144 offset:51200
	ds_read_b128 v[226:229], v144 offset:52224
	s_waitcnt vmcnt(0)
	s_barrier
	s_waitcnt lgkmcnt(0)
	s_setprio 1
	s_waitcnt lgkmcnt(0)
	v_mfma_f32_16x16x32_bf16 v[82:85], v[130:133], v[66:69], v[218:221]
	v_mfma_f32_16x16x32_bf16 v[66:69], v[196:199], v[66:69], v[154:157]
	v_mfma_f32_16x16x32_bf16 v[102:105], v[226:229], v[74:77], v[66:69]
	v_mfma_f32_16x16x32_bf16 v[66:69], v[130:133], v[78:81], v[86:89]
	v_mfma_f32_16x16x32_bf16 v[98:101], v[158:161], v[74:77], v[82:85]
	v_mfma_f32_16x16x32_bf16 v[82:85], v[158:161], v[184:187], v[66:69]
	v_mfma_f32_16x16x32_bf16 v[66:69], v[196:199], v[78:81], v[70:73]
	v_mfma_f32_16x16x32_bf16 v[62:65], v[130:133], v[188:191], v[62:65]
	v_mfma_f32_16x16x32_bf16 v[58:61], v[196:199], v[188:191], v[58:61]
	v_mfma_f32_16x16x32_bf16 v[54:57], v[130:133], v[200:203], v[54:57]
	v_mfma_f32_16x16x32_bf16 v[50:53], v[196:199], v[200:203], v[50:53]
	v_mfma_f32_16x16x32_bf16 v[86:89], v[226:229], v[184:187], v[66:69]
	v_mfma_f32_16x16x32_bf16 v[74:77], v[158:161], v[192:195], v[62:65]
	v_mfma_f32_16x16x32_bf16 v[78:81], v[226:229], v[192:195], v[58:61]
	v_mfma_f32_16x16x32_bf16 v[66:69], v[158:161], v[222:225], v[54:57]
	v_mfma_f32_16x16x32_bf16 v[70:73], v[226:229], v[222:225], v[50:53]
	s_setprio 0
	s_barrier
	ds_read_b128 v[154:157], v0 offset:49152
	ds_read_b128 v[184:187], v0 offset:50176
	ds_read_b128 v[188:191], v0 offset:51200
	ds_read_b128 v[192:195], v0 offset:52224
	ds_read_b128 v[200:203], v0 offset:53248
	ds_read_b128 v[218:221], v0 offset:54272
	ds_read_b128 v[222:225], v0 offset:55296
	ds_read_b128 v[230:233], v0 offset:56320
	s_barrier
	s_waitcnt lgkmcnt(0)
	s_setprio 1
	s_waitcnt lgkmcnt(0)
	v_mfma_f32_16x16x32_bf16 v[46:49], v[162:165], v[154:157], v[46:49]
	v_mfma_f32_16x16x32_bf16 v[42:45], v[170:173], v[154:157], v[42:45]
	v_mfma_f32_16x16x32_bf16 v[38:41], v[162:165], v[188:191], v[38:41]
	v_mfma_f32_16x16x32_bf16 v[34:37], v[170:173], v[188:191], v[34:37]
	v_mfma_f32_16x16x32_bf16 v[30:33], v[162:165], v[200:203], v[30:33]
	v_mfma_f32_16x16x32_bf16 v[26:29], v[170:173], v[200:203], v[26:29]
	v_mfma_f32_16x16x32_bf16 v[22:25], v[162:165], v[222:225], v[22:25]
	v_mfma_f32_16x16x32_bf16 v[18:21], v[170:173], v[222:225], v[18:21]
	v_mfma_f32_16x16x32_bf16 v[58:61], v[166:169], v[184:187], v[46:49]
	v_mfma_f32_16x16x32_bf16 v[62:65], v[174:177], v[184:187], v[42:45]
	v_mfma_f32_16x16x32_bf16 v[50:53], v[166:169], v[192:195], v[38:41]
	v_mfma_f32_16x16x32_bf16 v[54:57], v[174:177], v[192:195], v[34:37]
	v_mfma_f32_16x16x32_bf16 v[42:45], v[166:169], v[218:221], v[30:33]
	v_mfma_f32_16x16x32_bf16 v[46:49], v[174:177], v[218:221], v[26:29]
	v_mfma_f32_16x16x32_bf16 v[34:37], v[166:169], v[230:233], v[22:25]
	v_mfma_f32_16x16x32_bf16 v[38:41], v[174:177], v[230:233], v[18:21]
	s_setprio 0
	s_setprio 1
	v_mfma_f32_16x16x32_bf16 v[2:5], v[196:199], v[188:191], v[2:5]
	v_mfma_f32_16x16x32_bf16 v[10:13], v[196:199], v[154:157], v[10:13]
	v_mfma_f32_16x16x32_bf16 v[22:25], v[226:229], v[192:195], v[2:5]
	v_mfma_f32_16x16x32_bf16 v[2:5], v[130:133], v[200:203], v[134:137]
	v_mfma_f32_16x16x32_bf16 v[14:17], v[130:133], v[154:157], v[14:17]
	v_mfma_f32_16x16x32_bf16 v[30:33], v[226:229], v[184:187], v[10:13]
	v_mfma_f32_16x16x32_bf16 v[6:9], v[130:133], v[188:191], v[6:9]
	v_mfma_f32_16x16x32_bf16 v[10:13], v[158:161], v[218:221], v[2:5]
	v_mfma_f32_16x16x32_bf16 v[2:5], v[196:199], v[200:203], v[138:141]
	v_mfma_f32_16x16x32_bf16 v[26:29], v[158:161], v[184:187], v[14:17]
	v_mfma_f32_16x16x32_bf16 v[18:21], v[158:161], v[192:195], v[6:9]
	v_mfma_f32_16x16x32_bf16 v[14:17], v[226:229], v[218:221], v[2:5]
	v_mfma_f32_16x16x32_bf16 v[2:5], v[130:133], v[222:225], v[146:149]
	v_mfma_f32_16x16x32_bf16 v[6:9], v[196:199], v[222:225], v[150:153]
	v_mfma_f32_16x16x32_bf16 v[2:5], v[158:161], v[230:233], v[2:5]
	v_mfma_f32_16x16x32_bf16 v[6:9], v[226:229], v[230:233], v[6:9]
	s_setprio 0
	s_barrier
	s_cbranch_scc1 .LBB0_763
	s_barrier
	s_branch .LBB0_763

; #define STAGE(P, BASE, LD, br, kt) do { const bf16* _gb = BASE + ((long)(br) * (LD) + (long)(kt) * BK); \
;     _Pragma("unroll") for (int _i = 0; _i < 2; ++_i) { \
;       __builtin_amdgcn_global_load_lds((const unsigned*)(_gb + ((&LD == &lda) ? offA[_i] : offB[_i])), \
;         (unsigned*)((char*)(P) + tidx_ * 16 + _i * 8192), 16, 0, 0); } } while (0)
; #define LDA(dst, b, h) _Pragma("unroll") for (int m = 0; m < 4; ++m) _Pragma("unroll") for (int k = 0; k < 2; ++k) \
;     dst[m][k] = *reinterpret_cast<const bf16x8*>(smem + (((b) * 2 + (h)) * 16384 + m * 2048 + k * 1024) + aoff)
; #define LDB(dst, b, h) _Pragma("unroll") for (int n = 0; n < 2; ++n) _Pragma("unroll") for (int k = 0; k < 2; ++k) \
;     dst[n][k] = *reinterpret_cast<const bf16x8*>(smem + (((b) * 2 + (h)) * 16384 + n * 2048 + k * 1024) + boff)
; #define MMA(ai, bj, At_, Bt_) do { __builtin_amdgcn_s_setprio(1); \
;     _Pragma("unroll") for (int m = 0; m < 4; ++m) _Pragma("unroll") for (int n = 0; n < 2; ++n) _Pragma("unroll") for (int k = 0; k < 2; ++k) \
;       acc[ai][bj][m][n] = __builtin_amdgcn_mfma_f32_16x16x32_bf16(Bt_[n][k], At_[m][k], acc[ai][bj][m][n], 0, 0, 0); \
;     __builtin_amdgcn_s_setprio(0); } while (0)
; #define WAIT_L(n) asm volatile("s_waitcnt lgkmcnt(" #n ")" ::: "memory")
; #define BAR __builtin_amdgcn_s_barrier()
; #define SCHED __builtin_amdgcn_sched_barrier(0)
; template <class Epi, int NB>
; DEV void gemm_tile_nb(const bf16* __restrict__ A, int lda, long strideA, const bf16* __restrict__ Bt, int ldb, long strideB, int K, int brow, int bcol, Epi& epi) {
;     ...
;     LDB(B0, 0, 0); SCHED; LDA(At, 0, 0); STAGE(SA(1, 1), A, lda, brow + HALF, t + 1);
;     WAIT_L(8); BAR; WAIT_L(0); MMA(0, 0, At, B0); BAR; SCHED;
;     LDB(B1, 0, 1); STAGE(SB(0, 0), Bt, ldb, bcol, t + 2);
;     BAR; WAIT_L(0); MMA(0, 1, At, B1); BAR;
;     LDA(At, 0, 1); STAGE(SA(0, 0), A, lda, brow, t + 2);
;     BAR; WAIT_L(0); MMA(1, 0, At, B0); BAR; SCHED;
.LBB0_784:
	v_add_u32_e32 v159, 0xc000, v146
	v_lshl_add_u64 v[204:205], s[88:89], 0, v[138:139]
	v_readfirstlane_b32 s40, v159
	v_lshl_add_u64 v[160:161], v[204:205], 0, s[42:43]
	v_lshl_add_u64 v[208:209], s[88:89], 0, v[140:141]
	v_lshl_add_u64 v[214:215], v[208:209], 0, s[42:43]
	s_mov_b32 m0, s40
	ds_read_b128 v[184:187], v0
	ds_read_b128 v[188:191], v0 offset:1024
	ds_read_b128 v[192:195], v0 offset:2048
	ds_read_b128 v[196:199], v0 offset:3072
	ds_read_b128 v[200:203], v0 offset:4096
	ds_read_b128 v[218:221], v0 offset:5120
	ds_read_b128 v[222:225], v0 offset:6144
	ds_read_b128 v[226:229], v0 offset:7168
	global_load_lds_dwordx4 v[160:161], off
	s_add_i32 m0, m0, 0x2000
	v_add_u32_e32 v160, 0xe000, v146
	global_load_lds_dwordx4 v[214:215], off
	s_waitcnt lgkmcnt(8)
	s_barrier
	s_waitcnt lgkmcnt(0)
	s_setprio 1
	s_waitcnt lgkmcnt(0)
	v_mfma_f32_16x16x32_bf16 v[126:129], v[162:165], v[184:187], v[126:129]
	v_mfma_f32_16x16x32_bf16 v[122:125], v[170:173], v[184:187], v[122:125]
	v_mfma_f32_16x16x32_bf16 v[118:121], v[162:165], v[192:195], v[118:121]
	v_mfma_f32_16x16x32_bf16 v[114:117], v[170:173], v[192:195], v[114:117]
	v_mfma_f32_16x16x32_bf16 v[110:113], v[162:165], v[200:203], v[110:113]
	v_mfma_f32_16x16x32_bf16 v[106:109], v[170:173], v[200:203], v[106:109]
	v_mfma_f32_16x16x32_bf16 v[102:105], v[162:165], v[222:225], v[102:105]
	v_mfma_f32_16x16x32_bf16 v[98:101], v[170:173], v[222:225], v[98:101]
	v_mfma_f32_16x16x32_bf16 v[126:129], v[166:169], v[188:191], v[126:129]
	v_mfma_f32_16x16x32_bf16 v[122:125], v[174:177], v[188:191], v[122:125]
	v_mfma_f32_16x16x32_bf16 v[118:121], v[166:169], v[196:199], v[118:121]
	v_mfma_f32_16x16x32_bf16 v[114:117], v[174:177], v[196:199], v[114:117]
	v_mfma_f32_16x16x32_bf16 v[110:113], v[166:169], v[218:221], v[110:113]
	v_mfma_f32_16x16x32_bf16 v[106:109], v[174:177], v[218:221], v[106:109]
	v_mfma_f32_16x16x32_bf16 v[102:105], v[166:169], v[226:229], v[102:105]
	v_mfma_f32_16x16x32_bf16 v[98:101], v[174:177], v[226:229], v[98:101]
	s_setprio 0
	s_barrier
	v_lshl_add_u64 v[214:215], s[88:89], 0, v[134:135]
	v_readfirstlane_b32 s40, v145
	v_lshl_add_u64 v[246:247], v[214:215], 0, s[52:53]
	s_mov_b32 m0, s40
	ds_read_b128 v[230:233], v144 offset:16384
	ds_read_b128 v[234:237], v144 offset:17408
	ds_read_b128 v[238:241], v144 offset:18432
	ds_read_b128 v[242:245], v144 offset:19456
	global_load_lds_dwordx4 v[246:247], off
	v_lshl_add_u64 v[246:247], s[88:89], 0, v[136:137]
	v_readfirstlane_b32 s40, v148
	v_lshl_add_u64 v[248:249], v[246:247], 0, s[52:53]
	s_mov_b32 m0, s40
	s_nop 0
	global_load_lds_dwordx4 v[248:249], off
	s_barrier
	s_waitcnt lgkmcnt(0)
	s_setprio 1
	s_waitcnt lgkmcnt(0)
	v_mfma_f32_16x16x32_bf16 v[94:97], v[230:233], v[184:187], v[94:97]
	v_mfma_f32_16x16x32_bf16 v[90:93], v[238:241], v[184:187], v[90:93]
	v_mfma_f32_16x16x32_bf16 v[86:89], v[230:233], v[192:195], v[86:89]
	v_mfma_f32_16x16x32_bf16 v[70:73], v[238:241], v[192:195], v[70:73]
	v_mfma_f32_16x16x32_bf16 v[62:65], v[230:233], v[200:203], v[62:65]
	v_mfma_f32_16x16x32_bf16 v[58:61], v[238:241], v[200:203], v[58:61]
	v_mfma_f32_16x16x32_bf16 v[54:57], v[230:233], v[222:225], v[54:57]
	v_mfma_f32_16x16x32_bf16 v[50:53], v[238:241], v[222:225], v[50:53]
	v_mfma_f32_16x16x32_bf16 v[94:97], v[234:237], v[188:191], v[94:97]
	v_mfma_f32_16x16x32_bf16 v[90:93], v[242:245], v[188:191], v[90:93]
	v_mfma_f32_16x16x32_bf16 v[86:89], v[234:237], v[196:199], v[86:89]
	v_mfma_f32_16x16x32_bf16 v[70:73], v[242:245], v[196:199], v[70:73]
	v_mfma_f32_16x16x32_bf16 v[62:65], v[234:237], v[218:221], v[62:65]
	v_mfma_f32_16x16x32_bf16 v[58:61], v[242:245], v[218:221], v[58:61]
	v_mfma_f32_16x16x32_bf16 v[54:57], v[234:237], v[226:229], v[54:57]
	v_mfma_f32_16x16x32_bf16 v[50:53], v[242:245], v[226:229], v[50:53]
	s_setprio 0
	v_readfirstlane_b32 s40, v146
	v_lshl_add_u64 v[248:249], v[204:205], 0, s[28:29]
	s_mov_b32 m0, s40
	v_readfirstlane_b32 s40, v150
	s_barrier
	ds_read_b128 v[184:187], v0 offset:16384
	ds_read_b128 v[188:191], v0 offset:17408
	ds_read_b128 v[192:195], v0 offset:18432
	ds_read_b128 v[196:199], v0 offset:19456
	ds_read_b128 v[200:203], v0 offset:20480
	ds_read_b128 v[218:221], v0 offset:21504
	ds_read_b128 v[222:225], v0 offset:22528
	ds_read_b128 v[226:229], v0 offset:23552
	global_load_lds_dwordx4 v[248:249], off
	v_lshl_add_u64 v[248:249], v[208:209], 0, s[28:29]
	s_mov_b32 m0, s40
	s_nop 0
	global_load_lds_dwordx4 v[248:249], off
	s_waitcnt vmcnt(10)
	s_barrier
	s_waitcnt lgkmcnt(0)
	s_setprio 1
	s_waitcnt lgkmcnt(0)
	v_mfma_f32_16x16x32_bf16 v[46:49], v[162:165], v[184:187], v[46:49]
	v_mfma_f32_16x16x32_bf16 v[42:45], v[170:173], v[184:187], v[42:45]
	v_mfma_f32_16x16x32_bf16 v[38:41], v[162:165], v[192:195], v[38:41]
	v_mfma_f32_16x16x32_bf16 v[34:37], v[170:173], v[192:195], v[34:37]
	v_mfma_f32_16x16x32_bf16 v[30:33], v[162:165], v[200:203], v[30:33]
	v_mfma_f32_16x16x32_bf16 v[26:29], v[170:173], v[200:203], v[26:29]
	v_mfma_f32_16x16x32_bf16 v[22:25], v[162:165], v[222:225], v[22:25]
	v_mfma_f32_16x16x32_bf16 v[18:21], v[170:173], v[222:225], v[18:21]
	v_mfma_f32_16x16x32_bf16 v[46:49], v[166:169], v[188:191], v[46:49]
	v_mfma_f32_16x16x32_bf16 v[42:45], v[174:177], v[188:191], v[42:45]
	v_mfma_f32_16x16x32_bf16 v[38:41], v[166:169], v[196:199], v[38:41]
	v_mfma_f32_16x16x32_bf16 v[34:37], v[174:177], v[196:199], v[34:37]
	v_mfma_f32_16x16x32_bf16 v[30:33], v[166:169], v[218:221], v[30:33]
	v_mfma_f32_16x16x32_bf16 v[26:29], v[174:177], v[218:221], v[26:29]
	v_mfma_f32_16x16x32_bf16 v[22:25], v[166:169], v[226:229], v[22:25]
	v_mfma_f32_16x16x32_bf16 v[18:21], v[174:177], v[226:229], v[18:21]
	s_setprio 0
	s_barrier
; #define STAGE(P, BASE, LD, br, kt) do { const bf16* _gb = BASE + ((long)(br) * (LD) + (long)(kt) * BK); \
;     _Pragma("unroll") for (int _i = 0; _i < 2; ++_i) { \
;       __builtin_amdgcn_global_load_lds((const unsigned*)(_gb + ((&LD == &lda) ? offA[_i] : offB[_i])), \
;         (unsigned*)((char*)(P) + tidx_ * 16 + _i * 8192), 16, 0, 0); } } while (0)
; #define LDA(dst, b, h) _Pragma("unroll") for (int m = 0; m < 4; ++m) _Pragma("unroll") for (int k = 0; k < 2; ++k) \
;     dst[m][k] = *reinterpret_cast<const bf16x8*>(smem + (((b) * 2 + (h)) * 16384 + m * 2048 + k * 1024) + aoff)
; #define LDB(dst, b, h) _Pragma("unroll") for (int n = 0; n < 2; ++n) _Pragma("unroll") for (int k = 0; k < 2; ++k) \
;     dst[n][k] = *reinterpret_cast<const bf16x8*>(smem + (((b) * 2 + (h)) * 16384 + n * 2048 + k * 1024) + boff)
; #define MMA(ai, bj, At_, Bt_) do { __builtin_amdgcn_s_setprio(1); \
;     _Pragma("unroll") for (int m = 0; m < 4; ++m) _Pragma("unroll") for (int n = 0; n < 2; ++n) _Pragma("unroll") for (int k = 0; k < 2; ++k) \
;       acc[ai][bj][m][n] = __builtin_amdgcn_mfma_f32_16x16x32_bf16(Bt_[n][k], At_[m][k], acc[ai][bj][m][n], 0, 0, 0); \
;     __builtin_amdgcn_s_setprio(0); } while (0)
; #define WAIT_V(n) asm volatile("s_waitcnt vmcnt(" #n ")" ::: "memory")
; #define WAIT_L(n) asm volatile("s_waitcnt lgkmcnt(" #n ")" ::: "memory")
; #define BAR __builtin_amdgcn_s_barrier()
; #define SCHED __builtin_amdgcn_sched_barrier(0)
; template <class Epi, int NB>
; DEV void gemm_tile_nb(const bf16* __restrict__ A, int lda, long strideA, const bf16* __restrict__ Bt, int ldb, long strideB, int K, int brow, int bcol, Epi& epi) {
;     ...
;     STAGE(SB(0, 1), Bt, ldb, bcol + HALF, t + 2);
;     WAIT_V(6); BAR; MMA(1, 1, At, B1); BAR;
;     LDB(B0, 1, 0); SCHED; LDA(At, 1, 0); STAGE(SA(0, 1), A, lda, brow + HALF, t + 2);
;     WAIT_L(8); BAR; WAIT_L(0); MMA(0, 0, At, B0); BAR; SCHED;
;     LDB(B1, 1, 1); STAGE(SB(1, 0), Bt, ldb, bcol, t + 3);
;     BAR; WAIT_L(0); MMA(0, 1, At, B1); BAR;
	v_readfirstlane_b32 s40, v147
	v_lshl_add_u64 v[162:163], v[214:215], 0, s[54:55]
	s_mov_b32 m0, s40
	v_readfirstlane_b32 s40, v151
	global_load_lds_dwordx4 v[162:163], off
	v_lshl_add_u64 v[162:163], v[246:247], 0, s[54:55]
	s_mov_b32 m0, s40
	s_nop 0
	global_load_lds_dwordx4 v[162:163], off
	ds_read_b128 v[162:165], v144 offset:32768
	ds_read_b128 v[166:169], v144 offset:33792
	ds_read_b128 v[170:173], v144 offset:34816
	ds_read_b128 v[174:177], v144 offset:35840
	s_waitcnt vmcnt(6)
	s_barrier
	s_setprio 1
	v_mfma_f32_16x16x32_bf16 v[14:17], v[230:233], v[184:187], v[14:17]
	v_mfma_f32_16x16x32_bf16 v[10:13], v[238:241], v[184:187], v[10:13]
	v_mfma_f32_16x16x32_bf16 v[6:9], v[230:233], v[192:195], v[6:9]
	v_mfma_f32_16x16x32_bf16 v[2:5], v[238:241], v[192:195], v[2:5]
	v_mfma_f32_16x16x32_bf16 v[66:69], v[230:233], v[200:203], v[66:69]
	v_mfma_f32_16x16x32_bf16 v[74:77], v[238:241], v[200:203], v[74:77]
	v_mfma_f32_16x16x32_bf16 v[78:81], v[230:233], v[222:225], v[78:81]
	v_mfma_f32_16x16x32_bf16 v[82:85], v[238:241], v[222:225], v[82:85]
	v_mfma_f32_16x16x32_bf16 v[14:17], v[234:237], v[188:191], v[14:17]
	v_mfma_f32_16x16x32_bf16 v[10:13], v[242:245], v[188:191], v[10:13]
	v_mfma_f32_16x16x32_bf16 v[6:9], v[234:237], v[196:199], v[6:9]
	v_mfma_f32_16x16x32_bf16 v[2:5], v[242:245], v[196:199], v[2:5]
	v_mfma_f32_16x16x32_bf16 v[66:69], v[234:237], v[218:221], v[66:69]
	v_mfma_f32_16x16x32_bf16 v[74:77], v[242:245], v[218:221], v[74:77]
	v_mfma_f32_16x16x32_bf16 v[78:81], v[234:237], v[226:229], v[78:81]
	v_mfma_f32_16x16x32_bf16 v[82:85], v[242:245], v[226:229], v[82:85]
	s_setprio 0
	s_barrier
	v_readfirstlane_b32 s40, v149
	v_lshl_add_u64 v[230:231], v[204:205], 0, s[56:57]
	s_mov_b32 m0, s40
	v_readfirstlane_b32 s40, v152
	ds_read_b128 v[184:187], v0 offset:32768
	ds_read_b128 v[188:191], v0 offset:33792
	ds_read_b128 v[192:195], v0 offset:34816
	ds_read_b128 v[196:199], v0 offset:35840
	ds_read_b128 v[200:203], v0 offset:36864
	ds_read_b128 v[218:221], v0 offset:37888
	ds_read_b128 v[222:225], v0 offset:38912
	ds_read_b128 v[226:229], v0 offset:39936
	global_load_lds_dwordx4 v[230:231], off
	v_lshl_add_u64 v[230:231], v[208:209], 0, s[56:57]
	s_mov_b32 m0, s40
	s_nop 0
	global_load_lds_dwordx4 v[230:231], off
	s_waitcnt lgkmcnt(8)
	s_barrier
	s_waitcnt lgkmcnt(0)
	s_setprio 1
	s_waitcnt lgkmcnt(0)
	v_mfma_f32_16x16x32_bf16 v[126:129], v[162:165], v[184:187], v[126:129]
	v_mfma_f32_16x16x32_bf16 v[122:125], v[170:173], v[184:187], v[122:125]
	v_mfma_f32_16x16x32_bf16 v[118:121], v[162:165], v[192:195], v[118:121]
	v_mfma_f32_16x16x32_bf16 v[114:117], v[170:173], v[192:195], v[114:117]
	v_mfma_f32_16x16x32_bf16 v[110:113], v[162:165], v[200:203], v[110:113]
	v_mfma_f32_16x16x32_bf16 v[106:109], v[170:173], v[200:203], v[106:109]
	v_mfma_f32_16x16x32_bf16 v[102:105], v[162:165], v[222:225], v[102:105]
	v_mfma_f32_16x16x32_bf16 v[98:101], v[170:173], v[222:225], v[98:101]
	v_mfma_f32_16x16x32_bf16 v[126:129], v[166:169], v[188:191], v[126:129]
	v_mfma_f32_16x16x32_bf16 v[122:125], v[174:177], v[188:191], v[122:125]
	v_mfma_f32_16x16x32_bf16 v[118:121], v[166:169], v[196:199], v[118:121]
	v_mfma_f32_16x16x32_bf16 v[114:117], v[174:177], v[196:199], v[114:117]
	v_mfma_f32_16x16x32_bf16 v[110:113], v[166:169], v[218:221], v[110:113]
	v_mfma_f32_16x16x32_bf16 v[106:109], v[174:177], v[218:221], v[106:109]
	v_mfma_f32_16x16x32_bf16 v[102:105], v[166:169], v[226:229], v[102:105]
	v_mfma_f32_16x16x32_bf16 v[98:101], v[174:177], v[226:229], v[98:101]
	s_setprio 0
	s_barrier
	v_readfirstlane_b32 s40, v153
	v_lshl_add_u64 v[248:249], v[214:215], 0, s[58:59]
	s_mov_b32 m0, s40
	v_readfirstlane_b32 s40, v154
	ds_read_b128 v[230:233], v144 offset:49152
	ds_read_b128 v[234:237], v144 offset:50176
	ds_read_b128 v[238:241], v144 offset:51200
	ds_read_b128 v[242:245], v144 offset:52224
	global_load_lds_dwordx4 v[248:249], off
	v_lshl_add_u64 v[248:249], v[246:247], 0, s[58:59]
	s_mov_b32 m0, s40
	s_nop 0
	global_load_lds_dwordx4 v[248:249], off
	s_barrier
	s_waitcnt lgkmcnt(0)
	s_setprio 1
	s_waitcnt lgkmcnt(0)
	v_mfma_f32_16x16x32_bf16 v[94:97], v[230:233], v[184:187], v[94:97]
	v_mfma_f32_16x16x32_bf16 v[90:93], v[238:241], v[184:187], v[90:93]
	v_mfma_f32_16x16x32_bf16 v[86:89], v[230:233], v[192:195], v[86:89]
	v_mfma_f32_16x16x32_bf16 v[70:73], v[238:241], v[192:195], v[70:73]
	v_mfma_f32_16x16x32_bf16 v[62:65], v[230:233], v[200:203], v[62:65]
	v_mfma_f32_16x16x32_bf16 v[58:61], v[238:241], v[200:203], v[58:61]
	v_mfma_f32_16x16x32_bf16 v[54:57], v[230:233], v[222:225], v[54:57]
	v_mfma_f32_16x16x32_bf16 v[50:53], v[238:241], v[222:225], v[50:53]
	v_mfma_f32_16x16x32_bf16 v[94:97], v[234:237], v[188:191], v[94:97]
	v_mfma_f32_16x16x32_bf16 v[90:93], v[242:245], v[188:191], v[90:93]
	v_mfma_f32_16x16x32_bf16 v[86:89], v[234:237], v[196:199], v[86:89]
	v_mfma_f32_16x16x32_bf16 v[70:73], v[242:245], v[196:199], v[70:73]
	v_mfma_f32_16x16x32_bf16 v[62:65], v[234:237], v[218:221], v[62:65]
	v_mfma_f32_16x16x32_bf16 v[58:61], v[242:245], v[218:221], v[58:61]
	v_mfma_f32_16x16x32_bf16 v[54:57], v[234:237], v[226:229], v[54:57]
	v_mfma_f32_16x16x32_bf16 v[50:53], v[242:245], v[226:229], v[50:53]
	s_setprio 0
	v_readfirstlane_b32 s40, v155
	v_lshl_add_u64 v[204:205], v[204:205], 0, s[20:21]
	s_mov_b32 m0, s40
	v_readfirstlane_b32 s40, v156
	s_barrier
	ds_read_b128 v[184:187], v0 offset:49152
	ds_read_b128 v[188:191], v0 offset:50176
	ds_read_b128 v[192:195], v0 offset:51200
	ds_read_b128 v[196:199], v0 offset:52224
	ds_read_b128 v[200:203], v0 offset:53248
	ds_read_b128 v[218:221], v0 offset:54272
	ds_read_b128 v[222:225], v0 offset:55296
	ds_read_b128 v[226:229], v0 offset:56320
	global_load_lds_dwordx4 v[204:205], off
	v_lshl_add_u64 v[204:205], v[208:209], 0, s[20:21]
	s_mov_b32 m0, s40
	s_nop 0
	global_load_lds_dwordx4 v[204:205], off
	s_waitcnt vmcnt(10)
	s_barrier
; #define STAGE(P, BASE, LD, br, kt) do { const bf16* _gb = BASE + ((long)(br) * (LD) + (long)(kt) * BK); \
;     _Pragma("unroll") for (int _i = 0; _i < 2; ++_i) { \
;       __builtin_amdgcn_global_load_lds((const unsigned*)(_gb + ((&LD == &lda) ? offA[_i] : offB[_i])), \
;         (unsigned*)((char*)(P) + tidx_ * 16 + _i * 8192), 16, 0, 0); } } while (0)
; #define LDA(dst, b, h) _Pragma("unroll") for (int m = 0; m < 4; ++m) _Pragma("unroll") for (int k = 0; k < 2; ++k) \
;     dst[m][k] = *reinterpret_cast<const bf16x8*>(smem + (((b) * 2 + (h)) * 16384 + m * 2048 + k * 1024) + aoff)
; #define LDB(dst, b, h) _Pragma("unroll") for (int n = 0; n < 2; ++n) _Pragma("unroll") for (int k = 0; k < 2; ++k) \
;     dst[n][k] = *reinterpret_cast<const bf16x8*>(smem + (((b) * 2 + (h)) * 16384 + n * 2048 + k * 1024) + boff)
; #define MMA(ai, bj, At_, Bt_) do { __builtin_amdgcn_s_setprio(1); \
;     _Pragma("unroll") for (int m = 0; m < 4; ++m) _Pragma("unroll") for (int n = 0; n < 2; ++n) _Pragma("unroll") for (int k = 0; k < 2; ++k) \
;       acc[ai][bj][m][n] = __builtin_amdgcn_mfma_f32_16x16x32_bf16(Bt_[n][k], At_[m][k], acc[ai][bj][m][n], 0, 0, 0); \
;     __builtin_amdgcn_s_setprio(0); } while (0)
; #define WAIT_V(n) asm volatile("s_waitcnt vmcnt(" #n ")" ::: "memory")
; #define WAIT_L(n) asm volatile("s_waitcnt lgkmcnt(" #n ")" ::: "memory")
; #define BAR __builtin_amdgcn_s_barrier()
; #define SCHED __builtin_amdgcn_sched_barrier(0)
; template <class Epi, int NB>
; DEV void gemm_tile_nb(const bf16* __restrict__ A, int lda, long strideA, const bf16* __restrict__ Bt, int ldb, long strideB, int K, int brow, int bcol, Epi& epi) {
;     ...
;     LDA(At, 1, 1); STAGE(SA(1, 0), A, lda, brow, t + 3);
;     BAR; WAIT_L(0); MMA(1, 0, At, B0); BAR; SCHED;
;     STAGE(SB(1, 1), Bt, ldb, bcol + HALF, t + 3);
;     WAIT_V(6); BAR; MMA(1, 1, At, B1); BAR;
;   }
;   { LDB(B0, 0, 0); LDA(At, 0, 0); STAGE(SA(1, 1), A, lda, brow + HALF, nt - 1);
;     BAR; WAIT_L(0); MMA(0, 0, At, B0); BAR;
	s_waitcnt lgkmcnt(0)
	s_setprio 1
	s_waitcnt lgkmcnt(0)
	v_mfma_f32_16x16x32_bf16 v[46:49], v[162:165], v[184:187], v[46:49]
	v_mfma_f32_16x16x32_bf16 v[42:45], v[170:173], v[184:187], v[42:45]
	v_mfma_f32_16x16x32_bf16 v[38:41], v[162:165], v[192:195], v[38:41]
	v_mfma_f32_16x16x32_bf16 v[34:37], v[170:173], v[192:195], v[34:37]
	v_mfma_f32_16x16x32_bf16 v[30:33], v[162:165], v[200:203], v[30:33]
	v_mfma_f32_16x16x32_bf16 v[26:29], v[170:173], v[200:203], v[26:29]
	v_mfma_f32_16x16x32_bf16 v[22:25], v[162:165], v[222:225], v[22:25]
	v_mfma_f32_16x16x32_bf16 v[18:21], v[170:173], v[222:225], v[18:21]
	v_mfma_f32_16x16x32_bf16 v[46:49], v[166:169], v[188:191], v[46:49]
	v_mfma_f32_16x16x32_bf16 v[42:45], v[174:177], v[188:191], v[42:45]
	v_mfma_f32_16x16x32_bf16 v[38:41], v[166:169], v[196:199], v[38:41]
	v_mfma_f32_16x16x32_bf16 v[34:37], v[174:177], v[196:199], v[34:37]
	v_mfma_f32_16x16x32_bf16 v[30:33], v[166:169], v[218:221], v[30:33]
	v_mfma_f32_16x16x32_bf16 v[26:29], v[174:177], v[218:221], v[26:29]
	v_mfma_f32_16x16x32_bf16 v[22:25], v[166:169], v[226:229], v[22:25]
	v_mfma_f32_16x16x32_bf16 v[18:21], v[174:177], v[226:229], v[18:21]
	s_setprio 0
	s_barrier
	v_readfirstlane_b32 s40, v157
	v_lshl_add_u64 v[162:163], v[214:215], 0, s[60:61]
	s_mov_b32 m0, s40
	v_readfirstlane_b32 s40, v158
	global_load_lds_dwordx4 v[162:163], off
	v_lshl_add_u64 v[162:163], v[246:247], 0, s[60:61]
	s_mov_b32 m0, s40
	s_nop 0
	global_load_lds_dwordx4 v[162:163], off
	ds_read_b128 v[162:165], v144
	ds_read_b128 v[166:169], v144 offset:1024
	ds_read_b128 v[170:173], v144 offset:2048
	ds_read_b128 v[174:177], v144 offset:3072
	s_waitcnt vmcnt(6)
	s_barrier
	s_setprio 1
	v_mfma_f32_16x16x32_bf16 v[14:17], v[230:233], v[184:187], v[14:17]
	v_mfma_f32_16x16x32_bf16 v[10:13], v[238:241], v[184:187], v[10:13]
	v_mfma_f32_16x16x32_bf16 v[6:9], v[230:233], v[192:195], v[6:9]
	v_mfma_f32_16x16x32_bf16 v[2:5], v[238:241], v[192:195], v[2:5]
	v_mfma_f32_16x16x32_bf16 v[66:69], v[230:233], v[200:203], v[66:69]
	v_mfma_f32_16x16x32_bf16 v[74:77], v[238:241], v[200:203], v[74:77]
	v_mfma_f32_16x16x32_bf16 v[78:81], v[230:233], v[222:225], v[78:81]
	v_mfma_f32_16x16x32_bf16 v[82:85], v[238:241], v[222:225], v[82:85]
	v_mfma_f32_16x16x32_bf16 v[14:17], v[234:237], v[188:191], v[14:17]
	v_mfma_f32_16x16x32_bf16 v[10:13], v[242:245], v[188:191], v[10:13]
	v_mfma_f32_16x16x32_bf16 v[6:9], v[234:237], v[196:199], v[6:9]
	v_mfma_f32_16x16x32_bf16 v[2:5], v[242:245], v[196:199], v[2:5]
	v_mfma_f32_16x16x32_bf16 v[66:69], v[234:237], v[218:221], v[66:69]
	v_mfma_f32_16x16x32_bf16 v[74:77], v[242:245], v[218:221], v[74:77]
	v_mfma_f32_16x16x32_bf16 v[78:81], v[234:237], v[226:229], v[78:81]
	v_mfma_f32_16x16x32_bf16 v[82:85], v[242:245], v[226:229], v[82:85]
	s_setprio 0
	s_add_i32 s39, s39, 2
	v_lshl_add_u64 v[134:135], v[134:135], 0, s[72:73]
	v_lshl_add_u64 v[136:137], v[136:137], 0, s[72:73]
	v_lshl_add_u64 v[138:139], v[138:139], 0, s[72:73]
	s_cmp_lt_u32 s39, 12
	v_lshl_add_u64 v[140:141], v[140:141], 0, s[72:73]
	s_barrier
	s_cbranch_scc1 .LBB0_784
	s_mov_b64 s[40:41], 0x780
	v_readfirstlane_b32 s39, v159
	v_lshl_add_u64 v[132:133], v[132:133], 0, s[40:41]
	s_mov_b32 m0, s39
	v_readfirstlane_b32 s39, v160
	ds_read_b128 v[134:137], v144
	ds_read_b128 v[138:141], v144 offset:1024
	ds_read_b128 v[146:149], v144 offset:2048
	ds_read_b128 v[150:153], v144 offset:3072
	ds_read_b128 v[154:157], v0
	ds_read_b128 v[162:165], v0 offset:1024
	ds_read_b128 v[166:169], v0 offset:2048
	ds_read_b128 v[170:173], v0 offset:3072
	ds_read_b128 v[174:177], v0 offset:4096
	ds_read_b128 v[184:187], v0 offset:5120
	ds_read_b128 v[188:191], v0 offset:6144
	ds_read_b128 v[192:195], v0 offset:7168
	global_load_lds_dwordx4 v[132:133], off
	v_lshl_add_u64 v[130:131], v[130:131], 0, s[40:41]
	s_mov_b32 m0, s39
	s_cmpk_gt_u32 s50, 0xff
	global_load_lds_dwordx4 v[130:131], off
	s_barrier
	s_waitcnt lgkmcnt(0)
	s_setprio 1
	s_waitcnt lgkmcnt(0)
	v_mfma_f32_16x16x32_bf16 v[126:129], v[134:137], v[154:157], v[126:129]
	v_mfma_f32_16x16x32_bf16 v[118:121], v[134:137], v[166:169], v[118:121]
	v_mfma_f32_16x16x32_bf16 v[110:113], v[134:137], v[174:177], v[110:113]
	v_mfma_f32_16x16x32_bf16 v[102:105], v[134:137], v[188:191], v[102:105]
	v_mfma_f32_16x16x32_bf16 v[98:101], v[146:149], v[188:191], v[98:101]
	v_mfma_f32_16x16x32_bf16 v[126:129], v[138:141], v[162:165], v[126:129]
	v_mfma_f32_16x16x32_bf16 v[122:125], v[146:149], v[154:157], v[122:125]
	v_mfma_f32_16x16x32_bf16 v[118:121], v[138:141], v[170:173], v[118:121]
	v_mfma_f32_16x16x32_bf16 v[114:117], v[146:149], v[166:169], v[114:117]
	v_mfma_f32_16x16x32_bf16 v[110:113], v[138:141], v[184:187], v[110:113]
	v_mfma_f32_16x16x32_bf16 v[106:109], v[146:149], v[174:177], v[106:109]
	v_mfma_f32_16x16x32_bf16 v[102:105], v[138:141], v[192:195], v[102:105]
	v_mfma_f32_16x16x32_bf16 v[98:101], v[150:153], v[192:195], v[98:101]
	v_mfma_f32_16x16x32_bf16 v[130:133], v[150:153], v[162:165], v[122:125]
	v_mfma_f32_16x16x32_bf16 v[158:161], v[150:153], v[170:173], v[114:117]
	v_mfma_f32_16x16x32_bf16 v[196:199], v[150:153], v[184:187], v[106:109]
	s_setprio 0
	s_barrier
	s_nop 0
	ds_read_b128 v[106:109], v144 offset:16384
	ds_read_b128 v[114:117], v144 offset:17408
	ds_read_b128 v[122:125], v144 offset:18432
	ds_read_b128 v[200:203], v144 offset:19456
	s_barrier
; #define LDA(dst, b, h) _Pragma("unroll") for (int m = 0; m < 4; ++m) _Pragma("unroll") for (int k = 0; k < 2; ++k) \
;     dst[m][k] = *reinterpret_cast<const bf16x8*>(smem + (((b) * 2 + (h)) * 16384 + m * 2048 + k * 1024) + aoff)
; #define LDB(dst, b, h) _Pragma("unroll") for (int n = 0; n < 2; ++n) _Pragma("unroll") for (int k = 0; k < 2; ++k) \
;     dst[n][k] = *reinterpret_cast<const bf16x8*>(smem + (((b) * 2 + (h)) * 16384 + n * 2048 + k * 1024) + boff)
; #define MMA(ai, bj, At_, Bt_) do { __builtin_amdgcn_s_setprio(1); \
;     _Pragma("unroll") for (int m = 0; m < 4; ++m) _Pragma("unroll") for (int n = 0; n < 2; ++n) _Pragma("unroll") for (int k = 0; k < 2; ++k) \
;       acc[ai][bj][m][n] = __builtin_amdgcn_mfma_f32_16x16x32_bf16(Bt_[n][k], At_[m][k], acc[ai][bj][m][n], 0, 0, 0); \
;     __builtin_amdgcn_s_setprio(0); } while (0)
; #define WAIT_V(n) asm volatile("s_waitcnt vmcnt(" #n ")" ::: "memory")
; #define WAIT_L(n) asm volatile("s_waitcnt lgkmcnt(" #n ")" ::: "memory")
; #define BAR __builtin_amdgcn_s_barrier()
; template <class Epi, int NB>
; DEV void gemm_tile_nb(const bf16* __restrict__ A, int lda, long strideA, const bf16* __restrict__ Bt, int ldb, long strideB, int K, int brow, int bcol, Epi& epi) {
;     ...
;     BAR; WAIT_L(0); MMA(0, 0, At, B0); BAR;
;     LDB(B1, 0, 1); BAR; WAIT_L(0); MMA(0, 1, At, B1); BAR;
;     LDA(At, 0, 1); WAIT_V(4); BAR; WAIT_L(0); MMA(1, 0, At, B0); MMA(1, 1, At, B1); BAR; }
;   { LDB(B0, 1, 0); LDA(At, 1, 0); WAIT_V(2); BAR; WAIT_L(0); MMA(0, 0, At, B0); BAR;
	s_waitcnt lgkmcnt(0)
	s_setprio 1
	s_waitcnt lgkmcnt(0)
	v_mfma_f32_16x16x32_bf16 v[86:89], v[106:109], v[166:169], v[86:89]
	v_mfma_f32_16x16x32_bf16 v[70:73], v[122:125], v[166:169], v[70:73]
	v_mfma_f32_16x16x32_bf16 v[62:65], v[106:109], v[174:177], v[62:65]
	v_mfma_f32_16x16x32_bf16 v[58:61], v[122:125], v[174:177], v[58:61]
	v_mfma_f32_16x16x32_bf16 v[54:57], v[106:109], v[188:191], v[54:57]
	v_mfma_f32_16x16x32_bf16 v[50:53], v[122:125], v[188:191], v[50:53]
	v_mfma_f32_16x16x32_bf16 v[94:97], v[106:109], v[154:157], v[94:97]
	v_mfma_f32_16x16x32_bf16 v[90:93], v[122:125], v[154:157], v[90:93]
	v_mfma_f32_16x16x32_bf16 v[86:89], v[114:117], v[170:173], v[86:89]
	v_mfma_f32_16x16x32_bf16 v[70:73], v[200:203], v[170:173], v[70:73]
	v_mfma_f32_16x16x32_bf16 v[62:65], v[114:117], v[184:187], v[62:65]
	v_mfma_f32_16x16x32_bf16 v[58:61], v[200:203], v[184:187], v[58:61]
	v_mfma_f32_16x16x32_bf16 v[54:57], v[114:117], v[192:195], v[54:57]
	v_mfma_f32_16x16x32_bf16 v[50:53], v[200:203], v[192:195], v[50:53]
	v_mfma_f32_16x16x32_bf16 v[218:221], v[114:117], v[162:165], v[94:97]
	v_mfma_f32_16x16x32_bf16 v[154:157], v[200:203], v[162:165], v[90:93]
	s_setprio 0
	s_barrier
	s_nop 0
	ds_read_b128 v[90:93], v0 offset:16384
	ds_read_b128 v[94:97], v0 offset:17408
	ds_read_b128 v[162:165], v0 offset:18432
	ds_read_b128 v[166:169], v0 offset:19456
	ds_read_b128 v[170:173], v0 offset:20480
	ds_read_b128 v[174:177], v0 offset:21504
	ds_read_b128 v[184:187], v0 offset:22528
	ds_read_b128 v[188:191], v0 offset:23552
	s_waitcnt vmcnt(4)
	s_barrier
	s_waitcnt lgkmcnt(0)
	s_setprio 1
	s_waitcnt lgkmcnt(0)
	v_mfma_f32_16x16x32_bf16 v[46:49], v[134:137], v[90:93], v[46:49]
	v_mfma_f32_16x16x32_bf16 v[42:45], v[146:149], v[90:93], v[42:45]
	v_mfma_f32_16x16x32_bf16 v[38:41], v[134:137], v[162:165], v[38:41]
	v_mfma_f32_16x16x32_bf16 v[34:37], v[146:149], v[162:165], v[34:37]
	v_mfma_f32_16x16x32_bf16 v[30:33], v[134:137], v[170:173], v[30:33]
	v_mfma_f32_16x16x32_bf16 v[26:29], v[146:149], v[170:173], v[26:29]
	v_mfma_f32_16x16x32_bf16 v[22:25], v[134:137], v[184:187], v[22:25]
	v_mfma_f32_16x16x32_bf16 v[18:21], v[146:149], v[184:187], v[18:21]
	v_mfma_f32_16x16x32_bf16 v[46:49], v[138:141], v[94:97], v[46:49]
	v_mfma_f32_16x16x32_bf16 v[42:45], v[150:153], v[94:97], v[42:45]
	v_mfma_f32_16x16x32_bf16 v[38:41], v[138:141], v[166:169], v[38:41]
	v_mfma_f32_16x16x32_bf16 v[34:37], v[150:153], v[166:169], v[34:37]
	v_mfma_f32_16x16x32_bf16 v[30:33], v[138:141], v[174:177], v[30:33]
	v_mfma_f32_16x16x32_bf16 v[26:29], v[150:153], v[174:177], v[26:29]
	v_mfma_f32_16x16x32_bf16 v[22:25], v[138:141], v[188:191], v[22:25]
	v_mfma_f32_16x16x32_bf16 v[18:21], v[150:153], v[188:191], v[18:21]
	s_setprio 0
	s_setprio 1
	v_mfma_f32_16x16x32_bf16 v[66:69], v[106:109], v[170:173], v[66:69]
	v_mfma_f32_16x16x32_bf16 v[134:137], v[114:117], v[174:177], v[66:69]
	v_mfma_f32_16x16x32_bf16 v[66:69], v[122:125], v[170:173], v[74:77]
	v_mfma_f32_16x16x32_bf16 v[14:17], v[106:109], v[90:93], v[14:17]
	v_mfma_f32_16x16x32_bf16 v[10:13], v[122:125], v[90:93], v[10:13]
	v_mfma_f32_16x16x32_bf16 v[6:9], v[106:109], v[162:165], v[6:9]
	v_mfma_f32_16x16x32_bf16 v[2:5], v[122:125], v[162:165], v[2:5]
	v_mfma_f32_16x16x32_bf16 v[138:141], v[200:203], v[174:177], v[66:69]
	v_mfma_f32_16x16x32_bf16 v[66:69], v[106:109], v[184:187], v[78:81]
	v_mfma_f32_16x16x32_bf16 v[14:17], v[114:117], v[94:97], v[14:17]
	v_mfma_f32_16x16x32_bf16 v[10:13], v[200:203], v[94:97], v[10:13]
	v_mfma_f32_16x16x32_bf16 v[6:9], v[114:117], v[166:169], v[6:9]
	v_mfma_f32_16x16x32_bf16 v[2:5], v[200:203], v[166:169], v[2:5]
	v_mfma_f32_16x16x32_bf16 v[146:149], v[114:117], v[188:191], v[66:69]
	v_mfma_f32_16x16x32_bf16 v[66:69], v[122:125], v[184:187], v[82:85]
	v_mfma_f32_16x16x32_bf16 v[150:153], v[200:203], v[188:191], v[66:69]
	s_setprio 0
	s_barrier
	ds_read_b128 v[162:165], v144 offset:32768
	ds_read_b128 v[166:169], v144 offset:33792
	ds_read_b128 v[170:173], v144 offset:34816
	ds_read_b128 v[174:177], v144 offset:35840
	s_nop 0
	ds_read_b128 v[66:69], v0 offset:32768
	ds_read_b128 v[74:77], v0 offset:33792
	ds_read_b128 v[78:81], v0 offset:34816
	ds_read_b128 v[184:187], v0 offset:35840
	ds_read_b128 v[188:191], v0 offset:36864
	ds_read_b128 v[192:195], v0 offset:37888
	ds_read_b128 v[200:203], v0 offset:38912
	ds_read_b128 v[222:225], v0 offset:39936
	s_waitcnt vmcnt(2)
	s_barrier
; #define LDA(dst, b, h) _Pragma("unroll") for (int m = 0; m < 4; ++m) _Pragma("unroll") for (int k = 0; k < 2; ++k) \
;     dst[m][k] = *reinterpret_cast<const bf16x8*>(smem + (((b) * 2 + (h)) * 16384 + m * 2048 + k * 1024) + aoff)
; #define LDB(dst, b, h) _Pragma("unroll") for (int n = 0; n < 2; ++n) _Pragma("unroll") for (int k = 0; k < 2; ++k) \
;     dst[n][k] = *reinterpret_cast<const bf16x8*>(smem + (((b) * 2 + (h)) * 16384 + n * 2048 + k * 1024) + boff)
; #define MMA(ai, bj, At_, Bt_) do { __builtin_amdgcn_s_setprio(1); \
;     _Pragma("unroll") for (int m = 0; m < 4; ++m) _Pragma("unroll") for (int n = 0; n < 2; ++n) _Pragma("unroll") for (int k = 0; k < 2; ++k) \
;       acc[ai][bj][m][n] = __builtin_amdgcn_mfma_f32_16x16x32_bf16(Bt_[n][k], At_[m][k], acc[ai][bj][m][n], 0, 0, 0); \
;     __builtin_amdgcn_s_setprio(0); } while (0)
; #define WAIT_V(n) asm volatile("s_waitcnt vmcnt(" #n ")" ::: "memory")
; #define WAIT_L(n) asm volatile("s_waitcnt lgkmcnt(" #n ")" ::: "memory")
; #define BAR __builtin_amdgcn_s_barrier()
; template <class Epi, int NB>
; DEV void gemm_tile_nb(const bf16* __restrict__ A, int lda, long strideA, const bf16* __restrict__ Bt, int ldb, long strideB, int K, int brow, int bcol, Epi& epi) {
;     ...
;   { LDB(B0, 1, 0); LDA(At, 1, 0); WAIT_V(2); BAR; WAIT_L(0); MMA(0, 0, At, B0); BAR;
;     LDB(B1, 1, 1); WAIT_V(0); BAR; WAIT_L(0); MMA(0, 1, At, B1); BAR;
;     LDA(At, 1, 1); BAR; WAIT_L(0); MMA(1, 0, At, B0); MMA(1, 1, At, B1); BAR; }
;   if (wr == 0) BAR;
	s_waitcnt lgkmcnt(0)
	s_setprio 1
	s_waitcnt lgkmcnt(0)
	v_mfma_f32_16x16x32_bf16 v[82:85], v[162:165], v[66:69], v[126:129]
	v_mfma_f32_16x16x32_bf16 v[122:125], v[166:169], v[74:77], v[82:85]
	v_mfma_f32_16x16x32_bf16 v[82:85], v[170:173], v[66:69], v[130:133]
	v_mfma_f32_16x16x32_bf16 v[126:129], v[174:177], v[74:77], v[82:85]
	v_mfma_f32_16x16x32_bf16 v[82:85], v[162:165], v[78:81], v[118:121]
	v_mfma_f32_16x16x32_bf16 v[114:117], v[166:169], v[184:187], v[82:85]
	v_mfma_f32_16x16x32_bf16 v[82:85], v[170:173], v[78:81], v[158:161]
	v_mfma_f32_16x16x32_bf16 v[118:121], v[174:177], v[184:187], v[82:85]
	v_mfma_f32_16x16x32_bf16 v[82:85], v[162:165], v[188:191], v[110:113]
	v_mfma_f32_16x16x32_bf16 v[106:109], v[166:169], v[192:195], v[82:85]
	v_mfma_f32_16x16x32_bf16 v[82:85], v[170:173], v[188:191], v[196:199]
	v_mfma_f32_16x16x32_bf16 v[110:113], v[174:177], v[192:195], v[82:85]
	v_mfma_f32_16x16x32_bf16 v[82:85], v[162:165], v[200:203], v[102:105]
	v_mfma_f32_16x16x32_bf16 v[90:93], v[166:169], v[222:225], v[82:85]
	v_mfma_f32_16x16x32_bf16 v[82:85], v[170:173], v[200:203], v[98:101]
	v_mfma_f32_16x16x32_bf16 v[94:97], v[174:177], v[222:225], v[82:85]
	s_setprio 0
	s_barrier
	ds_read_b128 v[130:133], v144 offset:49152
	ds_read_b128 v[158:161], v144 offset:50176
	ds_read_b128 v[196:199], v144 offset:51200
	ds_read_b128 v[226:229], v144 offset:52224
	s_waitcnt vmcnt(0)
	s_barrier
	s_waitcnt lgkmcnt(0)
	s_setprio 1
	s_waitcnt lgkmcnt(0)
	v_mfma_f32_16x16x32_bf16 v[82:85], v[130:133], v[66:69], v[218:221]
	v_mfma_f32_16x16x32_bf16 v[66:69], v[196:199], v[66:69], v[154:157]
	v_mfma_f32_16x16x32_bf16 v[102:105], v[226:229], v[74:77], v[66:69]
	v_mfma_f32_16x16x32_bf16 v[66:69], v[130:133], v[78:81], v[86:89]
	v_mfma_f32_16x16x32_bf16 v[98:101], v[158:161], v[74:77], v[82:85]
	v_mfma_f32_16x16x32_bf16 v[82:85], v[158:161], v[184:187], v[66:69]
	v_mfma_f32_16x16x32_bf16 v[66:69], v[196:199], v[78:81], v[70:73]
	v_mfma_f32_16x16x32_bf16 v[62:65], v[130:133], v[188:191], v[62:65]
	v_mfma_f32_16x16x32_bf16 v[58:61], v[196:199], v[188:191], v[58:61]
	v_mfma_f32_16x16x32_bf16 v[54:57], v[130:133], v[200:203], v[54:57]
	v_mfma_f32_16x16x32_bf16 v[50:53], v[196:199], v[200:203], v[50:53]
	v_mfma_f32_16x16x32_bf16 v[86:89], v[226:229], v[184:187], v[66:69]
	v_mfma_f32_16x16x32_bf16 v[74:77], v[158:161], v[192:195], v[62:65]
	v_mfma_f32_16x16x32_bf16 v[78:81], v[226:229], v[192:195], v[58:61]
	v_mfma_f32_16x16x32_bf16 v[66:69], v[158:161], v[222:225], v[54:57]
	v_mfma_f32_16x16x32_bf16 v[70:73], v[226:229], v[222:225], v[50:53]
	s_setprio 0
	s_barrier
	ds_read_b128 v[154:157], v0 offset:49152
	ds_read_b128 v[184:187], v0 offset:50176
	ds_read_b128 v[188:191], v0 offset:51200
	ds_read_b128 v[192:195], v0 offset:52224
	ds_read_b128 v[200:203], v0 offset:53248
	ds_read_b128 v[218:221], v0 offset:54272
	ds_read_b128 v[222:225], v0 offset:55296
	ds_read_b128 v[230:233], v0 offset:56320
	s_barrier
	s_waitcnt lgkmcnt(0)
	s_setprio 1
	s_waitcnt lgkmcnt(0)
	v_mfma_f32_16x16x32_bf16 v[46:49], v[162:165], v[154:157], v[46:49]
	v_mfma_f32_16x16x32_bf16 v[42:45], v[170:173], v[154:157], v[42:45]
	v_mfma_f32_16x16x32_bf16 v[38:41], v[162:165], v[188:191], v[38:41]
	v_mfma_f32_16x16x32_bf16 v[34:37], v[170:173], v[188:191], v[34:37]
	v_mfma_f32_16x16x32_bf16 v[30:33], v[162:165], v[200:203], v[30:33]
	v_mfma_f32_16x16x32_bf16 v[26:29], v[170:173], v[200:203], v[26:29]
	v_mfma_f32_16x16x32_bf16 v[22:25], v[162:165], v[222:225], v[22:25]
	v_mfma_f32_16x16x32_bf16 v[18:21], v[170:173], v[222:225], v[18:21]
	v_mfma_f32_16x16x32_bf16 v[58:61], v[166:169], v[184:187], v[46:49]
	v_mfma_f32_16x16x32_bf16 v[62:65], v[174:177], v[184:187], v[42:45]
	v_mfma_f32_16x16x32_bf16 v[50:53], v[166:169], v[192:195], v[38:41]
	v_mfma_f32_16x16x32_bf16 v[54:57], v[174:177], v[192:195], v[34:37]
	v_mfma_f32_16x16x32_bf16 v[42:45], v[166:169], v[218:221], v[30:33]
	v_mfma_f32_16x16x32_bf16 v[46:49], v[174:177], v[218:221], v[26:29]
	v_mfma_f32_16x16x32_bf16 v[34:37], v[166:169], v[230:233], v[22:25]
	v_mfma_f32_16x16x32_bf16 v[38:41], v[174:177], v[230:233], v[18:21]
	s_setprio 0
	s_setprio 1
	v_mfma_f32_16x16x32_bf16 v[2:5], v[196:199], v[188:191], v[2:5]
	v_mfma_f32_16x16x32_bf16 v[10:13], v[196:199], v[154:157], v[10:13]
	v_mfma_f32_16x16x32_bf16 v[22:25], v[226:229], v[192:195], v[2:5]
	v_mfma_f32_16x16x32_bf16 v[2:5], v[130:133], v[200:203], v[134:137]
	v_mfma_f32_16x16x32_bf16 v[14:17], v[130:133], v[154:157], v[14:17]
	v_mfma_f32_16x16x32_bf16 v[30:33], v[226:229], v[184:187], v[10:13]
	v_mfma_f32_16x16x32_bf16 v[6:9], v[130:133], v[188:191], v[6:9]
	v_mfma_f32_16x16x32_bf16 v[10:13], v[158:161], v[218:221], v[2:5]
	v_mfma_f32_16x16x32_bf16 v[2:5], v[196:199], v[200:203], v[138:141]
	v_mfma_f32_16x16x32_bf16 v[26:29], v[158:161], v[184:187], v[14:17]
	v_mfma_f32_16x16x32_bf16 v[18:21], v[158:161], v[192:195], v[6:9]
	v_mfma_f32_16x16x32_bf16 v[14:17], v[226:229], v[218:221], v[2:5]
	v_mfma_f32_16x16x32_bf16 v[2:5], v[130:133], v[222:225], v[146:149]
	v_mfma_f32_16x16x32_bf16 v[6:9], v[196:199], v[222:225], v[150:153]
	v_mfma_f32_16x16x32_bf16 v[2:5], v[158:161], v[230:233], v[2:5]
	v_mfma_f32_16x16x32_bf16 v[6:9], v[226:229], v[230:233], v[6:9]
	s_setprio 0
	s_barrier
	s_cbranch_scc1 .LBB0_775
	s_barrier
	s_branch .LBB0_775

; #define STAGE(P, BASE, LD, br, kt) do { const bf16* _gb = BASE + ((long)(br) * (LD) + (long)(kt) * BK); \
;     _Pragma("unroll") for (int _i = 0; _i < 2; ++_i) { \
;       __builtin_amdgcn_global_load_lds((const unsigned*)(_gb + ((&LD == &lda) ? offA[_i] : offB[_i])), \
;         (unsigned*)((char*)(P) + tidx_ * 16 + _i * 8192), 16, 0, 0); } } while (0)
; #define LDA(dst, b, h) _Pragma("unroll") for (int m = 0; m < 4; ++m) _Pragma("unroll") for (int k = 0; k < 2; ++k) \
;     dst[m][k] = *reinterpret_cast<const bf16x8*>(smem + (((b) * 2 + (h)) * 16384 + m * 2048 + k * 1024) + aoff)
; #define LDB(dst, b, h) _Pragma("unroll") for (int n = 0; n < 2; ++n) _Pragma("unroll") for (int k = 0; k < 2; ++k) \
;     dst[n][k] = *reinterpret_cast<const bf16x8*>(smem + (((b) * 2 + (h)) * 16384 + n * 2048 + k * 1024) + boff)
; #define MMA(ai, bj, At_, Bt_) do { __builtin_amdgcn_s_setprio(1); \
;     _Pragma("unroll") for (int m = 0; m < 4; ++m) _Pragma("unroll") for (int n = 0; n < 2; ++n) _Pragma("unroll") for (int k = 0; k < 2; ++k) \
;       acc[ai][bj][m][n] = __builtin_amdgcn_mfma_f32_16x16x32_bf16(Bt_[n][k], At_[m][k], acc[ai][bj][m][n], 0, 0, 0); \
;     __builtin_amdgcn_s_setprio(0); } while (0)
; #define WAIT_L(n) asm volatile("s_waitcnt lgkmcnt(" #n ")" ::: "memory")
; #define BAR __builtin_amdgcn_s_barrier()
; #define SCHED __builtin_amdgcn_sched_barrier(0)
; template <class Epi, int NB>
; DEV void gemm_tile_nb(const bf16* __restrict__ A, int lda, long strideA, const bf16* __restrict__ Bt, int ldb, long strideB, int K, int brow, int bcol, Epi& epi) {
;     ...
;     LDB(B0, 0, 0); SCHED; LDA(At, 0, 0); STAGE(SA(1, 1), A, lda, brow + HALF, t + 1);
;     WAIT_L(8); BAR; WAIT_L(0); MMA(0, 0, At, B0); BAR; SCHED;
;     LDB(B1, 0, 1); STAGE(SB(0, 0), Bt, ldb, bcol, t + 2);
;     BAR; WAIT_L(0); MMA(0, 1, At, B1); BAR;
;     LDA(At, 0, 1); STAGE(SA(0, 0), A, lda, brow, t + 2);
;     BAR; WAIT_L(0); MMA(1, 0, At, B0); BAR; SCHED;
.LBB0_960:
	v_add_u32_e32 v159, 0xc000, v146
	v_lshl_add_u64 v[246:247], v[138:139], 0, s[42:43]
	v_readfirstlane_b32 s59, v159
	v_lshl_add_u64 v[160:161], v[246:247], 0, s[80:81]
	v_lshl_add_u64 v[248:249], v[140:141], 0, s[42:43]
	v_lshl_add_u64 v[230:231], v[248:249], 0, s[80:81]
	s_mov_b32 m0, s59
	ds_read_b128 v[184:187], v0
	ds_read_b128 v[188:191], v0 offset:1024
	ds_read_b128 v[192:195], v0 offset:2048
	ds_read_b128 v[196:199], v0 offset:3072
	ds_read_b128 v[200:203], v0 offset:4096
	ds_read_b128 v[218:221], v0 offset:5120
	ds_read_b128 v[222:225], v0 offset:6144
	ds_read_b128 v[226:229], v0 offset:7168
	global_load_lds_dwordx4 v[160:161], off
	s_add_i32 m0, m0, 0x2000
	v_add_u32_e32 v160, 0xe000, v146
	global_load_lds_dwordx4 v[230:231], off
	s_waitcnt lgkmcnt(8)
	s_barrier
	s_waitcnt lgkmcnt(0)
	s_setprio 1
	s_waitcnt lgkmcnt(0)
	v_mfma_f32_16x16x32_bf16 v[126:129], v[162:165], v[184:187], v[126:129]
	v_mfma_f32_16x16x32_bf16 v[122:125], v[170:173], v[184:187], v[122:125]
	v_mfma_f32_16x16x32_bf16 v[118:121], v[162:165], v[192:195], v[118:121]
	v_mfma_f32_16x16x32_bf16 v[114:117], v[170:173], v[192:195], v[114:117]
	v_mfma_f32_16x16x32_bf16 v[110:113], v[162:165], v[200:203], v[110:113]
	v_mfma_f32_16x16x32_bf16 v[106:109], v[170:173], v[200:203], v[106:109]
	v_mfma_f32_16x16x32_bf16 v[102:105], v[162:165], v[222:225], v[102:105]
	v_mfma_f32_16x16x32_bf16 v[98:101], v[170:173], v[222:225], v[98:101]
	v_mfma_f32_16x16x32_bf16 v[126:129], v[166:169], v[188:191], v[126:129]
	v_mfma_f32_16x16x32_bf16 v[122:125], v[174:177], v[188:191], v[122:125]
	v_mfma_f32_16x16x32_bf16 v[118:121], v[166:169], v[196:199], v[118:121]
	v_mfma_f32_16x16x32_bf16 v[114:117], v[174:177], v[196:199], v[114:117]
	v_mfma_f32_16x16x32_bf16 v[110:113], v[166:169], v[218:221], v[110:113]
	v_mfma_f32_16x16x32_bf16 v[106:109], v[174:177], v[218:221], v[106:109]
	v_mfma_f32_16x16x32_bf16 v[102:105], v[166:169], v[226:229], v[102:105]
	v_mfma_f32_16x16x32_bf16 v[98:101], v[174:177], v[226:229], v[98:101]
	s_setprio 0
	s_barrier
	v_lshl_add_u64 v[204:205], v[134:135], 0, s[42:43]
	v_readfirstlane_b32 s59, v144
	v_lshl_add_u64 v[214:215], v[204:205], 0, s[72:73]
	s_mov_b32 m0, s59
	ds_read_b128 v[230:233], v145 offset:16384
	ds_read_b128 v[234:237], v145 offset:17408
	ds_read_b128 v[238:241], v145 offset:18432
	ds_read_b128 v[242:245], v145 offset:19456
	global_load_lds_dwordx4 v[214:215], off
	v_lshl_add_u64 v[214:215], v[136:137], 0, s[42:43]
	v_readfirstlane_b32 s59, v148
	v_lshl_add_u64 v[208:209], v[214:215], 0, s[72:73]
	s_mov_b32 m0, s59
	s_nop 0
	global_load_lds_dwordx4 v[208:209], off
	s_barrier
	s_waitcnt lgkmcnt(0)
	s_setprio 1
	s_waitcnt lgkmcnt(0)
	v_mfma_f32_16x16x32_bf16 v[94:97], v[230:233], v[184:187], v[94:97]
	v_mfma_f32_16x16x32_bf16 v[90:93], v[238:241], v[184:187], v[90:93]
	v_mfma_f32_16x16x32_bf16 v[86:89], v[230:233], v[192:195], v[86:89]
	v_mfma_f32_16x16x32_bf16 v[70:73], v[238:241], v[192:195], v[70:73]
	v_mfma_f32_16x16x32_bf16 v[62:65], v[230:233], v[200:203], v[62:65]
	v_mfma_f32_16x16x32_bf16 v[58:61], v[238:241], v[200:203], v[58:61]
	v_mfma_f32_16x16x32_bf16 v[54:57], v[230:233], v[222:225], v[54:57]
	v_mfma_f32_16x16x32_bf16 v[50:53], v[238:241], v[222:225], v[50:53]
	v_mfma_f32_16x16x32_bf16 v[94:97], v[234:237], v[188:191], v[94:97]
	v_mfma_f32_16x16x32_bf16 v[90:93], v[242:245], v[188:191], v[90:93]
	v_mfma_f32_16x16x32_bf16 v[86:89], v[234:237], v[196:199], v[86:89]
	v_mfma_f32_16x16x32_bf16 v[70:73], v[242:245], v[196:199], v[70:73]
	v_mfma_f32_16x16x32_bf16 v[62:65], v[234:237], v[218:221], v[62:65]
	v_mfma_f32_16x16x32_bf16 v[58:61], v[242:245], v[218:221], v[58:61]
	v_mfma_f32_16x16x32_bf16 v[54:57], v[234:237], v[226:229], v[54:57]
	v_mfma_f32_16x16x32_bf16 v[50:53], v[242:245], v[226:229], v[50:53]
	s_setprio 0
	v_readfirstlane_b32 s59, v146
	v_lshl_add_u64 v[208:209], v[246:247], 0, s[72:73]
	s_mov_b32 m0, s59
	v_readfirstlane_b32 s59, v150
	s_barrier
	ds_read_b128 v[184:187], v0 offset:16384
	ds_read_b128 v[188:191], v0 offset:17408
	ds_read_b128 v[192:195], v0 offset:18432
	ds_read_b128 v[196:199], v0 offset:19456
	ds_read_b128 v[200:203], v0 offset:20480
	ds_read_b128 v[218:221], v0 offset:21504
	ds_read_b128 v[222:225], v0 offset:22528
	ds_read_b128 v[226:229], v0 offset:23552
	global_load_lds_dwordx4 v[208:209], off
	v_lshl_add_u64 v[208:209], v[248:249], 0, s[72:73]
	s_mov_b32 m0, s59
	s_nop 0
	global_load_lds_dwordx4 v[208:209], off
	s_waitcnt vmcnt(10)
	s_barrier
	s_waitcnt lgkmcnt(0)
	s_setprio 1
	s_waitcnt lgkmcnt(0)
	v_mfma_f32_16x16x32_bf16 v[46:49], v[162:165], v[184:187], v[46:49]
	v_mfma_f32_16x16x32_bf16 v[42:45], v[170:173], v[184:187], v[42:45]
	v_mfma_f32_16x16x32_bf16 v[38:41], v[162:165], v[192:195], v[38:41]
	v_mfma_f32_16x16x32_bf16 v[34:37], v[170:173], v[192:195], v[34:37]
	v_mfma_f32_16x16x32_bf16 v[30:33], v[162:165], v[200:203], v[30:33]
	v_mfma_f32_16x16x32_bf16 v[26:29], v[170:173], v[200:203], v[26:29]
	v_mfma_f32_16x16x32_bf16 v[22:25], v[162:165], v[222:225], v[22:25]
	v_mfma_f32_16x16x32_bf16 v[18:21], v[170:173], v[222:225], v[18:21]
	v_mfma_f32_16x16x32_bf16 v[46:49], v[166:169], v[188:191], v[46:49]
	v_mfma_f32_16x16x32_bf16 v[42:45], v[174:177], v[188:191], v[42:45]
	v_mfma_f32_16x16x32_bf16 v[38:41], v[166:169], v[196:199], v[38:41]
	v_mfma_f32_16x16x32_bf16 v[34:37], v[174:177], v[196:199], v[34:37]
	v_mfma_f32_16x16x32_bf16 v[30:33], v[166:169], v[218:221], v[30:33]
	v_mfma_f32_16x16x32_bf16 v[26:29], v[174:177], v[218:221], v[26:29]
	v_mfma_f32_16x16x32_bf16 v[22:25], v[166:169], v[226:229], v[22:25]
	v_mfma_f32_16x16x32_bf16 v[18:21], v[174:177], v[226:229], v[18:21]
	s_setprio 0
	s_barrier
; #define STAGE(P, BASE, LD, br, kt) do { const bf16* _gb = BASE + ((long)(br) * (LD) + (long)(kt) * BK); \
;     _Pragma("unroll") for (int _i = 0; _i < 2; ++_i) { \
;       __builtin_amdgcn_global_load_lds((const unsigned*)(_gb + ((&LD == &lda) ? offA[_i] : offB[_i])), \
;         (unsigned*)((char*)(P) + tidx_ * 16 + _i * 8192), 16, 0, 0); } } while (0)
; #define LDA(dst, b, h) _Pragma("unroll") for (int m = 0; m < 4; ++m) _Pragma("unroll") for (int k = 0; k < 2; ++k) \
;     dst[m][k] = *reinterpret_cast<const bf16x8*>(smem + (((b) * 2 + (h)) * 16384 + m * 2048 + k * 1024) + aoff)
; #define LDB(dst, b, h) _Pragma("unroll") for (int n = 0; n < 2; ++n) _Pragma("unroll") for (int k = 0; k < 2; ++k) \
;     dst[n][k] = *reinterpret_cast<const bf16x8*>(smem + (((b) * 2 + (h)) * 16384 + n * 2048 + k * 1024) + boff)
; #define MMA(ai, bj, At_, Bt_) do { __builtin_amdgcn_s_setprio(1); \
;     _Pragma("unroll") for (int m = 0; m < 4; ++m) _Pragma("unroll") for (int n = 0; n < 2; ++n) _Pragma("unroll") for (int k = 0; k < 2; ++k) \
;       acc[ai][bj][m][n] = __builtin_amdgcn_mfma_f32_16x16x32_bf16(Bt_[n][k], At_[m][k], acc[ai][bj][m][n], 0, 0, 0); \
;     __builtin_amdgcn_s_setprio(0); } while (0)
; #define WAIT_V(n) asm volatile("s_waitcnt vmcnt(" #n ")" ::: "memory")
; #define WAIT_L(n) asm volatile("s_waitcnt lgkmcnt(" #n ")" ::: "memory")
; #define BAR __builtin_amdgcn_s_barrier()
; #define SCHED __builtin_amdgcn_sched_barrier(0)
; template <class Epi, int NB>
; DEV void gemm_tile_nb(const bf16* __restrict__ A, int lda, long strideA, const bf16* __restrict__ Bt, int ldb, long strideB, int K, int brow, int bcol, Epi& epi) {
;     ...
;     STAGE(SB(0, 1), Bt, ldb, bcol + HALF, t + 2);
;     WAIT_V(6); BAR; MMA(1, 1, At, B1); BAR;
;     LDB(B0, 1, 0); SCHED; LDA(At, 1, 0); STAGE(SA(0, 1), A, lda, brow + HALF, t + 2);
;     WAIT_L(8); BAR; WAIT_L(0); MMA(0, 0, At, B0); BAR; SCHED;
;     LDB(B1, 1, 1); STAGE(SB(1, 0), Bt, ldb, bcol, t + 3);
;     BAR; WAIT_L(0); MMA(0, 1, At, B1); BAR;
;     LDA(At, 1, 1); STAGE(SA(1, 0), A, lda, brow, t + 3);
;     BAR; WAIT_L(0); MMA(1, 0, At, B0); BAR; SCHED;
	v_readfirstlane_b32 s59, v147
	v_lshl_add_u64 v[162:163], v[204:205], 0, s[82:83]
	s_mov_b32 m0, s59
	v_readfirstlane_b32 s59, v151
	global_load_lds_dwordx4 v[162:163], off
	v_lshl_add_u64 v[162:163], v[214:215], 0, s[82:83]
	s_mov_b32 m0, s59
	s_nop 0
	global_load_lds_dwordx4 v[162:163], off
	ds_read_b128 v[162:165], v145 offset:32768
	ds_read_b128 v[166:169], v145 offset:33792
	ds_read_b128 v[170:173], v145 offset:34816
	ds_read_b128 v[174:177], v145 offset:35840
	s_waitcnt vmcnt(6)
	s_barrier
	s_setprio 1
	v_mfma_f32_16x16x32_bf16 v[14:17], v[230:233], v[184:187], v[14:17]
	v_mfma_f32_16x16x32_bf16 v[10:13], v[238:241], v[184:187], v[10:13]
	v_mfma_f32_16x16x32_bf16 v[6:9], v[230:233], v[192:195], v[6:9]
	v_mfma_f32_16x16x32_bf16 v[2:5], v[238:241], v[192:195], v[2:5]
	v_mfma_f32_16x16x32_bf16 v[66:69], v[230:233], v[200:203], v[66:69]
	v_mfma_f32_16x16x32_bf16 v[74:77], v[238:241], v[200:203], v[74:77]
	v_mfma_f32_16x16x32_bf16 v[78:81], v[230:233], v[222:225], v[78:81]
	v_mfma_f32_16x16x32_bf16 v[82:85], v[238:241], v[222:225], v[82:85]
	v_mfma_f32_16x16x32_bf16 v[14:17], v[234:237], v[188:191], v[14:17]
	v_mfma_f32_16x16x32_bf16 v[10:13], v[242:245], v[188:191], v[10:13]
	v_mfma_f32_16x16x32_bf16 v[6:9], v[234:237], v[196:199], v[6:9]
	v_mfma_f32_16x16x32_bf16 v[2:5], v[242:245], v[196:199], v[2:5]
	v_mfma_f32_16x16x32_bf16 v[66:69], v[234:237], v[218:221], v[66:69]
	v_mfma_f32_16x16x32_bf16 v[74:77], v[242:245], v[218:221], v[74:77]
	v_mfma_f32_16x16x32_bf16 v[78:81], v[234:237], v[226:229], v[78:81]
	v_mfma_f32_16x16x32_bf16 v[82:85], v[242:245], v[226:229], v[82:85]
	s_setprio 0
	s_barrier
	v_readfirstlane_b32 s59, v149
	v_lshl_add_u64 v[208:209], v[246:247], 0, s[82:83]
	s_mov_b32 m0, s59
	v_readfirstlane_b32 s59, v152
	ds_read_b128 v[184:187], v0 offset:32768
	ds_read_b128 v[188:191], v0 offset:33792
	ds_read_b128 v[192:195], v0 offset:34816
	ds_read_b128 v[196:199], v0 offset:35840
	ds_read_b128 v[200:203], v0 offset:36864
	ds_read_b128 v[218:221], v0 offset:37888
	ds_read_b128 v[222:225], v0 offset:38912
	ds_read_b128 v[226:229], v0 offset:39936
	global_load_lds_dwordx4 v[208:209], off
	v_lshl_add_u64 v[208:209], v[248:249], 0, s[82:83]
	s_mov_b32 m0, s59
	s_nop 0
	global_load_lds_dwordx4 v[208:209], off
	s_waitcnt lgkmcnt(8)
	s_barrier
	s_waitcnt lgkmcnt(0)
	s_setprio 1
	s_waitcnt lgkmcnt(0)
	v_mfma_f32_16x16x32_bf16 v[126:129], v[162:165], v[184:187], v[126:129]
	v_mfma_f32_16x16x32_bf16 v[122:125], v[170:173], v[184:187], v[122:125]
	v_mfma_f32_16x16x32_bf16 v[118:121], v[162:165], v[192:195], v[118:121]
	v_mfma_f32_16x16x32_bf16 v[114:117], v[170:173], v[192:195], v[114:117]
	v_mfma_f32_16x16x32_bf16 v[110:113], v[162:165], v[200:203], v[110:113]
	v_mfma_f32_16x16x32_bf16 v[106:109], v[170:173], v[200:203], v[106:109]
	v_mfma_f32_16x16x32_bf16 v[102:105], v[162:165], v[222:225], v[102:105]
	v_mfma_f32_16x16x32_bf16 v[98:101], v[170:173], v[222:225], v[98:101]
	v_mfma_f32_16x16x32_bf16 v[126:129], v[166:169], v[188:191], v[126:129]
	v_mfma_f32_16x16x32_bf16 v[122:125], v[174:177], v[188:191], v[122:125]
	v_mfma_f32_16x16x32_bf16 v[118:121], v[166:169], v[196:199], v[118:121]
	v_mfma_f32_16x16x32_bf16 v[114:117], v[174:177], v[196:199], v[114:117]
	v_mfma_f32_16x16x32_bf16 v[110:113], v[166:169], v[218:221], v[110:113]
	v_mfma_f32_16x16x32_bf16 v[106:109], v[174:177], v[218:221], v[106:109]
	v_mfma_f32_16x16x32_bf16 v[102:105], v[166:169], v[226:229], v[102:105]
	v_mfma_f32_16x16x32_bf16 v[98:101], v[174:177], v[226:229], v[98:101]
	s_setprio 0
	s_barrier
	v_readfirstlane_b32 s59, v153
	v_lshl_add_u64 v[208:209], v[204:205], 0, s[84:85]
	s_mov_b32 m0, s59
	v_readfirstlane_b32 s59, v154
	ds_read_b128 v[230:233], v145 offset:49152
	ds_read_b128 v[234:237], v145 offset:50176
	ds_read_b128 v[238:241], v145 offset:51200
	ds_read_b128 v[242:245], v145 offset:52224
	global_load_lds_dwordx4 v[208:209], off
	v_lshl_add_u64 v[208:209], v[214:215], 0, s[84:85]
	s_mov_b32 m0, s59
	s_nop 0
	global_load_lds_dwordx4 v[208:209], off
	s_barrier
	s_waitcnt lgkmcnt(0)
	s_setprio 1
	s_waitcnt lgkmcnt(0)
	v_mfma_f32_16x16x32_bf16 v[94:97], v[230:233], v[184:187], v[94:97]
	v_mfma_f32_16x16x32_bf16 v[90:93], v[238:241], v[184:187], v[90:93]
	v_mfma_f32_16x16x32_bf16 v[86:89], v[230:233], v[192:195], v[86:89]
	v_mfma_f32_16x16x32_bf16 v[70:73], v[238:241], v[192:195], v[70:73]
	v_mfma_f32_16x16x32_bf16 v[62:65], v[230:233], v[200:203], v[62:65]
	v_mfma_f32_16x16x32_bf16 v[58:61], v[238:241], v[200:203], v[58:61]
	v_mfma_f32_16x16x32_bf16 v[54:57], v[230:233], v[222:225], v[54:57]
	v_mfma_f32_16x16x32_bf16 v[50:53], v[238:241], v[222:225], v[50:53]
	v_mfma_f32_16x16x32_bf16 v[94:97], v[234:237], v[188:191], v[94:97]
	v_mfma_f32_16x16x32_bf16 v[90:93], v[242:245], v[188:191], v[90:93]
	v_mfma_f32_16x16x32_bf16 v[86:89], v[234:237], v[196:199], v[86:89]
	v_mfma_f32_16x16x32_bf16 v[70:73], v[242:245], v[196:199], v[70:73]
	v_mfma_f32_16x16x32_bf16 v[62:65], v[234:237], v[218:221], v[62:65]
	v_mfma_f32_16x16x32_bf16 v[58:61], v[242:245], v[218:221], v[58:61]
	v_mfma_f32_16x16x32_bf16 v[54:57], v[234:237], v[226:229], v[54:57]
	v_mfma_f32_16x16x32_bf16 v[50:53], v[242:245], v[226:229], v[50:53]
	s_setprio 0
	v_readfirstlane_b32 s59, v155
	v_lshl_add_u64 v[208:209], v[246:247], 0, s[84:85]
	s_mov_b32 m0, s59
	v_readfirstlane_b32 s59, v156
	s_barrier
	ds_read_b128 v[184:187], v0 offset:49152
	ds_read_b128 v[188:191], v0 offset:50176
	ds_read_b128 v[192:195], v0 offset:51200
	ds_read_b128 v[196:199], v0 offset:52224
	ds_read_b128 v[200:203], v0 offset:53248
	ds_read_b128 v[218:221], v0 offset:54272
	ds_read_b128 v[222:225], v0 offset:55296
	ds_read_b128 v[226:229], v0 offset:56320
	global_load_lds_dwordx4 v[208:209], off
	v_lshl_add_u64 v[208:209], v[248:249], 0, s[84:85]
	s_mov_b32 m0, s59
	s_nop 0
	global_load_lds_dwordx4 v[208:209], off
	s_waitcnt vmcnt(10)
	s_barrier
; #define STAGE(P, BASE, LD, br, kt) do { const bf16* _gb = BASE + ((long)(br) * (LD) + (long)(kt) * BK); \
;     _Pragma("unroll") for (int _i = 0; _i < 2; ++_i) { \
;       __builtin_amdgcn_global_load_lds((const unsigned*)(_gb + ((&LD == &lda) ? offA[_i] : offB[_i])), \
;         (unsigned*)((char*)(P) + tidx_ * 16 + _i * 8192), 16, 0, 0); } } while (0)
; #define LDA(dst, b, h) _Pragma("unroll") for (int m = 0; m < 4; ++m) _Pragma("unroll") for (int k = 0; k < 2; ++k) \
;     dst[m][k] = *reinterpret_cast<const bf16x8*>(smem + (((b) * 2 + (h)) * 16384 + m * 2048 + k * 1024) + aoff)
; #define LDB(dst, b, h) _Pragma("unroll") for (int n = 0; n < 2; ++n) _Pragma("unroll") for (int k = 0; k < 2; ++k) \
;     dst[n][k] = *reinterpret_cast<const bf16x8*>(smem + (((b) * 2 + (h)) * 16384 + n * 2048 + k * 1024) + boff)
; #define MMA(ai, bj, At_, Bt_) do { __builtin_amdgcn_s_setprio(1); \
;     _Pragma("unroll") for (int m = 0; m < 4; ++m) _Pragma("unroll") for (int n = 0; n < 2; ++n) _Pragma("unroll") for (int k = 0; k < 2; ++k) \
;       acc[ai][bj][m][n] = __builtin_amdgcn_mfma_f32_16x16x32_bf16(Bt_[n][k], At_[m][k], acc[ai][bj][m][n], 0, 0, 0); \
;     __builtin_amdgcn_s_setprio(0); } while (0)
; #define WAIT_V(n) asm volatile("s_waitcnt vmcnt(" #n ")" ::: "memory")
; #define WAIT_L(n) asm volatile("s_waitcnt lgkmcnt(" #n ")" ::: "memory")
; #define BAR __builtin_amdgcn_s_barrier()
; #define SCHED __builtin_amdgcn_sched_barrier(0)
; template <class Epi, int NB>
; DEV void gemm_tile_nb(const bf16* __restrict__ A, int lda, long strideA, const bf16* __restrict__ Bt, int ldb, long strideB, int K, int brow, int bcol, Epi& epi) {
;     ...
;     BAR; WAIT_L(0); MMA(1, 0, At, B0); BAR; SCHED;
;     STAGE(SB(1, 1), Bt, ldb, bcol + HALF, t + 3);
;     WAIT_V(6); BAR; MMA(1, 1, At, B1); BAR;
;   }
;   { LDB(B0, 0, 0); LDA(At, 0, 0); STAGE(SA(1, 1), A, lda, brow + HALF, nt - 1);
;     BAR; WAIT_L(0); MMA(0, 0, At, B0); BAR;
;     LDB(B1, 0, 1); BAR; WAIT_L(0); MMA(0, 1, At, B1); BAR;
	s_waitcnt lgkmcnt(0)
	s_setprio 1
	s_waitcnt lgkmcnt(0)
	v_mfma_f32_16x16x32_bf16 v[46:49], v[162:165], v[184:187], v[46:49]
	v_mfma_f32_16x16x32_bf16 v[42:45], v[170:173], v[184:187], v[42:45]
	v_mfma_f32_16x16x32_bf16 v[38:41], v[162:165], v[192:195], v[38:41]
	v_mfma_f32_16x16x32_bf16 v[34:37], v[170:173], v[192:195], v[34:37]
	v_mfma_f32_16x16x32_bf16 v[30:33], v[162:165], v[200:203], v[30:33]
	v_mfma_f32_16x16x32_bf16 v[26:29], v[170:173], v[200:203], v[26:29]
	v_mfma_f32_16x16x32_bf16 v[22:25], v[162:165], v[222:225], v[22:25]
	v_mfma_f32_16x16x32_bf16 v[18:21], v[170:173], v[222:225], v[18:21]
	v_mfma_f32_16x16x32_bf16 v[46:49], v[166:169], v[188:191], v[46:49]
	v_mfma_f32_16x16x32_bf16 v[42:45], v[174:177], v[188:191], v[42:45]
	v_mfma_f32_16x16x32_bf16 v[38:41], v[166:169], v[196:199], v[38:41]
	v_mfma_f32_16x16x32_bf16 v[34:37], v[174:177], v[196:199], v[34:37]
	v_mfma_f32_16x16x32_bf16 v[30:33], v[166:169], v[218:221], v[30:33]
	v_mfma_f32_16x16x32_bf16 v[26:29], v[174:177], v[218:221], v[26:29]
	v_mfma_f32_16x16x32_bf16 v[22:25], v[166:169], v[226:229], v[22:25]
	v_mfma_f32_16x16x32_bf16 v[18:21], v[174:177], v[226:229], v[18:21]
	s_setprio 0
	s_barrier
	v_readfirstlane_b32 s59, v157
	v_lshl_add_u64 v[162:163], v[204:205], 0, s[86:87]
	s_mov_b32 m0, s59
	v_readfirstlane_b32 s59, v158
	global_load_lds_dwordx4 v[162:163], off
	v_lshl_add_u64 v[162:163], v[214:215], 0, s[86:87]
	s_mov_b32 m0, s59
	s_nop 0
	global_load_lds_dwordx4 v[162:163], off
	ds_read_b128 v[162:165], v145
	ds_read_b128 v[166:169], v145 offset:1024
	ds_read_b128 v[170:173], v145 offset:2048
	ds_read_b128 v[174:177], v145 offset:3072
	s_waitcnt vmcnt(6)
	s_barrier
	s_setprio 1
	v_mfma_f32_16x16x32_bf16 v[14:17], v[230:233], v[184:187], v[14:17]
	v_mfma_f32_16x16x32_bf16 v[10:13], v[238:241], v[184:187], v[10:13]
	v_mfma_f32_16x16x32_bf16 v[6:9], v[230:233], v[192:195], v[6:9]
	v_mfma_f32_16x16x32_bf16 v[2:5], v[238:241], v[192:195], v[2:5]
	v_mfma_f32_16x16x32_bf16 v[66:69], v[230:233], v[200:203], v[66:69]
	v_mfma_f32_16x16x32_bf16 v[74:77], v[238:241], v[200:203], v[74:77]
	v_mfma_f32_16x16x32_bf16 v[78:81], v[230:233], v[222:225], v[78:81]
	v_mfma_f32_16x16x32_bf16 v[82:85], v[238:241], v[222:225], v[82:85]
	v_mfma_f32_16x16x32_bf16 v[14:17], v[234:237], v[188:191], v[14:17]
	v_mfma_f32_16x16x32_bf16 v[10:13], v[242:245], v[188:191], v[10:13]
	v_mfma_f32_16x16x32_bf16 v[6:9], v[234:237], v[196:199], v[6:9]
	v_mfma_f32_16x16x32_bf16 v[2:5], v[242:245], v[196:199], v[2:5]
	v_mfma_f32_16x16x32_bf16 v[66:69], v[234:237], v[218:221], v[66:69]
	v_mfma_f32_16x16x32_bf16 v[74:77], v[242:245], v[218:221], v[74:77]
	v_mfma_f32_16x16x32_bf16 v[78:81], v[234:237], v[226:229], v[78:81]
	v_mfma_f32_16x16x32_bf16 v[82:85], v[242:245], v[226:229], v[82:85]
	s_setprio 0
	s_add_i32 s58, s58, 2
	s_add_u32 s42, s42, 0x100
	s_addc_u32 s43, s43, 0
	s_cmp_lt_u32 s58, 12
	s_barrier
	s_cbranch_scc1 .LBB0_960
	s_mov_b64 s[58:59], 0x780
	v_readfirstlane_b32 s42, v159
	v_lshl_add_u64 v[132:133], v[132:133], 0, s[58:59]
	s_mov_b32 m0, s42
	v_readfirstlane_b32 s42, v160
	ds_read_b128 v[134:137], v145
	ds_read_b128 v[138:141], v145 offset:1024
	ds_read_b128 v[146:149], v145 offset:2048
	ds_read_b128 v[150:153], v145 offset:3072
	ds_read_b128 v[154:157], v0
	ds_read_b128 v[162:165], v0 offset:1024
	ds_read_b128 v[166:169], v0 offset:2048
	ds_read_b128 v[170:173], v0 offset:3072
	ds_read_b128 v[174:177], v0 offset:4096
	ds_read_b128 v[184:187], v0 offset:5120
	ds_read_b128 v[188:191], v0 offset:6144
	ds_read_b128 v[192:195], v0 offset:7168
	global_load_lds_dwordx4 v[132:133], off
	v_lshl_add_u64 v[130:131], v[130:131], 0, s[58:59]
	s_mov_b32 m0, s42
	s_cmpk_gt_u32 s57, 0xff
	global_load_lds_dwordx4 v[130:131], off
	s_barrier
	s_waitcnt lgkmcnt(0)
	s_setprio 1
	s_waitcnt lgkmcnt(0)
	v_mfma_f32_16x16x32_bf16 v[126:129], v[134:137], v[154:157], v[126:129]
	v_mfma_f32_16x16x32_bf16 v[118:121], v[134:137], v[166:169], v[118:121]
	v_mfma_f32_16x16x32_bf16 v[110:113], v[134:137], v[174:177], v[110:113]
	v_mfma_f32_16x16x32_bf16 v[102:105], v[134:137], v[188:191], v[102:105]
	v_mfma_f32_16x16x32_bf16 v[126:129], v[138:141], v[162:165], v[126:129]
	v_mfma_f32_16x16x32_bf16 v[122:125], v[146:149], v[154:157], v[122:125]
	v_mfma_f32_16x16x32_bf16 v[118:121], v[138:141], v[170:173], v[118:121]
	v_mfma_f32_16x16x32_bf16 v[114:117], v[146:149], v[166:169], v[114:117]
	v_mfma_f32_16x16x32_bf16 v[110:113], v[138:141], v[184:187], v[110:113]
	v_mfma_f32_16x16x32_bf16 v[106:109], v[146:149], v[174:177], v[106:109]
	v_mfma_f32_16x16x32_bf16 v[102:105], v[138:141], v[192:195], v[102:105]
	v_mfma_f32_16x16x32_bf16 v[98:101], v[146:149], v[188:191], v[98:101]
	v_mfma_f32_16x16x32_bf16 v[130:133], v[150:153], v[162:165], v[122:125]
	v_mfma_f32_16x16x32_bf16 v[158:161], v[150:153], v[170:173], v[114:117]
	v_mfma_f32_16x16x32_bf16 v[196:199], v[150:153], v[184:187], v[106:109]
	v_mfma_f32_16x16x32_bf16 v[200:203], v[150:153], v[192:195], v[98:101]
	s_setprio 0
	s_barrier
	s_nop 1
	ds_read_b128 v[98:101], v145 offset:16384
	ds_read_b128 v[106:109], v145 offset:17408
	ds_read_b128 v[114:117], v145 offset:18432
	ds_read_b128 v[122:125], v145 offset:19456
	s_barrier
; #define LDA(dst, b, h) _Pragma("unroll") for (int m = 0; m < 4; ++m) _Pragma("unroll") for (int k = 0; k < 2; ++k) \
;     dst[m][k] = *reinterpret_cast<const bf16x8*>(smem + (((b) * 2 + (h)) * 16384 + m * 2048 + k * 1024) + aoff)
; #define LDB(dst, b, h) _Pragma("unroll") for (int n = 0; n < 2; ++n) _Pragma("unroll") for (int k = 0; k < 2; ++k) \
;     dst[n][k] = *reinterpret_cast<const bf16x8*>(smem + (((b) * 2 + (h)) * 16384 + n * 2048 + k * 1024) + boff)
; #define MMA(ai, bj, At_, Bt_) do { __builtin_amdgcn_s_setprio(1); \
;     _Pragma("unroll") for (int m = 0; m < 4; ++m) _Pragma("unroll") for (int n = 0; n < 2; ++n) _Pragma("unroll") for (int k = 0; k < 2; ++k) \
;       acc[ai][bj][m][n] = __builtin_amdgcn_mfma_f32_16x16x32_bf16(Bt_[n][k], At_[m][k], acc[ai][bj][m][n], 0, 0, 0); \
;     __builtin_amdgcn_s_setprio(0); } while (0)
; #define WAIT_V(n) asm volatile("s_waitcnt vmcnt(" #n ")" ::: "memory")
; #define WAIT_L(n) asm volatile("s_waitcnt lgkmcnt(" #n ")" ::: "memory")
; #define BAR __builtin_amdgcn_s_barrier()
; template <class Epi, int NB>
; DEV void gemm_tile_nb(const bf16* __restrict__ A, int lda, long strideA, const bf16* __restrict__ Bt, int ldb, long strideB, int K, int brow, int bcol, Epi& epi) {
;     ...
;     LDB(B1, 0, 1); BAR; WAIT_L(0); MMA(0, 1, At, B1); BAR;
;     LDA(At, 0, 1); WAIT_V(4); BAR; WAIT_L(0); MMA(1, 0, At, B0); MMA(1, 1, At, B1); BAR; }
;   { LDB(B0, 1, 0); LDA(At, 1, 0); WAIT_V(2); BAR; WAIT_L(0); MMA(0, 0, At, B0); BAR;
	s_waitcnt lgkmcnt(0)
	s_setprio 1
	s_waitcnt lgkmcnt(0)
	v_mfma_f32_16x16x32_bf16 v[94:97], v[98:101], v[154:157], v[94:97]
	v_mfma_f32_16x16x32_bf16 v[86:89], v[98:101], v[166:169], v[86:89]
	v_mfma_f32_16x16x32_bf16 v[70:73], v[114:117], v[166:169], v[70:73]
	v_mfma_f32_16x16x32_bf16 v[62:65], v[98:101], v[174:177], v[62:65]
	v_mfma_f32_16x16x32_bf16 v[58:61], v[114:117], v[174:177], v[58:61]
	v_mfma_f32_16x16x32_bf16 v[54:57], v[98:101], v[188:191], v[54:57]
	v_mfma_f32_16x16x32_bf16 v[50:53], v[114:117], v[188:191], v[50:53]
	v_mfma_f32_16x16x32_bf16 v[94:97], v[106:109], v[162:165], v[94:97]
	v_mfma_f32_16x16x32_bf16 v[90:93], v[114:117], v[154:157], v[90:93]
	v_mfma_f32_16x16x32_bf16 v[86:89], v[106:109], v[170:173], v[86:89]
	v_mfma_f32_16x16x32_bf16 v[70:73], v[122:125], v[170:173], v[70:73]
	v_mfma_f32_16x16x32_bf16 v[62:65], v[106:109], v[184:187], v[62:65]
	v_mfma_f32_16x16x32_bf16 v[58:61], v[122:125], v[184:187], v[58:61]
	v_mfma_f32_16x16x32_bf16 v[54:57], v[106:109], v[192:195], v[54:57]
	v_mfma_f32_16x16x32_bf16 v[50:53], v[122:125], v[192:195], v[50:53]
	v_mfma_f32_16x16x32_bf16 v[154:157], v[122:125], v[162:165], v[90:93]
	s_setprio 0
	s_barrier
	s_nop 0
	ds_read_b128 v[90:93], v0 offset:16384
	ds_read_b128 v[162:165], v0 offset:17408
	ds_read_b128 v[166:169], v0 offset:18432
	ds_read_b128 v[170:173], v0 offset:19456
	ds_read_b128 v[174:177], v0 offset:20480
	ds_read_b128 v[184:187], v0 offset:21504
	ds_read_b128 v[188:191], v0 offset:22528
	ds_read_b128 v[192:195], v0 offset:23552
	s_waitcnt vmcnt(4)
	s_barrier
	s_waitcnt lgkmcnt(0)
	s_setprio 1
	s_waitcnt lgkmcnt(0)
	v_mfma_f32_16x16x32_bf16 v[46:49], v[134:137], v[90:93], v[46:49]
	v_mfma_f32_16x16x32_bf16 v[42:45], v[146:149], v[90:93], v[42:45]
	v_mfma_f32_16x16x32_bf16 v[38:41], v[134:137], v[166:169], v[38:41]
	v_mfma_f32_16x16x32_bf16 v[34:37], v[146:149], v[166:169], v[34:37]
	v_mfma_f32_16x16x32_bf16 v[30:33], v[134:137], v[174:177], v[30:33]
	v_mfma_f32_16x16x32_bf16 v[22:25], v[134:137], v[188:191], v[22:25]
	v_mfma_f32_16x16x32_bf16 v[46:49], v[138:141], v[162:165], v[46:49]
	v_mfma_f32_16x16x32_bf16 v[42:45], v[150:153], v[162:165], v[42:45]
	v_mfma_f32_16x16x32_bf16 v[38:41], v[138:141], v[170:173], v[38:41]
	v_mfma_f32_16x16x32_bf16 v[34:37], v[150:153], v[170:173], v[34:37]
	v_mfma_f32_16x16x32_bf16 v[30:33], v[138:141], v[184:187], v[30:33]
	v_mfma_f32_16x16x32_bf16 v[26:29], v[146:149], v[174:177], v[26:29]
	v_mfma_f32_16x16x32_bf16 v[22:25], v[138:141], v[192:195], v[22:25]
	v_mfma_f32_16x16x32_bf16 v[18:21], v[146:149], v[188:191], v[18:21]
	v_mfma_f32_16x16x32_bf16 v[218:221], v[150:153], v[184:187], v[26:29]
	v_mfma_f32_16x16x32_bf16 v[134:137], v[150:153], v[192:195], v[18:21]
	s_setprio 0
	s_setprio 1
	v_mfma_f32_16x16x32_bf16 v[2:5], v[114:117], v[166:169], v[2:5]
	v_mfma_f32_16x16x32_bf16 v[146:149], v[122:125], v[170:173], v[2:5]
	v_mfma_f32_16x16x32_bf16 v[2:5], v[98:101], v[174:177], v[66:69]
	v_mfma_f32_16x16x32_bf16 v[14:17], v[98:101], v[90:93], v[14:17]
	v_mfma_f32_16x16x32_bf16 v[10:13], v[114:117], v[90:93], v[10:13]
	v_mfma_f32_16x16x32_bf16 v[150:153], v[106:109], v[184:187], v[2:5]
	v_mfma_f32_16x16x32_bf16 v[2:5], v[114:117], v[174:177], v[74:77]
	v_mfma_f32_16x16x32_bf16 v[14:17], v[106:109], v[162:165], v[14:17]
	v_mfma_f32_16x16x32_bf16 v[138:141], v[122:125], v[162:165], v[10:13]
	v_mfma_f32_16x16x32_bf16 v[6:9], v[98:101], v[166:169], v[6:9]
	v_mfma_f32_16x16x32_bf16 v[162:165], v[122:125], v[184:187], v[2:5]
	v_mfma_f32_16x16x32_bf16 v[2:5], v[98:101], v[188:191], v[78:81]
	v_mfma_f32_16x16x32_bf16 v[6:9], v[106:109], v[170:173], v[6:9]
	v_mfma_f32_16x16x32_bf16 v[166:169], v[106:109], v[192:195], v[2:5]
	v_mfma_f32_16x16x32_bf16 v[2:5], v[114:117], v[188:191], v[82:85]
	v_mfma_f32_16x16x32_bf16 v[170:173], v[122:125], v[192:195], v[2:5]
	s_setprio 0
	s_barrier
	s_nop 4
	ds_read_b128 v[2:5], v145 offset:32768
	ds_read_b128 v[10:13], v145 offset:33792
	ds_read_b128 v[174:177], v145 offset:34816
	ds_read_b128 v[184:187], v145 offset:35840
	ds_read_b128 v[18:21], v0 offset:32768
	ds_read_b128 v[26:29], v0 offset:33792
	ds_read_b128 v[78:81], v0 offset:34816
	ds_read_b128 v[188:191], v0 offset:35840
	ds_read_b128 v[192:195], v0 offset:36864
	ds_read_b128 v[222:225], v0 offset:37888
	ds_read_b128 v[226:229], v0 offset:38912
	ds_read_b128 v[230:233], v0 offset:39936
	s_waitcnt vmcnt(2)
	s_barrier
; #define LDA(dst, b, h) _Pragma("unroll") for (int m = 0; m < 4; ++m) _Pragma("unroll") for (int k = 0; k < 2; ++k) \
;     dst[m][k] = *reinterpret_cast<const bf16x8*>(smem + (((b) * 2 + (h)) * 16384 + m * 2048 + k * 1024) + aoff)
; #define LDB(dst, b, h) _Pragma("unroll") for (int n = 0; n < 2; ++n) _Pragma("unroll") for (int k = 0; k < 2; ++k) \
;     dst[n][k] = *reinterpret_cast<const bf16x8*>(smem + (((b) * 2 + (h)) * 16384 + n * 2048 + k * 1024) + boff)
; #define MMA(ai, bj, At_, Bt_) do { __builtin_amdgcn_s_setprio(1); \
;     _Pragma("unroll") for (int m = 0; m < 4; ++m) _Pragma("unroll") for (int n = 0; n < 2; ++n) _Pragma("unroll") for (int k = 0; k < 2; ++k) \
;       acc[ai][bj][m][n] = __builtin_amdgcn_mfma_f32_16x16x32_bf16(Bt_[n][k], At_[m][k], acc[ai][bj][m][n], 0, 0, 0); \
;     __builtin_amdgcn_s_setprio(0); } while (0)
; #define WAIT_V(n) asm volatile("s_waitcnt vmcnt(" #n ")" ::: "memory")
; #define WAIT_L(n) asm volatile("s_waitcnt lgkmcnt(" #n ")" ::: "memory")
; #define BAR __builtin_amdgcn_s_barrier()
; template <class Epi, int NB>
; DEV void gemm_tile_nb(const bf16* __restrict__ A, int lda, long strideA, const bf16* __restrict__ Bt, int ldb, long strideB, int K, int brow, int bcol, Epi& epi) {
;     ...
;   { LDB(B0, 1, 0); LDA(At, 1, 0); WAIT_V(2); BAR; WAIT_L(0); MMA(0, 0, At, B0); BAR;
;     LDB(B1, 1, 1); WAIT_V(0); BAR; WAIT_L(0); MMA(0, 1, At, B1); BAR;
;     LDA(At, 1, 1); BAR; WAIT_L(0); MMA(1, 0, At, B0); MMA(1, 1, At, B1); BAR; }
;   if (wr == 0) BAR;
	s_waitcnt lgkmcnt(0)
	s_setprio 1
	s_waitcnt lgkmcnt(0)
	v_mfma_f32_16x16x32_bf16 v[66:69], v[2:5], v[18:21], v[126:129]
	v_mfma_f32_16x16x32_bf16 v[122:125], v[10:13], v[26:29], v[66:69]
	v_mfma_f32_16x16x32_bf16 v[66:69], v[174:177], v[18:21], v[130:133]
	v_mfma_f32_16x16x32_bf16 v[114:117], v[184:187], v[26:29], v[66:69]
	v_mfma_f32_16x16x32_bf16 v[66:69], v[2:5], v[78:81], v[118:121]
	v_mfma_f32_16x16x32_bf16 v[106:109], v[10:13], v[188:191], v[66:69]
	v_mfma_f32_16x16x32_bf16 v[66:69], v[174:177], v[78:81], v[158:161]
	v_mfma_f32_16x16x32_bf16 v[98:101], v[184:187], v[188:191], v[66:69]
	v_mfma_f32_16x16x32_bf16 v[66:69], v[2:5], v[192:195], v[110:113]
	v_mfma_f32_16x16x32_bf16 v[90:93], v[10:13], v[222:225], v[66:69]
	v_mfma_f32_16x16x32_bf16 v[66:69], v[174:177], v[192:195], v[196:199]
	v_mfma_f32_16x16x32_bf16 v[82:85], v[184:187], v[222:225], v[66:69]
	v_mfma_f32_16x16x32_bf16 v[66:69], v[2:5], v[226:229], v[102:105]
	v_mfma_f32_16x16x32_bf16 v[74:77], v[10:13], v[230:233], v[66:69]
	v_mfma_f32_16x16x32_bf16 v[66:69], v[174:177], v[226:229], v[200:203]
	v_mfma_f32_16x16x32_bf16 v[66:69], v[184:187], v[230:233], v[66:69]
	s_setprio 0
	s_barrier
	ds_read_b128 v[130:133], v145 offset:49152
	ds_read_b128 v[158:161], v145 offset:50176
	ds_read_b128 v[196:199], v145 offset:51200
	ds_read_b128 v[200:203], v145 offset:52224
	s_waitcnt vmcnt(0)
	s_barrier
	s_waitcnt lgkmcnt(0)
	s_setprio 1
	s_waitcnt lgkmcnt(0)
	v_mfma_f32_16x16x32_bf16 v[94:97], v[130:133], v[18:21], v[94:97]
	v_mfma_f32_16x16x32_bf16 v[18:21], v[196:199], v[18:21], v[154:157]
	v_mfma_f32_16x16x32_bf16 v[118:121], v[200:203], v[26:29], v[18:21]
	v_mfma_f32_16x16x32_bf16 v[18:21], v[130:133], v[78:81], v[86:89]
	v_mfma_f32_16x16x32_bf16 v[110:113], v[158:161], v[188:191], v[18:21]
	v_mfma_f32_16x16x32_bf16 v[18:21], v[196:199], v[78:81], v[70:73]
	v_mfma_f32_16x16x32_bf16 v[102:105], v[200:203], v[188:191], v[18:21]
	v_mfma_f32_16x16x32_bf16 v[18:21], v[130:133], v[192:195], v[62:65]
	v_mfma_f32_16x16x32_bf16 v[126:129], v[158:161], v[26:29], v[94:97]
	v_mfma_f32_16x16x32_bf16 v[94:97], v[158:161], v[222:225], v[18:21]
	v_mfma_f32_16x16x32_bf16 v[18:21], v[196:199], v[192:195], v[58:61]
	v_mfma_f32_16x16x32_bf16 v[86:89], v[200:203], v[222:225], v[18:21]
	v_mfma_f32_16x16x32_bf16 v[18:21], v[130:133], v[226:229], v[54:57]
	v_mfma_f32_16x16x32_bf16 v[78:81], v[158:161], v[230:233], v[18:21]
	v_mfma_f32_16x16x32_bf16 v[18:21], v[196:199], v[226:229], v[50:53]
	v_mfma_f32_16x16x32_bf16 v[70:73], v[200:203], v[230:233], v[18:21]
	s_setprio 0
	s_barrier
	ds_read_b128 v[54:57], v0 offset:49152
	ds_read_b128 v[154:157], v0 offset:50176
	ds_read_b128 v[188:191], v0 offset:51200
	ds_read_b128 v[192:195], v0 offset:52224
	ds_read_b128 v[222:225], v0 offset:53248
	ds_read_b128 v[226:229], v0 offset:54272
	ds_read_b128 v[230:233], v0 offset:55296
	ds_read_b128 v[234:237], v0 offset:56320
	s_barrier
	s_waitcnt lgkmcnt(0)
	s_setprio 1
	s_waitcnt lgkmcnt(0)
	v_mfma_f32_16x16x32_bf16 v[18:21], v[2:5], v[54:57], v[46:49]
	v_mfma_f32_16x16x32_bf16 v[58:61], v[10:13], v[154:157], v[18:21]
	v_mfma_f32_16x16x32_bf16 v[18:21], v[174:177], v[54:57], v[42:45]
	v_mfma_f32_16x16x32_bf16 v[50:53], v[184:187], v[154:157], v[18:21]
	v_mfma_f32_16x16x32_bf16 v[18:21], v[2:5], v[188:191], v[38:41]
	v_mfma_f32_16x16x32_bf16 v[42:45], v[10:13], v[192:195], v[18:21]
	v_mfma_f32_16x16x32_bf16 v[18:21], v[174:177], v[188:191], v[34:37]
	v_mfma_f32_16x16x32_bf16 v[34:37], v[184:187], v[192:195], v[18:21]
	v_mfma_f32_16x16x32_bf16 v[18:21], v[2:5], v[222:225], v[30:33]
	v_mfma_f32_16x16x32_bf16 v[2:5], v[2:5], v[230:233], v[22:25]
	v_mfma_f32_16x16x32_bf16 v[26:29], v[10:13], v[226:229], v[18:21]
	v_mfma_f32_16x16x32_bf16 v[18:21], v[174:177], v[222:225], v[218:221]
	v_mfma_f32_16x16x32_bf16 v[10:13], v[10:13], v[234:237], v[2:5]
	v_mfma_f32_16x16x32_bf16 v[2:5], v[174:177], v[230:233], v[134:137]
	v_mfma_f32_16x16x32_bf16 v[18:21], v[184:187], v[226:229], v[18:21]
	v_mfma_f32_16x16x32_bf16 v[2:5], v[184:187], v[234:237], v[2:5]
	s_setprio 0
	s_setprio 1
	v_mfma_f32_16x16x32_bf16 v[6:9], v[130:133], v[188:191], v[6:9]
	v_mfma_f32_16x16x32_bf16 v[46:49], v[158:161], v[192:195], v[6:9]
	v_mfma_f32_16x16x32_bf16 v[6:9], v[196:199], v[188:191], v[146:149]
	v_mfma_f32_16x16x32_bf16 v[38:41], v[200:203], v[192:195], v[6:9]
	v_mfma_f32_16x16x32_bf16 v[6:9], v[130:133], v[222:225], v[150:153]
	v_mfma_f32_16x16x32_bf16 v[14:17], v[130:133], v[54:57], v[14:17]
	v_mfma_f32_16x16x32_bf16 v[30:33], v[158:161], v[226:229], v[6:9]
	v_mfma_f32_16x16x32_bf16 v[6:9], v[196:199], v[222:225], v[162:165]
	v_mfma_f32_16x16x32_bf16 v[62:65], v[158:161], v[154:157], v[14:17]
	v_mfma_f32_16x16x32_bf16 v[14:17], v[196:199], v[54:57], v[138:141]
	v_mfma_f32_16x16x32_bf16 v[22:25], v[200:203], v[226:229], v[6:9]
	v_mfma_f32_16x16x32_bf16 v[6:9], v[130:133], v[230:233], v[166:169]
	v_mfma_f32_16x16x32_bf16 v[54:57], v[200:203], v[154:157], v[14:17]
	v_mfma_f32_16x16x32_bf16 v[14:17], v[158:161], v[234:237], v[6:9]
	v_mfma_f32_16x16x32_bf16 v[6:9], v[196:199], v[230:233], v[170:173]
	v_mfma_f32_16x16x32_bf16 v[6:9], v[200:203], v[234:237], v[6:9]
	s_setprio 0
	s_barrier
	s_cbranch_scc1 .LBB0_956
	s_barrier
	s_branch .LBB0_956
